# pool tasks: (sum*rc - u) as v_pk_fma_f32 with broadcast rc (half the ops of that step)
# speedup vs baseline: 1.0097x; 1.0083x over previous
.LBB0_332:
	s_or_b64 exec, exec, s[6:7]
	s_waitcnt lgkmcnt(0)
	global_load_dwordx4 v[82:85], v[144:145], off offset:512
	global_load_dwordx4 v[86:89], v[146:147], off offset:512
	global_load_dwordx4 v[90:93], v[148:149], off offset:512
	global_load_dwordx4 v[94:97], v[150:151], off offset:512
	global_load_dwordx4 v[112:115], v[144:145], off offset:1024
	global_load_dwordx4 v[116:119], v[146:147], off offset:1024
	global_load_dwordx4 v[122:125], v[148:149], off offset:1024
	global_load_dwordx4 v[126:129], v[150:151], off offset:1024
	v_lshl_add_u32 v246, v197, 1, v214
	ds_read_b128 v[222:225], v246 offset:4080
	ds_read_b128 v[226:229], v246 offset:3808
	ds_read_b128 v[230:233], v246 offset:3536
	ds_read_b128 v[234:237], v246 offset:3264
	ds_read_b128 v[238:241], v246 offset:2992
	ds_read_b128 v[242:245], v246 offset:2720
	ds_read_b128 v[248:251], v246 offset:2448
	ds_read_b128 v[252:255], v246 offset:2176
	v_or_b32_e32 v2, s28, v1
	v_min_u32_e32 v3, 15, v2
	v_add_u32_e32 v3, 1, v3
	v_cvt_f32_ubyte0_e32 v3, v3
	v_div_scale_f32 v4, s[6:7], v3, v3, 1.0
	v_rcp_f32_e32 v5, v4
	s_ashr_i32 s8, s30, 6
	s_mul_i32 s10, s8, 15
	v_cmp_lt_u32_e64 s[6:7], s41, v2
	v_fma_f32 v6, -v4, v5, 1.0
	v_fmac_f32_e32 v5, v6, v5
	v_div_scale_f32 v6, vcc, 1.0, v3, 1.0
	v_mul_f32_e32 v7, v6, v5
	v_fma_f32 v8, -v4, v7, v6
	v_fmac_f32_e32 v7, v8, v5
	v_fma_f32 v4, -v4, v7, v6
	v_div_fmas_f32 v4, v4, v5, v7
	v_div_fixup_f32 v159, v4, v3, 1.0
	s_ashr_i32 s11, s10, 31
	v_add_u32_e32 v2, 0xfffff80f, v2
	v_mov_b32_e32 v3, v155
	v_lshl_add_u64 v[2:3], v[2:3], 0, s[10:11]
	v_lshlrev_b64 v[2:3], 11, v[2:3]
	v_lshl_add_u64 v[2:3], s[70:71], 0, v[2:3]
	v_mov_b32_e32 v163, v155
	v_lshl_add_u64 v[2:3], v[2:3], 0, v[162:163]
	v_lshl_add_u64 v[192:193], v[2:3], 0, s[16:17]
	v_mov_b64_e32 v[2:3], 0
	v_mov_b64_e32 v[4:5], 0
	v_mov_b64_e32 v[6:7], 0
	v_mov_b64_e32 v[8:9], 0
	v_mov_b64_e32 v[10:11], 0
	v_mov_b64_e32 v[12:13], 0
	v_mov_b64_e32 v[14:15], 0
	v_mov_b64_e32 v[16:17], 0
	v_mov_b64_e32 v[18:19], 0
	v_mov_b64_e32 v[20:21], 0
	v_mov_b64_e32 v[22:23], 0
	v_mov_b64_e32 v[24:25], 0
	v_mov_b64_e32 v[26:27], 0
	v_mov_b64_e32 v[28:29], 0
	v_mov_b64_e32 v[30:31], 0
	v_mov_b64_e32 v[32:33], 0
	v_mov_b64_e32 v[34:35], 0
	v_mov_b64_e32 v[36:37], 0
	v_mov_b64_e32 v[38:39], 0
	v_mov_b64_e32 v[40:41], 0
	v_mov_b64_e32 v[42:43], 0
	v_mov_b64_e32 v[44:45], 0
	v_mov_b64_e32 v[46:47], 0
	v_mov_b64_e32 v[48:49], 0
	v_mov_b64_e32 v[50:51], 0
	v_mov_b64_e32 v[52:53], 0
	v_mov_b64_e32 v[54:55], 0
	v_mov_b64_e32 v[56:57], 0
	v_mov_b64_e32 v[58:59], 0
	v_mov_b64_e32 v[60:61], 0
	v_mov_b64_e32 v[62:63], 0
	v_mov_b64_e32 v[64:65], 0
	s_mov_b32 s49, 0
	s_mov_b64 s[10:11], 0
	s_waitcnt lgkmcnt(7)
	v_lshlrev_b32_e32 v98, 16, v222
	v_and_b32_e32 v99, 0xffff0000, v222
	v_lshlrev_b32_e32 v100, 16, v223
	v_and_b32_e32 v101, 0xffff0000, v223
	v_lshlrev_b32_e32 v102, 16, v224
	v_and_b32_e32 v103, 0xffff0000, v224
	v_lshlrev_b32_e32 v104, 16, v225
	v_and_b32_e32 v105, 0xffff0000, v225
	ds_read_b128 v[222:225], v246 offset:1904
	s_waitcnt lgkmcnt(7)
	v_lshlrev_b32_e32 v216, 16, v226
	v_and_b32_e32 v217, 0xffff0000, v226
	v_lshlrev_b32_e32 v226, 16, v227
	v_and_b32_e32 v227, 0xffff0000, v227
	v_pk_add_f32 v[106:107], v[98:99], v[216:217]
	v_pk_add_f32 v[108:109], v[100:101], v[226:227]
	v_lshlrev_b32_e32 v216, 16, v228
	v_and_b32_e32 v217, 0xffff0000, v228
	v_lshlrev_b32_e32 v228, 16, v229
	v_and_b32_e32 v229, 0xffff0000, v229
	v_pk_add_f32 v[218:219], v[102:103], v[216:217]
	v_pk_add_f32 v[220:221], v[104:105], v[228:229]
	ds_read_b128 v[226:229], v246 offset:1632
	s_waitcnt lgkmcnt(7)
	v_lshlrev_b32_e32 v216, 16, v230
	v_and_b32_e32 v217, 0xffff0000, v230
	v_lshlrev_b32_e32 v230, 16, v231
	v_and_b32_e32 v231, 0xffff0000, v231
	v_pk_add_f32 v[106:107], v[106:107], v[216:217]
	v_pk_add_f32 v[108:109], v[108:109], v[230:231]
	v_lshlrev_b32_e32 v216, 16, v232
	v_and_b32_e32 v217, 0xffff0000, v232
	v_lshlrev_b32_e32 v232, 16, v233
	v_and_b32_e32 v233, 0xffff0000, v233
	v_pk_add_f32 v[218:219], v[218:219], v[216:217]
	v_pk_add_f32 v[220:221], v[220:221], v[232:233]
	ds_read_b128 v[230:233], v246 offset:1360
	s_waitcnt lgkmcnt(7)
	v_lshlrev_b32_e32 v216, 16, v234
	v_and_b32_e32 v217, 0xffff0000, v234
	v_lshlrev_b32_e32 v234, 16, v235
	v_and_b32_e32 v235, 0xffff0000, v235
	v_pk_add_f32 v[106:107], v[106:107], v[216:217]
	v_pk_add_f32 v[108:109], v[108:109], v[234:235]
	v_lshlrev_b32_e32 v216, 16, v236
	v_and_b32_e32 v217, 0xffff0000, v236
	v_lshlrev_b32_e32 v236, 16, v237
	v_and_b32_e32 v237, 0xffff0000, v237
	v_pk_add_f32 v[218:219], v[218:219], v[216:217]
	v_pk_add_f32 v[220:221], v[220:221], v[236:237]
	ds_read_b128 v[234:237], v246 offset:1088
	s_waitcnt lgkmcnt(7)
	v_lshlrev_b32_e32 v216, 16, v238
	v_and_b32_e32 v217, 0xffff0000, v238
	v_lshlrev_b32_e32 v238, 16, v239
	v_and_b32_e32 v239, 0xffff0000, v239
	v_pk_add_f32 v[106:107], v[106:107], v[216:217]
	v_pk_add_f32 v[108:109], v[108:109], v[238:239]
	v_lshlrev_b32_e32 v216, 16, v240
	v_and_b32_e32 v217, 0xffff0000, v240
	v_lshlrev_b32_e32 v240, 16, v241
	v_and_b32_e32 v241, 0xffff0000, v241
	v_pk_add_f32 v[218:219], v[218:219], v[216:217]
	v_pk_add_f32 v[220:221], v[220:221], v[240:241]
	ds_read_b128 v[238:241], v246 offset:816
	s_waitcnt lgkmcnt(7)
	v_lshlrev_b32_e32 v216, 16, v242
	v_and_b32_e32 v217, 0xffff0000, v242
	v_lshlrev_b32_e32 v242, 16, v243
	v_and_b32_e32 v243, 0xffff0000, v243
	v_pk_add_f32 v[106:107], v[106:107], v[216:217]
	v_pk_add_f32 v[108:109], v[108:109], v[242:243]
	v_lshlrev_b32_e32 v216, 16, v244
	v_and_b32_e32 v217, 0xffff0000, v244
	v_lshlrev_b32_e32 v244, 16, v245
	v_and_b32_e32 v245, 0xffff0000, v245
	v_pk_add_f32 v[218:219], v[218:219], v[216:217]
	v_pk_add_f32 v[220:221], v[220:221], v[244:245]
	ds_read_b128 v[242:245], v246 offset:544
	s_waitcnt lgkmcnt(7)
	v_lshlrev_b32_e32 v216, 16, v248
	v_and_b32_e32 v217, 0xffff0000, v248
	v_lshlrev_b32_e32 v248, 16, v249
	v_and_b32_e32 v249, 0xffff0000, v249
	v_pk_add_f32 v[106:107], v[106:107], v[216:217]
	v_pk_add_f32 v[108:109], v[108:109], v[248:249]
	v_lshlrev_b32_e32 v216, 16, v250
	v_and_b32_e32 v217, 0xffff0000, v250
	v_lshlrev_b32_e32 v250, 16, v251
	v_and_b32_e32 v251, 0xffff0000, v251
	v_pk_add_f32 v[218:219], v[218:219], v[216:217]
	v_pk_add_f32 v[220:221], v[220:221], v[250:251]
	ds_read_b128 v[248:251], v246 offset:272
	s_waitcnt lgkmcnt(7)
	v_lshlrev_b32_e32 v216, 16, v252
	v_and_b32_e32 v217, 0xffff0000, v252
	v_lshlrev_b32_e32 v252, 16, v253
	v_and_b32_e32 v253, 0xffff0000, v253
	v_pk_add_f32 v[106:107], v[106:107], v[216:217]
	v_pk_add_f32 v[108:109], v[108:109], v[252:253]
	v_lshlrev_b32_e32 v216, 16, v254
	v_and_b32_e32 v217, 0xffff0000, v254
	v_lshlrev_b32_e32 v254, 16, v255
	v_and_b32_e32 v255, 0xffff0000, v255
	v_pk_add_f32 v[218:219], v[218:219], v[216:217]
	v_pk_add_f32 v[220:221], v[220:221], v[254:255]
	ds_read_b128 v[252:255], v246 offset:0
	s_waitcnt lgkmcnt(7)
	v_lshlrev_b32_e32 v216, 16, v222
	v_and_b32_e32 v217, 0xffff0000, v222
	v_lshlrev_b32_e32 v222, 16, v223
	v_and_b32_e32 v223, 0xffff0000, v223
	v_pk_add_f32 v[106:107], v[106:107], v[216:217]
	v_pk_add_f32 v[108:109], v[108:109], v[222:223]
	v_lshlrev_b32_e32 v216, 16, v224
	v_and_b32_e32 v217, 0xffff0000, v224
	v_lshlrev_b32_e32 v224, 16, v225
	v_and_b32_e32 v225, 0xffff0000, v225
	v_pk_add_f32 v[218:219], v[218:219], v[216:217]
	v_pk_add_f32 v[220:221], v[220:221], v[224:225]
	ds_read_b128 v[222:225], v246 offset:4112
	s_waitcnt lgkmcnt(7)
	v_lshlrev_b32_e32 v216, 16, v226
	v_and_b32_e32 v217, 0xffff0000, v226
	v_lshlrev_b32_e32 v226, 16, v227
	v_and_b32_e32 v227, 0xffff0000, v227
	v_pk_add_f32 v[106:107], v[106:107], v[216:217]
	v_pk_add_f32 v[108:109], v[108:109], v[226:227]
	v_lshlrev_b32_e32 v216, 16, v228
	v_and_b32_e32 v217, 0xffff0000, v228
	v_lshlrev_b32_e32 v228, 16, v229
	v_and_b32_e32 v229, 0xffff0000, v229
	v_pk_add_f32 v[218:219], v[218:219], v[216:217]
	v_pk_add_f32 v[220:221], v[220:221], v[228:229]
	ds_read_b128 v[226:229], v246 offset:3840
	s_waitcnt lgkmcnt(7)
	v_lshlrev_b32_e32 v216, 16, v230
	v_and_b32_e32 v217, 0xffff0000, v230
	v_lshlrev_b32_e32 v230, 16, v231
	v_and_b32_e32 v231, 0xffff0000, v231
	v_pk_add_f32 v[106:107], v[106:107], v[216:217]
	v_pk_add_f32 v[108:109], v[108:109], v[230:231]
	v_lshlrev_b32_e32 v216, 16, v232
	v_and_b32_e32 v217, 0xffff0000, v232
	v_lshlrev_b32_e32 v232, 16, v233
	v_and_b32_e32 v233, 0xffff0000, v233
	v_pk_add_f32 v[218:219], v[218:219], v[216:217]
	v_pk_add_f32 v[220:221], v[220:221], v[232:233]
	ds_read_b128 v[230:233], v246 offset:3568
	s_waitcnt lgkmcnt(7)
	v_lshlrev_b32_e32 v216, 16, v234
	v_and_b32_e32 v217, 0xffff0000, v234
	v_lshlrev_b32_e32 v234, 16, v235
	v_and_b32_e32 v235, 0xffff0000, v235
	v_pk_add_f32 v[106:107], v[106:107], v[216:217]
	v_pk_add_f32 v[108:109], v[108:109], v[234:235]
	v_lshlrev_b32_e32 v216, 16, v236
	v_and_b32_e32 v217, 0xffff0000, v236
	v_lshlrev_b32_e32 v236, 16, v237
	v_and_b32_e32 v237, 0xffff0000, v237
	v_pk_add_f32 v[218:219], v[218:219], v[216:217]
	v_pk_add_f32 v[220:221], v[220:221], v[236:237]
	ds_read_b128 v[234:237], v246 offset:3296
	s_waitcnt lgkmcnt(7)
	v_lshlrev_b32_e32 v216, 16, v238
	v_and_b32_e32 v217, 0xffff0000, v238
	v_lshlrev_b32_e32 v238, 16, v239
	v_and_b32_e32 v239, 0xffff0000, v239
	v_pk_add_f32 v[106:107], v[106:107], v[216:217]
	v_pk_add_f32 v[108:109], v[108:109], v[238:239]
	v_lshlrev_b32_e32 v216, 16, v240
	v_and_b32_e32 v217, 0xffff0000, v240
	v_lshlrev_b32_e32 v240, 16, v241
	v_and_b32_e32 v241, 0xffff0000, v241
	v_pk_add_f32 v[218:219], v[218:219], v[216:217]
	v_pk_add_f32 v[220:221], v[220:221], v[240:241]
	ds_read_b128 v[238:241], v246 offset:3024
	s_waitcnt lgkmcnt(7)
	v_lshlrev_b32_e32 v216, 16, v242
	v_and_b32_e32 v217, 0xffff0000, v242
	v_lshlrev_b32_e32 v242, 16, v243
	v_and_b32_e32 v243, 0xffff0000, v243
	v_pk_add_f32 v[106:107], v[106:107], v[216:217]
	v_pk_add_f32 v[108:109], v[108:109], v[242:243]
	v_lshlrev_b32_e32 v216, 16, v244
	v_and_b32_e32 v217, 0xffff0000, v244
	v_lshlrev_b32_e32 v244, 16, v245
	v_and_b32_e32 v245, 0xffff0000, v245
	v_pk_add_f32 v[218:219], v[218:219], v[216:217]
	v_pk_add_f32 v[220:221], v[220:221], v[244:245]
	ds_read_b128 v[242:245], v246 offset:2752
	s_waitcnt lgkmcnt(7)
	v_lshlrev_b32_e32 v216, 16, v248
	v_and_b32_e32 v217, 0xffff0000, v248
	v_lshlrev_b32_e32 v248, 16, v249
	v_and_b32_e32 v249, 0xffff0000, v249
	v_pk_add_f32 v[106:107], v[106:107], v[216:217]
	v_pk_add_f32 v[108:109], v[108:109], v[248:249]
	v_lshlrev_b32_e32 v216, 16, v250
	v_and_b32_e32 v217, 0xffff0000, v250
	v_lshlrev_b32_e32 v250, 16, v251
	v_and_b32_e32 v251, 0xffff0000, v251
	v_pk_add_f32 v[218:219], v[218:219], v[216:217]
	v_pk_add_f32 v[220:221], v[220:221], v[250:251]
	ds_read_b128 v[248:251], v246 offset:2480
	s_waitcnt lgkmcnt(7)
	v_lshlrev_b32_e32 v216, 16, v252
	v_and_b32_e32 v217, 0xffff0000, v252
	v_lshlrev_b32_e32 v252, 16, v253
	v_and_b32_e32 v253, 0xffff0000, v253
	v_pk_add_f32 v[106:107], v[106:107], v[216:217]
	v_pk_add_f32 v[108:109], v[108:109], v[252:253]
	v_lshlrev_b32_e32 v216, 16, v254
	v_and_b32_e32 v217, 0xffff0000, v254
	v_lshlrev_b32_e32 v254, 16, v255
	v_and_b32_e32 v255, 0xffff0000, v255
	v_pk_add_f32 v[218:219], v[218:219], v[216:217]
	v_pk_add_f32 v[220:221], v[220:221], v[254:255]
	ds_read_b128 v[252:255], v246 offset:2208
	v_pk_fma_f32 v[106:107], v[158:159], v[106:107], v[98:99] op_sel:[1,0,0] neg_lo:[0,0,1] neg_hi:[0,0,1]
	v_pk_fma_f32 v[108:109], v[158:159], v[108:109], v[100:101] op_sel:[1,0,0] neg_lo:[0,0,1] neg_hi:[0,0,1]
	v_pk_fma_f32 v[218:219], v[158:159], v[218:219], v[102:103] op_sel:[1,0,0] neg_lo:[0,0,1] neg_hi:[0,0,1]
	v_pk_fma_f32 v[220:221], v[158:159], v[220:221], v[104:105] op_sel:[1,0,0] neg_lo:[0,0,1] neg_hi:[0,0,1]
	v_cvt_pk_bf16_f32 v106, v106, v107
	v_cvt_pk_bf16_f32 v107, v108, v109
	v_cvt_pk_bf16_f32 v108, v218, v219
	v_cvt_pk_bf16_f32 v109, v220, v221
	s_and_saveexec_b64 s[28:29], s[6:7]
	s_cbranch_execz .Lpu0_0
	global_store_dwordx4 v[192:193], v[98:101], off offset:0
	global_store_dwordx4 v[192:193], v[102:105], off offset:16
.Lpu0_0:
	s_or_b64 exec, exec, s[28:29]
	s_waitcnt vmcnt(8)
	v_mfma_f32_32x32x16_bf16 v[2:17], v[106:109], v[70:73], v[2:17]
	v_mfma_f32_32x32x16_bf16 v[18:33], v[106:109], v[74:77], v[18:33]
	v_mfma_f32_32x32x16_bf16 v[34:49], v[106:109], v[78:81], v[34:49]
	v_mfma_f32_32x32x16_bf16 v[50:65], v[106:109], v[66:69], v[50:65]
	global_load_dwordx4 v[70:73], v[144:145], off offset:1536
	global_load_dwordx4 v[74:77], v[146:147], off offset:1536
	global_load_dwordx4 v[78:81], v[148:149], off offset:1536
	global_load_dwordx4 v[66:69], v[150:151], off offset:1536
	s_waitcnt lgkmcnt(7)
	v_lshlrev_b32_e32 v98, 16, v222
	v_and_b32_e32 v99, 0xffff0000, v222
	v_lshlrev_b32_e32 v100, 16, v223
	v_and_b32_e32 v101, 0xffff0000, v223
	v_lshlrev_b32_e32 v102, 16, v224
	v_and_b32_e32 v103, 0xffff0000, v224
	v_lshlrev_b32_e32 v104, 16, v225
	v_and_b32_e32 v105, 0xffff0000, v225
	ds_read_b128 v[222:225], v246 offset:1936
	s_waitcnt lgkmcnt(7)
	v_lshlrev_b32_e32 v216, 16, v226
	v_and_b32_e32 v217, 0xffff0000, v226
	v_lshlrev_b32_e32 v226, 16, v227
	v_and_b32_e32 v227, 0xffff0000, v227
	v_pk_add_f32 v[106:107], v[98:99], v[216:217]
	v_pk_add_f32 v[108:109], v[100:101], v[226:227]
	v_lshlrev_b32_e32 v216, 16, v228
	v_and_b32_e32 v217, 0xffff0000, v228
	v_lshlrev_b32_e32 v228, 16, v229
	v_and_b32_e32 v229, 0xffff0000, v229
	v_pk_add_f32 v[218:219], v[102:103], v[216:217]
	v_pk_add_f32 v[220:221], v[104:105], v[228:229]
	ds_read_b128 v[226:229], v246 offset:1664
	s_waitcnt lgkmcnt(7)
	v_lshlrev_b32_e32 v216, 16, v230
	v_and_b32_e32 v217, 0xffff0000, v230
	v_lshlrev_b32_e32 v230, 16, v231
	v_and_b32_e32 v231, 0xffff0000, v231
	v_pk_add_f32 v[106:107], v[106:107], v[216:217]
	v_pk_add_f32 v[108:109], v[108:109], v[230:231]
	v_lshlrev_b32_e32 v216, 16, v232
	v_and_b32_e32 v217, 0xffff0000, v232
	v_lshlrev_b32_e32 v232, 16, v233
	v_and_b32_e32 v233, 0xffff0000, v233
	v_pk_add_f32 v[218:219], v[218:219], v[216:217]
	v_pk_add_f32 v[220:221], v[220:221], v[232:233]
	ds_read_b128 v[230:233], v246 offset:1392
	s_waitcnt lgkmcnt(7)
	v_lshlrev_b32_e32 v216, 16, v234
	v_and_b32_e32 v217, 0xffff0000, v234
	v_lshlrev_b32_e32 v234, 16, v235
	v_and_b32_e32 v235, 0xffff0000, v235
	v_pk_add_f32 v[106:107], v[106:107], v[216:217]
	v_pk_add_f32 v[108:109], v[108:109], v[234:235]
	v_lshlrev_b32_e32 v216, 16, v236
	v_and_b32_e32 v217, 0xffff0000, v236
	v_lshlrev_b32_e32 v236, 16, v237
	v_and_b32_e32 v237, 0xffff0000, v237
	v_pk_add_f32 v[218:219], v[218:219], v[216:217]
	v_pk_add_f32 v[220:221], v[220:221], v[236:237]
	ds_read_b128 v[234:237], v246 offset:1120
	s_waitcnt lgkmcnt(7)
	v_lshlrev_b32_e32 v216, 16, v238
	v_and_b32_e32 v217, 0xffff0000, v238
	v_lshlrev_b32_e32 v238, 16, v239
	v_and_b32_e32 v239, 0xffff0000, v239
	v_pk_add_f32 v[106:107], v[106:107], v[216:217]
	v_pk_add_f32 v[108:109], v[108:109], v[238:239]
	v_lshlrev_b32_e32 v216, 16, v240
	v_and_b32_e32 v217, 0xffff0000, v240
	v_lshlrev_b32_e32 v240, 16, v241
	v_and_b32_e32 v241, 0xffff0000, v241
	v_pk_add_f32 v[218:219], v[218:219], v[216:217]
	v_pk_add_f32 v[220:221], v[220:221], v[240:241]
	ds_read_b128 v[238:241], v246 offset:848
	s_waitcnt lgkmcnt(7)
	v_lshlrev_b32_e32 v216, 16, v242
	v_and_b32_e32 v217, 0xffff0000, v242
	v_lshlrev_b32_e32 v242, 16, v243
	v_and_b32_e32 v243, 0xffff0000, v243
	v_pk_add_f32 v[106:107], v[106:107], v[216:217]
	v_pk_add_f32 v[108:109], v[108:109], v[242:243]
	v_lshlrev_b32_e32 v216, 16, v244
	v_and_b32_e32 v217, 0xffff0000, v244
	v_lshlrev_b32_e32 v244, 16, v245
	v_and_b32_e32 v245, 0xffff0000, v245
	v_pk_add_f32 v[218:219], v[218:219], v[216:217]
	v_pk_add_f32 v[220:221], v[220:221], v[244:245]
	ds_read_b128 v[242:245], v246 offset:576
	s_waitcnt lgkmcnt(7)
	v_lshlrev_b32_e32 v216, 16, v248
	v_and_b32_e32 v217, 0xffff0000, v248
	v_lshlrev_b32_e32 v248, 16, v249
	v_and_b32_e32 v249, 0xffff0000, v249
	v_pk_add_f32 v[106:107], v[106:107], v[216:217]
	v_pk_add_f32 v[108:109], v[108:109], v[248:249]
	v_lshlrev_b32_e32 v216, 16, v250
	v_and_b32_e32 v217, 0xffff0000, v250
	v_lshlrev_b32_e32 v250, 16, v251
	v_and_b32_e32 v251, 0xffff0000, v251
	v_pk_add_f32 v[218:219], v[218:219], v[216:217]
	v_pk_add_f32 v[220:221], v[220:221], v[250:251]
	ds_read_b128 v[248:251], v246 offset:304
	s_waitcnt lgkmcnt(7)
	v_lshlrev_b32_e32 v216, 16, v252
	v_and_b32_e32 v217, 0xffff0000, v252
	v_lshlrev_b32_e32 v252, 16, v253
	v_and_b32_e32 v253, 0xffff0000, v253
	v_pk_add_f32 v[106:107], v[106:107], v[216:217]
	v_pk_add_f32 v[108:109], v[108:109], v[252:253]
	v_lshlrev_b32_e32 v216, 16, v254
	v_and_b32_e32 v217, 0xffff0000, v254
	v_lshlrev_b32_e32 v254, 16, v255
	v_and_b32_e32 v255, 0xffff0000, v255
	v_pk_add_f32 v[218:219], v[218:219], v[216:217]
	v_pk_add_f32 v[220:221], v[220:221], v[254:255]
	ds_read_b128 v[252:255], v246 offset:32
	s_waitcnt lgkmcnt(7)
	v_lshlrev_b32_e32 v216, 16, v222
	v_and_b32_e32 v217, 0xffff0000, v222
	v_lshlrev_b32_e32 v222, 16, v223
	v_and_b32_e32 v223, 0xffff0000, v223
	v_pk_add_f32 v[106:107], v[106:107], v[216:217]
	v_pk_add_f32 v[108:109], v[108:109], v[222:223]
	v_lshlrev_b32_e32 v216, 16, v224
	v_and_b32_e32 v217, 0xffff0000, v224
	v_lshlrev_b32_e32 v224, 16, v225
	v_and_b32_e32 v225, 0xffff0000, v225
	v_pk_add_f32 v[218:219], v[218:219], v[216:217]
	v_pk_add_f32 v[220:221], v[220:221], v[224:225]
	ds_read_b128 v[222:225], v246 offset:4144
	s_waitcnt lgkmcnt(7)
	v_lshlrev_b32_e32 v216, 16, v226
	v_and_b32_e32 v217, 0xffff0000, v226
	v_lshlrev_b32_e32 v226, 16, v227
	v_and_b32_e32 v227, 0xffff0000, v227
	v_pk_add_f32 v[106:107], v[106:107], v[216:217]
	v_pk_add_f32 v[108:109], v[108:109], v[226:227]
	v_lshlrev_b32_e32 v216, 16, v228
	v_and_b32_e32 v217, 0xffff0000, v228
	v_lshlrev_b32_e32 v228, 16, v229
	v_and_b32_e32 v229, 0xffff0000, v229
	v_pk_add_f32 v[218:219], v[218:219], v[216:217]
	v_pk_add_f32 v[220:221], v[220:221], v[228:229]
	ds_read_b128 v[226:229], v246 offset:3872
	s_waitcnt lgkmcnt(7)
	v_lshlrev_b32_e32 v216, 16, v230
	v_and_b32_e32 v217, 0xffff0000, v230
	v_lshlrev_b32_e32 v230, 16, v231
	v_and_b32_e32 v231, 0xffff0000, v231
	v_pk_add_f32 v[106:107], v[106:107], v[216:217]
	v_pk_add_f32 v[108:109], v[108:109], v[230:231]
	v_lshlrev_b32_e32 v216, 16, v232
	v_and_b32_e32 v217, 0xffff0000, v232
	v_lshlrev_b32_e32 v232, 16, v233
	v_and_b32_e32 v233, 0xffff0000, v233
	v_pk_add_f32 v[218:219], v[218:219], v[216:217]
	v_pk_add_f32 v[220:221], v[220:221], v[232:233]
	ds_read_b128 v[230:233], v246 offset:3600
	s_waitcnt lgkmcnt(7)
	v_lshlrev_b32_e32 v216, 16, v234
	v_and_b32_e32 v217, 0xffff0000, v234
	v_lshlrev_b32_e32 v234, 16, v235
	v_and_b32_e32 v235, 0xffff0000, v235
	v_pk_add_f32 v[106:107], v[106:107], v[216:217]
	v_pk_add_f32 v[108:109], v[108:109], v[234:235]
	v_lshlrev_b32_e32 v216, 16, v236
	v_and_b32_e32 v217, 0xffff0000, v236
	v_lshlrev_b32_e32 v236, 16, v237
	v_and_b32_e32 v237, 0xffff0000, v237
	v_pk_add_f32 v[218:219], v[218:219], v[216:217]
	v_pk_add_f32 v[220:221], v[220:221], v[236:237]
	ds_read_b128 v[234:237], v246 offset:3328
	s_waitcnt lgkmcnt(7)
	v_lshlrev_b32_e32 v216, 16, v238
	v_and_b32_e32 v217, 0xffff0000, v238
	v_lshlrev_b32_e32 v238, 16, v239
	v_and_b32_e32 v239, 0xffff0000, v239
	v_pk_add_f32 v[106:107], v[106:107], v[216:217]
	v_pk_add_f32 v[108:109], v[108:109], v[238:239]
	v_lshlrev_b32_e32 v216, 16, v240
	v_and_b32_e32 v217, 0xffff0000, v240
	v_lshlrev_b32_e32 v240, 16, v241
	v_and_b32_e32 v241, 0xffff0000, v241
	v_pk_add_f32 v[218:219], v[218:219], v[216:217]
	v_pk_add_f32 v[220:221], v[220:221], v[240:241]
	ds_read_b128 v[238:241], v246 offset:3056
	s_waitcnt lgkmcnt(7)
	v_lshlrev_b32_e32 v216, 16, v242
	v_and_b32_e32 v217, 0xffff0000, v242
	v_lshlrev_b32_e32 v242, 16, v243
	v_and_b32_e32 v243, 0xffff0000, v243
	v_pk_add_f32 v[106:107], v[106:107], v[216:217]
	v_pk_add_f32 v[108:109], v[108:109], v[242:243]
	v_lshlrev_b32_e32 v216, 16, v244
	v_and_b32_e32 v217, 0xffff0000, v244
	v_lshlrev_b32_e32 v244, 16, v245
	v_and_b32_e32 v245, 0xffff0000, v245
	v_pk_add_f32 v[218:219], v[218:219], v[216:217]
	v_pk_add_f32 v[220:221], v[220:221], v[244:245]
	ds_read_b128 v[242:245], v246 offset:2784
	s_waitcnt lgkmcnt(7)
	v_lshlrev_b32_e32 v216, 16, v248
	v_and_b32_e32 v217, 0xffff0000, v248
	v_lshlrev_b32_e32 v248, 16, v249
	v_and_b32_e32 v249, 0xffff0000, v249
	v_pk_add_f32 v[106:107], v[106:107], v[216:217]
	v_pk_add_f32 v[108:109], v[108:109], v[248:249]
	v_lshlrev_b32_e32 v216, 16, v250
	v_and_b32_e32 v217, 0xffff0000, v250
	v_lshlrev_b32_e32 v250, 16, v251
	v_and_b32_e32 v251, 0xffff0000, v251
	v_pk_add_f32 v[218:219], v[218:219], v[216:217]
	v_pk_add_f32 v[220:221], v[220:221], v[250:251]
	ds_read_b128 v[248:251], v246 offset:2512
	s_waitcnt lgkmcnt(7)
	v_lshlrev_b32_e32 v216, 16, v252
	v_and_b32_e32 v217, 0xffff0000, v252
	v_lshlrev_b32_e32 v252, 16, v253
	v_and_b32_e32 v253, 0xffff0000, v253
	v_pk_add_f32 v[106:107], v[106:107], v[216:217]
	v_pk_add_f32 v[108:109], v[108:109], v[252:253]
	v_lshlrev_b32_e32 v216, 16, v254
	v_and_b32_e32 v217, 0xffff0000, v254
	v_lshlrev_b32_e32 v254, 16, v255
	v_and_b32_e32 v255, 0xffff0000, v255
	v_pk_add_f32 v[218:219], v[218:219], v[216:217]
	v_pk_add_f32 v[220:221], v[220:221], v[254:255]
	ds_read_b128 v[252:255], v246 offset:2240
	v_pk_fma_f32 v[106:107], v[158:159], v[106:107], v[98:99] op_sel:[1,0,0] neg_lo:[0,0,1] neg_hi:[0,0,1]
	v_pk_fma_f32 v[108:109], v[158:159], v[108:109], v[100:101] op_sel:[1,0,0] neg_lo:[0,0,1] neg_hi:[0,0,1]
	v_pk_fma_f32 v[218:219], v[158:159], v[218:219], v[102:103] op_sel:[1,0,0] neg_lo:[0,0,1] neg_hi:[0,0,1]
	v_pk_fma_f32 v[220:221], v[158:159], v[220:221], v[104:105] op_sel:[1,0,0] neg_lo:[0,0,1] neg_hi:[0,0,1]
	v_cvt_pk_bf16_f32 v106, v106, v107
	v_cvt_pk_bf16_f32 v107, v108, v109
	v_cvt_pk_bf16_f32 v108, v218, v219
	v_cvt_pk_bf16_f32 v109, v220, v221
	s_and_saveexec_b64 s[28:29], s[6:7]
	s_cbranch_execz .Lpu0_1
	global_store_dwordx4 v[192:193], v[98:101], off offset:64
	global_store_dwordx4 v[192:193], v[102:105], off offset:80
.Lpu0_1:
	s_or_b64 exec, exec, s[28:29]
	s_waitcnt vmcnt(8)
	v_mfma_f32_32x32x16_bf16 v[2:17], v[106:109], v[82:85], v[2:17]
	v_mfma_f32_32x32x16_bf16 v[18:33], v[106:109], v[86:89], v[18:33]
	v_mfma_f32_32x32x16_bf16 v[34:49], v[106:109], v[90:93], v[34:49]
	v_mfma_f32_32x32x16_bf16 v[50:65], v[106:109], v[94:97], v[50:65]
	global_load_dwordx4 v[82:85], v[144:145], off offset:2048
	global_load_dwordx4 v[86:89], v[146:147], off offset:2048
	global_load_dwordx4 v[90:93], v[148:149], off offset:2048
	global_load_dwordx4 v[94:97], v[150:151], off offset:2048
	s_waitcnt lgkmcnt(7)
	v_lshlrev_b32_e32 v98, 16, v222
	v_and_b32_e32 v99, 0xffff0000, v222
	v_lshlrev_b32_e32 v100, 16, v223
	v_and_b32_e32 v101, 0xffff0000, v223
	v_lshlrev_b32_e32 v102, 16, v224
	v_and_b32_e32 v103, 0xffff0000, v224
	v_lshlrev_b32_e32 v104, 16, v225
	v_and_b32_e32 v105, 0xffff0000, v225
	ds_read_b128 v[222:225], v246 offset:1968
	s_waitcnt lgkmcnt(7)
	v_lshlrev_b32_e32 v216, 16, v226
	v_and_b32_e32 v217, 0xffff0000, v226
	v_lshlrev_b32_e32 v226, 16, v227
	v_and_b32_e32 v227, 0xffff0000, v227
	v_pk_add_f32 v[106:107], v[98:99], v[216:217]
	v_pk_add_f32 v[108:109], v[100:101], v[226:227]
	v_lshlrev_b32_e32 v216, 16, v228
	v_and_b32_e32 v217, 0xffff0000, v228
	v_lshlrev_b32_e32 v228, 16, v229
	v_and_b32_e32 v229, 0xffff0000, v229
	v_pk_add_f32 v[218:219], v[102:103], v[216:217]
	v_pk_add_f32 v[220:221], v[104:105], v[228:229]
	ds_read_b128 v[226:229], v246 offset:1696
	s_waitcnt lgkmcnt(7)
	v_lshlrev_b32_e32 v216, 16, v230
	v_and_b32_e32 v217, 0xffff0000, v230
	v_lshlrev_b32_e32 v230, 16, v231
	v_and_b32_e32 v231, 0xffff0000, v231
	v_pk_add_f32 v[106:107], v[106:107], v[216:217]
	v_pk_add_f32 v[108:109], v[108:109], v[230:231]
	v_lshlrev_b32_e32 v216, 16, v232
	v_and_b32_e32 v217, 0xffff0000, v232
	v_lshlrev_b32_e32 v232, 16, v233
	v_and_b32_e32 v233, 0xffff0000, v233
	v_pk_add_f32 v[218:219], v[218:219], v[216:217]
	v_pk_add_f32 v[220:221], v[220:221], v[232:233]
	ds_read_b128 v[230:233], v246 offset:1424
	s_waitcnt lgkmcnt(7)
	v_lshlrev_b32_e32 v216, 16, v234
	v_and_b32_e32 v217, 0xffff0000, v234
	v_lshlrev_b32_e32 v234, 16, v235
	v_and_b32_e32 v235, 0xffff0000, v235
	v_pk_add_f32 v[106:107], v[106:107], v[216:217]
	v_pk_add_f32 v[108:109], v[108:109], v[234:235]
	v_lshlrev_b32_e32 v216, 16, v236
	v_and_b32_e32 v217, 0xffff0000, v236
	v_lshlrev_b32_e32 v236, 16, v237
	v_and_b32_e32 v237, 0xffff0000, v237
	v_pk_add_f32 v[218:219], v[218:219], v[216:217]
	v_pk_add_f32 v[220:221], v[220:221], v[236:237]
	ds_read_b128 v[234:237], v246 offset:1152
	s_waitcnt lgkmcnt(7)
	v_lshlrev_b32_e32 v216, 16, v238
	v_and_b32_e32 v217, 0xffff0000, v238
	v_lshlrev_b32_e32 v238, 16, v239
	v_and_b32_e32 v239, 0xffff0000, v239
	v_pk_add_f32 v[106:107], v[106:107], v[216:217]
	v_pk_add_f32 v[108:109], v[108:109], v[238:239]
	v_lshlrev_b32_e32 v216, 16, v240
	v_and_b32_e32 v217, 0xffff0000, v240
	v_lshlrev_b32_e32 v240, 16, v241
	v_and_b32_e32 v241, 0xffff0000, v241
	v_pk_add_f32 v[218:219], v[218:219], v[216:217]
	v_pk_add_f32 v[220:221], v[220:221], v[240:241]
	ds_read_b128 v[238:241], v246 offset:880
	s_waitcnt lgkmcnt(7)
	v_lshlrev_b32_e32 v216, 16, v242
	v_and_b32_e32 v217, 0xffff0000, v242
	v_lshlrev_b32_e32 v242, 16, v243
	v_and_b32_e32 v243, 0xffff0000, v243
	v_pk_add_f32 v[106:107], v[106:107], v[216:217]
	v_pk_add_f32 v[108:109], v[108:109], v[242:243]
	v_lshlrev_b32_e32 v216, 16, v244
	v_and_b32_e32 v217, 0xffff0000, v244
	v_lshlrev_b32_e32 v244, 16, v245
	v_and_b32_e32 v245, 0xffff0000, v245
	v_pk_add_f32 v[218:219], v[218:219], v[216:217]
	v_pk_add_f32 v[220:221], v[220:221], v[244:245]
	ds_read_b128 v[242:245], v246 offset:608
	s_waitcnt lgkmcnt(7)
	v_lshlrev_b32_e32 v216, 16, v248
	v_and_b32_e32 v217, 0xffff0000, v248
	v_lshlrev_b32_e32 v248, 16, v249
	v_and_b32_e32 v249, 0xffff0000, v249
	v_pk_add_f32 v[106:107], v[106:107], v[216:217]
	v_pk_add_f32 v[108:109], v[108:109], v[248:249]
	v_lshlrev_b32_e32 v216, 16, v250
	v_and_b32_e32 v217, 0xffff0000, v250
	v_lshlrev_b32_e32 v250, 16, v251
	v_and_b32_e32 v251, 0xffff0000, v251
	v_pk_add_f32 v[218:219], v[218:219], v[216:217]
	v_pk_add_f32 v[220:221], v[220:221], v[250:251]
	ds_read_b128 v[248:251], v246 offset:336
	s_waitcnt lgkmcnt(7)
	v_lshlrev_b32_e32 v216, 16, v252
	v_and_b32_e32 v217, 0xffff0000, v252
	v_lshlrev_b32_e32 v252, 16, v253
	v_and_b32_e32 v253, 0xffff0000, v253
	v_pk_add_f32 v[106:107], v[106:107], v[216:217]
	v_pk_add_f32 v[108:109], v[108:109], v[252:253]
	v_lshlrev_b32_e32 v216, 16, v254
	v_and_b32_e32 v217, 0xffff0000, v254
	v_lshlrev_b32_e32 v254, 16, v255
	v_and_b32_e32 v255, 0xffff0000, v255
	v_pk_add_f32 v[218:219], v[218:219], v[216:217]
	v_pk_add_f32 v[220:221], v[220:221], v[254:255]
	ds_read_b128 v[252:255], v246 offset:64
	s_waitcnt lgkmcnt(7)
	v_lshlrev_b32_e32 v216, 16, v222
	v_and_b32_e32 v217, 0xffff0000, v222
	v_lshlrev_b32_e32 v222, 16, v223
	v_and_b32_e32 v223, 0xffff0000, v223
	v_pk_add_f32 v[106:107], v[106:107], v[216:217]
	v_pk_add_f32 v[108:109], v[108:109], v[222:223]
	v_lshlrev_b32_e32 v216, 16, v224
	v_and_b32_e32 v217, 0xffff0000, v224
	v_lshlrev_b32_e32 v224, 16, v225
	v_and_b32_e32 v225, 0xffff0000, v225
	v_pk_add_f32 v[218:219], v[218:219], v[216:217]
	v_pk_add_f32 v[220:221], v[220:221], v[224:225]
	ds_read_b128 v[222:225], v246 offset:4176
	s_waitcnt lgkmcnt(7)
	v_lshlrev_b32_e32 v216, 16, v226
	v_and_b32_e32 v217, 0xffff0000, v226
	v_lshlrev_b32_e32 v226, 16, v227
	v_and_b32_e32 v227, 0xffff0000, v227
	v_pk_add_f32 v[106:107], v[106:107], v[216:217]
	v_pk_add_f32 v[108:109], v[108:109], v[226:227]
	v_lshlrev_b32_e32 v216, 16, v228
	v_and_b32_e32 v217, 0xffff0000, v228
	v_lshlrev_b32_e32 v228, 16, v229
	v_and_b32_e32 v229, 0xffff0000, v229
	v_pk_add_f32 v[218:219], v[218:219], v[216:217]
	v_pk_add_f32 v[220:221], v[220:221], v[228:229]
	ds_read_b128 v[226:229], v246 offset:3904
	s_waitcnt lgkmcnt(7)
	v_lshlrev_b32_e32 v216, 16, v230
	v_and_b32_e32 v217, 0xffff0000, v230
	v_lshlrev_b32_e32 v230, 16, v231
	v_and_b32_e32 v231, 0xffff0000, v231
	v_pk_add_f32 v[106:107], v[106:107], v[216:217]
	v_pk_add_f32 v[108:109], v[108:109], v[230:231]
	v_lshlrev_b32_e32 v216, 16, v232
	v_and_b32_e32 v217, 0xffff0000, v232
	v_lshlrev_b32_e32 v232, 16, v233
	v_and_b32_e32 v233, 0xffff0000, v233
	v_pk_add_f32 v[218:219], v[218:219], v[216:217]
	v_pk_add_f32 v[220:221], v[220:221], v[232:233]
	ds_read_b128 v[230:233], v246 offset:3632
	s_waitcnt lgkmcnt(7)
	v_lshlrev_b32_e32 v216, 16, v234
	v_and_b32_e32 v217, 0xffff0000, v234
	v_lshlrev_b32_e32 v234, 16, v235
	v_and_b32_e32 v235, 0xffff0000, v235
	v_pk_add_f32 v[106:107], v[106:107], v[216:217]
	v_pk_add_f32 v[108:109], v[108:109], v[234:235]
	v_lshlrev_b32_e32 v216, 16, v236
	v_and_b32_e32 v217, 0xffff0000, v236
	v_lshlrev_b32_e32 v236, 16, v237
	v_and_b32_e32 v237, 0xffff0000, v237
	v_pk_add_f32 v[218:219], v[218:219], v[216:217]
	v_pk_add_f32 v[220:221], v[220:221], v[236:237]
	ds_read_b128 v[234:237], v246 offset:3360
	s_waitcnt lgkmcnt(7)
	v_lshlrev_b32_e32 v216, 16, v238
	v_and_b32_e32 v217, 0xffff0000, v238
	v_lshlrev_b32_e32 v238, 16, v239
	v_and_b32_e32 v239, 0xffff0000, v239
	v_pk_add_f32 v[106:107], v[106:107], v[216:217]
	v_pk_add_f32 v[108:109], v[108:109], v[238:239]
	v_lshlrev_b32_e32 v216, 16, v240
	v_and_b32_e32 v217, 0xffff0000, v240
	v_lshlrev_b32_e32 v240, 16, v241
	v_and_b32_e32 v241, 0xffff0000, v241
	v_pk_add_f32 v[218:219], v[218:219], v[216:217]
	v_pk_add_f32 v[220:221], v[220:221], v[240:241]
	ds_read_b128 v[238:241], v246 offset:3088
	s_waitcnt lgkmcnt(7)
	v_lshlrev_b32_e32 v216, 16, v242
	v_and_b32_e32 v217, 0xffff0000, v242
	v_lshlrev_b32_e32 v242, 16, v243
	v_and_b32_e32 v243, 0xffff0000, v243
	v_pk_add_f32 v[106:107], v[106:107], v[216:217]
	v_pk_add_f32 v[108:109], v[108:109], v[242:243]
	v_lshlrev_b32_e32 v216, 16, v244
	v_and_b32_e32 v217, 0xffff0000, v244
	v_lshlrev_b32_e32 v244, 16, v245
	v_and_b32_e32 v245, 0xffff0000, v245
	v_pk_add_f32 v[218:219], v[218:219], v[216:217]
	v_pk_add_f32 v[220:221], v[220:221], v[244:245]
	ds_read_b128 v[242:245], v246 offset:2816
	s_waitcnt lgkmcnt(7)
	v_lshlrev_b32_e32 v216, 16, v248
	v_and_b32_e32 v217, 0xffff0000, v248
	v_lshlrev_b32_e32 v248, 16, v249
	v_and_b32_e32 v249, 0xffff0000, v249
	v_pk_add_f32 v[106:107], v[106:107], v[216:217]
	v_pk_add_f32 v[108:109], v[108:109], v[248:249]
	v_lshlrev_b32_e32 v216, 16, v250
	v_and_b32_e32 v217, 0xffff0000, v250
	v_lshlrev_b32_e32 v250, 16, v251
	v_and_b32_e32 v251, 0xffff0000, v251
	v_pk_add_f32 v[218:219], v[218:219], v[216:217]
	v_pk_add_f32 v[220:221], v[220:221], v[250:251]
	ds_read_b128 v[248:251], v246 offset:2544
	s_waitcnt lgkmcnt(7)
	v_lshlrev_b32_e32 v216, 16, v252
	v_and_b32_e32 v217, 0xffff0000, v252
	v_lshlrev_b32_e32 v252, 16, v253
	v_and_b32_e32 v253, 0xffff0000, v253
	v_pk_add_f32 v[106:107], v[106:107], v[216:217]
	v_pk_add_f32 v[108:109], v[108:109], v[252:253]
	v_lshlrev_b32_e32 v216, 16, v254
	v_and_b32_e32 v217, 0xffff0000, v254
	v_lshlrev_b32_e32 v254, 16, v255
	v_and_b32_e32 v255, 0xffff0000, v255
	v_pk_add_f32 v[218:219], v[218:219], v[216:217]
	v_pk_add_f32 v[220:221], v[220:221], v[254:255]
	ds_read_b128 v[252:255], v246 offset:2272
	v_pk_fma_f32 v[106:107], v[158:159], v[106:107], v[98:99] op_sel:[1,0,0] neg_lo:[0,0,1] neg_hi:[0,0,1]
	v_pk_fma_f32 v[108:109], v[158:159], v[108:109], v[100:101] op_sel:[1,0,0] neg_lo:[0,0,1] neg_hi:[0,0,1]
	v_pk_fma_f32 v[218:219], v[158:159], v[218:219], v[102:103] op_sel:[1,0,0] neg_lo:[0,0,1] neg_hi:[0,0,1]
	v_pk_fma_f32 v[220:221], v[158:159], v[220:221], v[104:105] op_sel:[1,0,0] neg_lo:[0,0,1] neg_hi:[0,0,1]
	v_cvt_pk_bf16_f32 v106, v106, v107
	v_cvt_pk_bf16_f32 v107, v108, v109
	v_cvt_pk_bf16_f32 v108, v218, v219
	v_cvt_pk_bf16_f32 v109, v220, v221
	s_and_saveexec_b64 s[28:29], s[6:7]
	s_cbranch_execz .Lpu0_2
	global_store_dwordx4 v[192:193], v[98:101], off offset:128
	global_store_dwordx4 v[192:193], v[102:105], off offset:144
.Lpu0_2:
	s_or_b64 exec, exec, s[28:29]
	s_waitcnt vmcnt(8)
	v_mfma_f32_32x32x16_bf16 v[2:17], v[106:109], v[112:115], v[2:17]
	v_mfma_f32_32x32x16_bf16 v[18:33], v[106:109], v[116:119], v[18:33]
	v_mfma_f32_32x32x16_bf16 v[34:49], v[106:109], v[122:125], v[34:49]
	v_mfma_f32_32x32x16_bf16 v[50:65], v[106:109], v[126:129], v[50:65]
	global_load_dwordx4 v[112:115], v[144:145], off offset:2560
	global_load_dwordx4 v[116:119], v[146:147], off offset:2560
	global_load_dwordx4 v[122:125], v[148:149], off offset:2560
	global_load_dwordx4 v[126:129], v[150:151], off offset:2560
	s_waitcnt lgkmcnt(7)
	v_lshlrev_b32_e32 v98, 16, v222
	v_and_b32_e32 v99, 0xffff0000, v222
	v_lshlrev_b32_e32 v100, 16, v223
	v_and_b32_e32 v101, 0xffff0000, v223
	v_lshlrev_b32_e32 v102, 16, v224
	v_and_b32_e32 v103, 0xffff0000, v224
	v_lshlrev_b32_e32 v104, 16, v225
	v_and_b32_e32 v105, 0xffff0000, v225
	ds_read_b128 v[222:225], v246 offset:2000
	s_waitcnt lgkmcnt(7)
	v_lshlrev_b32_e32 v216, 16, v226
	v_and_b32_e32 v217, 0xffff0000, v226
	v_lshlrev_b32_e32 v226, 16, v227
	v_and_b32_e32 v227, 0xffff0000, v227
	v_pk_add_f32 v[106:107], v[98:99], v[216:217]
	v_pk_add_f32 v[108:109], v[100:101], v[226:227]
	v_lshlrev_b32_e32 v216, 16, v228
	v_and_b32_e32 v217, 0xffff0000, v228
	v_lshlrev_b32_e32 v228, 16, v229
	v_and_b32_e32 v229, 0xffff0000, v229
	v_pk_add_f32 v[218:219], v[102:103], v[216:217]
	v_pk_add_f32 v[220:221], v[104:105], v[228:229]
	ds_read_b128 v[226:229], v246 offset:1728
	s_waitcnt lgkmcnt(7)
	v_lshlrev_b32_e32 v216, 16, v230
	v_and_b32_e32 v217, 0xffff0000, v230
	v_lshlrev_b32_e32 v230, 16, v231
	v_and_b32_e32 v231, 0xffff0000, v231
	v_pk_add_f32 v[106:107], v[106:107], v[216:217]
	v_pk_add_f32 v[108:109], v[108:109], v[230:231]
	v_lshlrev_b32_e32 v216, 16, v232
	v_and_b32_e32 v217, 0xffff0000, v232
	v_lshlrev_b32_e32 v232, 16, v233
	v_and_b32_e32 v233, 0xffff0000, v233
	v_pk_add_f32 v[218:219], v[218:219], v[216:217]
	v_pk_add_f32 v[220:221], v[220:221], v[232:233]
	ds_read_b128 v[230:233], v246 offset:1456
	s_waitcnt lgkmcnt(7)
	v_lshlrev_b32_e32 v216, 16, v234
	v_and_b32_e32 v217, 0xffff0000, v234
	v_lshlrev_b32_e32 v234, 16, v235
	v_and_b32_e32 v235, 0xffff0000, v235
	v_pk_add_f32 v[106:107], v[106:107], v[216:217]
	v_pk_add_f32 v[108:109], v[108:109], v[234:235]
	v_lshlrev_b32_e32 v216, 16, v236
	v_and_b32_e32 v217, 0xffff0000, v236
	v_lshlrev_b32_e32 v236, 16, v237
	v_and_b32_e32 v237, 0xffff0000, v237
	v_pk_add_f32 v[218:219], v[218:219], v[216:217]
	v_pk_add_f32 v[220:221], v[220:221], v[236:237]
	ds_read_b128 v[234:237], v246 offset:1184
	s_waitcnt lgkmcnt(7)
	v_lshlrev_b32_e32 v216, 16, v238
	v_and_b32_e32 v217, 0xffff0000, v238
	v_lshlrev_b32_e32 v238, 16, v239
	v_and_b32_e32 v239, 0xffff0000, v239
	v_pk_add_f32 v[106:107], v[106:107], v[216:217]
	v_pk_add_f32 v[108:109], v[108:109], v[238:239]
	v_lshlrev_b32_e32 v216, 16, v240
	v_and_b32_e32 v217, 0xffff0000, v240
	v_lshlrev_b32_e32 v240, 16, v241
	v_and_b32_e32 v241, 0xffff0000, v241
	v_pk_add_f32 v[218:219], v[218:219], v[216:217]
	v_pk_add_f32 v[220:221], v[220:221], v[240:241]
	ds_read_b128 v[238:241], v246 offset:912
	s_waitcnt lgkmcnt(7)
	v_lshlrev_b32_e32 v216, 16, v242
	v_and_b32_e32 v217, 0xffff0000, v242
	v_lshlrev_b32_e32 v242, 16, v243
	v_and_b32_e32 v243, 0xffff0000, v243
	v_pk_add_f32 v[106:107], v[106:107], v[216:217]
	v_pk_add_f32 v[108:109], v[108:109], v[242:243]
	v_lshlrev_b32_e32 v216, 16, v244
	v_and_b32_e32 v217, 0xffff0000, v244
	v_lshlrev_b32_e32 v244, 16, v245
	v_and_b32_e32 v245, 0xffff0000, v245
	v_pk_add_f32 v[218:219], v[218:219], v[216:217]
	v_pk_add_f32 v[220:221], v[220:221], v[244:245]
	ds_read_b128 v[242:245], v246 offset:640
	s_waitcnt lgkmcnt(7)
	v_lshlrev_b32_e32 v216, 16, v248
	v_and_b32_e32 v217, 0xffff0000, v248
	v_lshlrev_b32_e32 v248, 16, v249
	v_and_b32_e32 v249, 0xffff0000, v249
	v_pk_add_f32 v[106:107], v[106:107], v[216:217]
	v_pk_add_f32 v[108:109], v[108:109], v[248:249]
	v_lshlrev_b32_e32 v216, 16, v250
	v_and_b32_e32 v217, 0xffff0000, v250
	v_lshlrev_b32_e32 v250, 16, v251
	v_and_b32_e32 v251, 0xffff0000, v251
	v_pk_add_f32 v[218:219], v[218:219], v[216:217]
	v_pk_add_f32 v[220:221], v[220:221], v[250:251]
	ds_read_b128 v[248:251], v246 offset:368
	s_waitcnt lgkmcnt(7)
	v_lshlrev_b32_e32 v216, 16, v252
	v_and_b32_e32 v217, 0xffff0000, v252
	v_lshlrev_b32_e32 v252, 16, v253
	v_and_b32_e32 v253, 0xffff0000, v253
	v_pk_add_f32 v[106:107], v[106:107], v[216:217]
	v_pk_add_f32 v[108:109], v[108:109], v[252:253]
	v_lshlrev_b32_e32 v216, 16, v254
	v_and_b32_e32 v217, 0xffff0000, v254
	v_lshlrev_b32_e32 v254, 16, v255
	v_and_b32_e32 v255, 0xffff0000, v255
	v_pk_add_f32 v[218:219], v[218:219], v[216:217]
	v_pk_add_f32 v[220:221], v[220:221], v[254:255]
	ds_read_b128 v[252:255], v246 offset:96
	s_waitcnt lgkmcnt(7)
	v_lshlrev_b32_e32 v216, 16, v222
	v_and_b32_e32 v217, 0xffff0000, v222
	v_lshlrev_b32_e32 v222, 16, v223
	v_and_b32_e32 v223, 0xffff0000, v223
	v_pk_add_f32 v[106:107], v[106:107], v[216:217]
	v_pk_add_f32 v[108:109], v[108:109], v[222:223]
	v_lshlrev_b32_e32 v216, 16, v224
	v_and_b32_e32 v217, 0xffff0000, v224
	v_lshlrev_b32_e32 v224, 16, v225
	v_and_b32_e32 v225, 0xffff0000, v225
	v_pk_add_f32 v[218:219], v[218:219], v[216:217]
	v_pk_add_f32 v[220:221], v[220:221], v[224:225]
	ds_read_b128 v[222:225], v246 offset:4208
	s_waitcnt lgkmcnt(7)
	v_lshlrev_b32_e32 v216, 16, v226
	v_and_b32_e32 v217, 0xffff0000, v226
	v_lshlrev_b32_e32 v226, 16, v227
	v_and_b32_e32 v227, 0xffff0000, v227
	v_pk_add_f32 v[106:107], v[106:107], v[216:217]
	v_pk_add_f32 v[108:109], v[108:109], v[226:227]
	v_lshlrev_b32_e32 v216, 16, v228
	v_and_b32_e32 v217, 0xffff0000, v228
	v_lshlrev_b32_e32 v228, 16, v229
	v_and_b32_e32 v229, 0xffff0000, v229
	v_pk_add_f32 v[218:219], v[218:219], v[216:217]
	v_pk_add_f32 v[220:221], v[220:221], v[228:229]
	ds_read_b128 v[226:229], v246 offset:3936
	s_waitcnt lgkmcnt(7)
	v_lshlrev_b32_e32 v216, 16, v230
	v_and_b32_e32 v217, 0xffff0000, v230
	v_lshlrev_b32_e32 v230, 16, v231
	v_and_b32_e32 v231, 0xffff0000, v231
	v_pk_add_f32 v[106:107], v[106:107], v[216:217]
	v_pk_add_f32 v[108:109], v[108:109], v[230:231]
	v_lshlrev_b32_e32 v216, 16, v232
	v_and_b32_e32 v217, 0xffff0000, v232
	v_lshlrev_b32_e32 v232, 16, v233
	v_and_b32_e32 v233, 0xffff0000, v233
	v_pk_add_f32 v[218:219], v[218:219], v[216:217]
	v_pk_add_f32 v[220:221], v[220:221], v[232:233]
	ds_read_b128 v[230:233], v246 offset:3664
	s_waitcnt lgkmcnt(7)
	v_lshlrev_b32_e32 v216, 16, v234
	v_and_b32_e32 v217, 0xffff0000, v234
	v_lshlrev_b32_e32 v234, 16, v235
	v_and_b32_e32 v235, 0xffff0000, v235
	v_pk_add_f32 v[106:107], v[106:107], v[216:217]
	v_pk_add_f32 v[108:109], v[108:109], v[234:235]
	v_lshlrev_b32_e32 v216, 16, v236
	v_and_b32_e32 v217, 0xffff0000, v236
	v_lshlrev_b32_e32 v236, 16, v237
	v_and_b32_e32 v237, 0xffff0000, v237
	v_pk_add_f32 v[218:219], v[218:219], v[216:217]
	v_pk_add_f32 v[220:221], v[220:221], v[236:237]
	ds_read_b128 v[234:237], v246 offset:3392
	s_waitcnt lgkmcnt(7)
	v_lshlrev_b32_e32 v216, 16, v238
	v_and_b32_e32 v217, 0xffff0000, v238
	v_lshlrev_b32_e32 v238, 16, v239
	v_and_b32_e32 v239, 0xffff0000, v239
	v_pk_add_f32 v[106:107], v[106:107], v[216:217]
	v_pk_add_f32 v[108:109], v[108:109], v[238:239]
	v_lshlrev_b32_e32 v216, 16, v240
	v_and_b32_e32 v217, 0xffff0000, v240
	v_lshlrev_b32_e32 v240, 16, v241
	v_and_b32_e32 v241, 0xffff0000, v241
	v_pk_add_f32 v[218:219], v[218:219], v[216:217]
	v_pk_add_f32 v[220:221], v[220:221], v[240:241]
	ds_read_b128 v[238:241], v246 offset:3120
	s_waitcnt lgkmcnt(7)
	v_lshlrev_b32_e32 v216, 16, v242
	v_and_b32_e32 v217, 0xffff0000, v242
	v_lshlrev_b32_e32 v242, 16, v243
	v_and_b32_e32 v243, 0xffff0000, v243
	v_pk_add_f32 v[106:107], v[106:107], v[216:217]
	v_pk_add_f32 v[108:109], v[108:109], v[242:243]
	v_lshlrev_b32_e32 v216, 16, v244
	v_and_b32_e32 v217, 0xffff0000, v244
	v_lshlrev_b32_e32 v244, 16, v245
	v_and_b32_e32 v245, 0xffff0000, v245
	v_pk_add_f32 v[218:219], v[218:219], v[216:217]
	v_pk_add_f32 v[220:221], v[220:221], v[244:245]
	ds_read_b128 v[242:245], v246 offset:2848
	s_waitcnt lgkmcnt(7)
	v_lshlrev_b32_e32 v216, 16, v248
	v_and_b32_e32 v217, 0xffff0000, v248
	v_lshlrev_b32_e32 v248, 16, v249
	v_and_b32_e32 v249, 0xffff0000, v249
	v_pk_add_f32 v[106:107], v[106:107], v[216:217]
	v_pk_add_f32 v[108:109], v[108:109], v[248:249]
	v_lshlrev_b32_e32 v216, 16, v250
	v_and_b32_e32 v217, 0xffff0000, v250
	v_lshlrev_b32_e32 v250, 16, v251
	v_and_b32_e32 v251, 0xffff0000, v251
	v_pk_add_f32 v[218:219], v[218:219], v[216:217]
	v_pk_add_f32 v[220:221], v[220:221], v[250:251]
	ds_read_b128 v[248:251], v246 offset:2576
	s_waitcnt lgkmcnt(7)
	v_lshlrev_b32_e32 v216, 16, v252
	v_and_b32_e32 v217, 0xffff0000, v252
	v_lshlrev_b32_e32 v252, 16, v253
	v_and_b32_e32 v253, 0xffff0000, v253
	v_pk_add_f32 v[106:107], v[106:107], v[216:217]
	v_pk_add_f32 v[108:109], v[108:109], v[252:253]
	v_lshlrev_b32_e32 v216, 16, v254
	v_and_b32_e32 v217, 0xffff0000, v254
	v_lshlrev_b32_e32 v254, 16, v255
	v_and_b32_e32 v255, 0xffff0000, v255
	v_pk_add_f32 v[218:219], v[218:219], v[216:217]
	v_pk_add_f32 v[220:221], v[220:221], v[254:255]
	ds_read_b128 v[252:255], v246 offset:2304
	v_pk_fma_f32 v[106:107], v[158:159], v[106:107], v[98:99] op_sel:[1,0,0] neg_lo:[0,0,1] neg_hi:[0,0,1]
	v_pk_fma_f32 v[108:109], v[158:159], v[108:109], v[100:101] op_sel:[1,0,0] neg_lo:[0,0,1] neg_hi:[0,0,1]
	v_pk_fma_f32 v[218:219], v[158:159], v[218:219], v[102:103] op_sel:[1,0,0] neg_lo:[0,0,1] neg_hi:[0,0,1]
	v_pk_fma_f32 v[220:221], v[158:159], v[220:221], v[104:105] op_sel:[1,0,0] neg_lo:[0,0,1] neg_hi:[0,0,1]
	v_cvt_pk_bf16_f32 v106, v106, v107
	v_cvt_pk_bf16_f32 v107, v108, v109
	v_cvt_pk_bf16_f32 v108, v218, v219
	v_cvt_pk_bf16_f32 v109, v220, v221
	s_and_saveexec_b64 s[28:29], s[6:7]
	s_cbranch_execz .Lpu0_3
	global_store_dwordx4 v[192:193], v[98:101], off offset:192
	global_store_dwordx4 v[192:193], v[102:105], off offset:208
.Lpu0_3:
	s_or_b64 exec, exec, s[28:29]
	s_waitcnt vmcnt(8)
	v_mfma_f32_32x32x16_bf16 v[2:17], v[106:109], v[70:73], v[2:17]
	v_mfma_f32_32x32x16_bf16 v[18:33], v[106:109], v[74:77], v[18:33]
	v_mfma_f32_32x32x16_bf16 v[34:49], v[106:109], v[78:81], v[34:49]
	v_mfma_f32_32x32x16_bf16 v[50:65], v[106:109], v[66:69], v[50:65]
	global_load_dwordx4 v[70:73], v[144:145], off offset:3072
	global_load_dwordx4 v[74:77], v[146:147], off offset:3072
	global_load_dwordx4 v[78:81], v[148:149], off offset:3072
	global_load_dwordx4 v[66:69], v[150:151], off offset:3072
	s_waitcnt lgkmcnt(7)
	v_lshlrev_b32_e32 v98, 16, v222
	v_and_b32_e32 v99, 0xffff0000, v222
	v_lshlrev_b32_e32 v100, 16, v223
	v_and_b32_e32 v101, 0xffff0000, v223
	v_lshlrev_b32_e32 v102, 16, v224
	v_and_b32_e32 v103, 0xffff0000, v224
	v_lshlrev_b32_e32 v104, 16, v225
	v_and_b32_e32 v105, 0xffff0000, v225
	ds_read_b128 v[222:225], v246 offset:2032
	s_waitcnt lgkmcnt(7)
	v_lshlrev_b32_e32 v216, 16, v226
	v_and_b32_e32 v217, 0xffff0000, v226
	v_lshlrev_b32_e32 v226, 16, v227
	v_and_b32_e32 v227, 0xffff0000, v227
	v_pk_add_f32 v[106:107], v[98:99], v[216:217]
	v_pk_add_f32 v[108:109], v[100:101], v[226:227]
	v_lshlrev_b32_e32 v216, 16, v228
	v_and_b32_e32 v217, 0xffff0000, v228
	v_lshlrev_b32_e32 v228, 16, v229
	v_and_b32_e32 v229, 0xffff0000, v229
	v_pk_add_f32 v[218:219], v[102:103], v[216:217]
	v_pk_add_f32 v[220:221], v[104:105], v[228:229]
	ds_read_b128 v[226:229], v246 offset:1760
	s_waitcnt lgkmcnt(7)
	v_lshlrev_b32_e32 v216, 16, v230
	v_and_b32_e32 v217, 0xffff0000, v230
	v_lshlrev_b32_e32 v230, 16, v231
	v_and_b32_e32 v231, 0xffff0000, v231
	v_pk_add_f32 v[106:107], v[106:107], v[216:217]
	v_pk_add_f32 v[108:109], v[108:109], v[230:231]
	v_lshlrev_b32_e32 v216, 16, v232
	v_and_b32_e32 v217, 0xffff0000, v232
	v_lshlrev_b32_e32 v232, 16, v233
	v_and_b32_e32 v233, 0xffff0000, v233
	v_pk_add_f32 v[218:219], v[218:219], v[216:217]
	v_pk_add_f32 v[220:221], v[220:221], v[232:233]
	ds_read_b128 v[230:233], v246 offset:1488
	s_waitcnt lgkmcnt(7)
	v_lshlrev_b32_e32 v216, 16, v234
	v_and_b32_e32 v217, 0xffff0000, v234
	v_lshlrev_b32_e32 v234, 16, v235
	v_and_b32_e32 v235, 0xffff0000, v235
	v_pk_add_f32 v[106:107], v[106:107], v[216:217]
	v_pk_add_f32 v[108:109], v[108:109], v[234:235]
	v_lshlrev_b32_e32 v216, 16, v236
	v_and_b32_e32 v217, 0xffff0000, v236
	v_lshlrev_b32_e32 v236, 16, v237
	v_and_b32_e32 v237, 0xffff0000, v237
	v_pk_add_f32 v[218:219], v[218:219], v[216:217]
	v_pk_add_f32 v[220:221], v[220:221], v[236:237]
	ds_read_b128 v[234:237], v246 offset:1216
	s_waitcnt lgkmcnt(7)
	v_lshlrev_b32_e32 v216, 16, v238
	v_and_b32_e32 v217, 0xffff0000, v238
	v_lshlrev_b32_e32 v238, 16, v239
	v_and_b32_e32 v239, 0xffff0000, v239
	v_pk_add_f32 v[106:107], v[106:107], v[216:217]
	v_pk_add_f32 v[108:109], v[108:109], v[238:239]
	v_lshlrev_b32_e32 v216, 16, v240
	v_and_b32_e32 v217, 0xffff0000, v240
	v_lshlrev_b32_e32 v240, 16, v241
	v_and_b32_e32 v241, 0xffff0000, v241
	v_pk_add_f32 v[218:219], v[218:219], v[216:217]
	v_pk_add_f32 v[220:221], v[220:221], v[240:241]
	ds_read_b128 v[238:241], v246 offset:944
	s_waitcnt lgkmcnt(7)
	v_lshlrev_b32_e32 v216, 16, v242
	v_and_b32_e32 v217, 0xffff0000, v242
	v_lshlrev_b32_e32 v242, 16, v243
	v_and_b32_e32 v243, 0xffff0000, v243
	v_pk_add_f32 v[106:107], v[106:107], v[216:217]
	v_pk_add_f32 v[108:109], v[108:109], v[242:243]
	v_lshlrev_b32_e32 v216, 16, v244
	v_and_b32_e32 v217, 0xffff0000, v244
	v_lshlrev_b32_e32 v244, 16, v245
	v_and_b32_e32 v245, 0xffff0000, v245
	v_pk_add_f32 v[218:219], v[218:219], v[216:217]
	v_pk_add_f32 v[220:221], v[220:221], v[244:245]
	ds_read_b128 v[242:245], v246 offset:672
	s_waitcnt lgkmcnt(7)
	v_lshlrev_b32_e32 v216, 16, v248
	v_and_b32_e32 v217, 0xffff0000, v248
	v_lshlrev_b32_e32 v248, 16, v249
	v_and_b32_e32 v249, 0xffff0000, v249
	v_pk_add_f32 v[106:107], v[106:107], v[216:217]
	v_pk_add_f32 v[108:109], v[108:109], v[248:249]
	v_lshlrev_b32_e32 v216, 16, v250
	v_and_b32_e32 v217, 0xffff0000, v250
	v_lshlrev_b32_e32 v250, 16, v251
	v_and_b32_e32 v251, 0xffff0000, v251
	v_pk_add_f32 v[218:219], v[218:219], v[216:217]
	v_pk_add_f32 v[220:221], v[220:221], v[250:251]
	ds_read_b128 v[248:251], v246 offset:400
	s_waitcnt lgkmcnt(7)
	v_lshlrev_b32_e32 v216, 16, v252
	v_and_b32_e32 v217, 0xffff0000, v252
	v_lshlrev_b32_e32 v252, 16, v253
	v_and_b32_e32 v253, 0xffff0000, v253
	v_pk_add_f32 v[106:107], v[106:107], v[216:217]
	v_pk_add_f32 v[108:109], v[108:109], v[252:253]
	v_lshlrev_b32_e32 v216, 16, v254
	v_and_b32_e32 v217, 0xffff0000, v254
	v_lshlrev_b32_e32 v254, 16, v255
	v_and_b32_e32 v255, 0xffff0000, v255
	v_pk_add_f32 v[218:219], v[218:219], v[216:217]
	v_pk_add_f32 v[220:221], v[220:221], v[254:255]
	ds_read_b128 v[252:255], v246 offset:128
	s_waitcnt lgkmcnt(7)
	v_lshlrev_b32_e32 v216, 16, v222
	v_and_b32_e32 v217, 0xffff0000, v222
	v_lshlrev_b32_e32 v222, 16, v223
	v_and_b32_e32 v223, 0xffff0000, v223
	v_pk_add_f32 v[106:107], v[106:107], v[216:217]
	v_pk_add_f32 v[108:109], v[108:109], v[222:223]
	v_lshlrev_b32_e32 v216, 16, v224
	v_and_b32_e32 v217, 0xffff0000, v224
	v_lshlrev_b32_e32 v224, 16, v225
	v_and_b32_e32 v225, 0xffff0000, v225
	v_pk_add_f32 v[218:219], v[218:219], v[216:217]
	v_pk_add_f32 v[220:221], v[220:221], v[224:225]
	ds_read_b128 v[222:225], v246 offset:4240
	s_waitcnt lgkmcnt(7)
	v_lshlrev_b32_e32 v216, 16, v226
	v_and_b32_e32 v217, 0xffff0000, v226
	v_lshlrev_b32_e32 v226, 16, v227
	v_and_b32_e32 v227, 0xffff0000, v227
	v_pk_add_f32 v[106:107], v[106:107], v[216:217]
	v_pk_add_f32 v[108:109], v[108:109], v[226:227]
	v_lshlrev_b32_e32 v216, 16, v228
	v_and_b32_e32 v217, 0xffff0000, v228
	v_lshlrev_b32_e32 v228, 16, v229
	v_and_b32_e32 v229, 0xffff0000, v229
	v_pk_add_f32 v[218:219], v[218:219], v[216:217]
	v_pk_add_f32 v[220:221], v[220:221], v[228:229]
	ds_read_b128 v[226:229], v246 offset:3968
	s_waitcnt lgkmcnt(7)
	v_lshlrev_b32_e32 v216, 16, v230
	v_and_b32_e32 v217, 0xffff0000, v230
	v_lshlrev_b32_e32 v230, 16, v231
	v_and_b32_e32 v231, 0xffff0000, v231
	v_pk_add_f32 v[106:107], v[106:107], v[216:217]
	v_pk_add_f32 v[108:109], v[108:109], v[230:231]
	v_lshlrev_b32_e32 v216, 16, v232
	v_and_b32_e32 v217, 0xffff0000, v232
	v_lshlrev_b32_e32 v232, 16, v233
	v_and_b32_e32 v233, 0xffff0000, v233
	v_pk_add_f32 v[218:219], v[218:219], v[216:217]
	v_pk_add_f32 v[220:221], v[220:221], v[232:233]
	ds_read_b128 v[230:233], v246 offset:3696
	s_waitcnt lgkmcnt(7)
	v_lshlrev_b32_e32 v216, 16, v234
	v_and_b32_e32 v217, 0xffff0000, v234
	v_lshlrev_b32_e32 v234, 16, v235
	v_and_b32_e32 v235, 0xffff0000, v235
	v_pk_add_f32 v[106:107], v[106:107], v[216:217]
	v_pk_add_f32 v[108:109], v[108:109], v[234:235]
	v_lshlrev_b32_e32 v216, 16, v236
	v_and_b32_e32 v217, 0xffff0000, v236
	v_lshlrev_b32_e32 v236, 16, v237
	v_and_b32_e32 v237, 0xffff0000, v237
	v_pk_add_f32 v[218:219], v[218:219], v[216:217]
	v_pk_add_f32 v[220:221], v[220:221], v[236:237]
	ds_read_b128 v[234:237], v246 offset:3424
	s_waitcnt lgkmcnt(7)
	v_lshlrev_b32_e32 v216, 16, v238
	v_and_b32_e32 v217, 0xffff0000, v238
	v_lshlrev_b32_e32 v238, 16, v239
	v_and_b32_e32 v239, 0xffff0000, v239
	v_pk_add_f32 v[106:107], v[106:107], v[216:217]
	v_pk_add_f32 v[108:109], v[108:109], v[238:239]
	v_lshlrev_b32_e32 v216, 16, v240
	v_and_b32_e32 v217, 0xffff0000, v240
	v_lshlrev_b32_e32 v240, 16, v241
	v_and_b32_e32 v241, 0xffff0000, v241
	v_pk_add_f32 v[218:219], v[218:219], v[216:217]
	v_pk_add_f32 v[220:221], v[220:221], v[240:241]
	ds_read_b128 v[238:241], v246 offset:3152
	s_waitcnt lgkmcnt(7)
	v_lshlrev_b32_e32 v216, 16, v242
	v_and_b32_e32 v217, 0xffff0000, v242
	v_lshlrev_b32_e32 v242, 16, v243
	v_and_b32_e32 v243, 0xffff0000, v243
	v_pk_add_f32 v[106:107], v[106:107], v[216:217]
	v_pk_add_f32 v[108:109], v[108:109], v[242:243]
	v_lshlrev_b32_e32 v216, 16, v244
	v_and_b32_e32 v217, 0xffff0000, v244
	v_lshlrev_b32_e32 v244, 16, v245
	v_and_b32_e32 v245, 0xffff0000, v245
	v_pk_add_f32 v[218:219], v[218:219], v[216:217]
	v_pk_add_f32 v[220:221], v[220:221], v[244:245]
	ds_read_b128 v[242:245], v246 offset:2880
	s_waitcnt lgkmcnt(7)
	v_lshlrev_b32_e32 v216, 16, v248
	v_and_b32_e32 v217, 0xffff0000, v248
	v_lshlrev_b32_e32 v248, 16, v249
	v_and_b32_e32 v249, 0xffff0000, v249
	v_pk_add_f32 v[106:107], v[106:107], v[216:217]
	v_pk_add_f32 v[108:109], v[108:109], v[248:249]
	v_lshlrev_b32_e32 v216, 16, v250
	v_and_b32_e32 v217, 0xffff0000, v250
	v_lshlrev_b32_e32 v250, 16, v251
	v_and_b32_e32 v251, 0xffff0000, v251
	v_pk_add_f32 v[218:219], v[218:219], v[216:217]
	v_pk_add_f32 v[220:221], v[220:221], v[250:251]
	ds_read_b128 v[248:251], v246 offset:2608
	s_waitcnt lgkmcnt(7)
	v_lshlrev_b32_e32 v216, 16, v252
	v_and_b32_e32 v217, 0xffff0000, v252
	v_lshlrev_b32_e32 v252, 16, v253
	v_and_b32_e32 v253, 0xffff0000, v253
	v_pk_add_f32 v[106:107], v[106:107], v[216:217]
	v_pk_add_f32 v[108:109], v[108:109], v[252:253]
	v_lshlrev_b32_e32 v216, 16, v254
	v_and_b32_e32 v217, 0xffff0000, v254
	v_lshlrev_b32_e32 v254, 16, v255
	v_and_b32_e32 v255, 0xffff0000, v255
	v_pk_add_f32 v[218:219], v[218:219], v[216:217]
	v_pk_add_f32 v[220:221], v[220:221], v[254:255]
	ds_read_b128 v[252:255], v246 offset:2336
	v_pk_fma_f32 v[106:107], v[158:159], v[106:107], v[98:99] op_sel:[1,0,0] neg_lo:[0,0,1] neg_hi:[0,0,1]
	v_pk_fma_f32 v[108:109], v[158:159], v[108:109], v[100:101] op_sel:[1,0,0] neg_lo:[0,0,1] neg_hi:[0,0,1]
	v_pk_fma_f32 v[218:219], v[158:159], v[218:219], v[102:103] op_sel:[1,0,0] neg_lo:[0,0,1] neg_hi:[0,0,1]
	v_pk_fma_f32 v[220:221], v[158:159], v[220:221], v[104:105] op_sel:[1,0,0] neg_lo:[0,0,1] neg_hi:[0,0,1]
	v_cvt_pk_bf16_f32 v106, v106, v107
	v_cvt_pk_bf16_f32 v107, v108, v109
	v_cvt_pk_bf16_f32 v108, v218, v219
	v_cvt_pk_bf16_f32 v109, v220, v221
	s_and_saveexec_b64 s[28:29], s[6:7]
	s_cbranch_execz .Lpu0_4
	global_store_dwordx4 v[192:193], v[98:101], off offset:256
	global_store_dwordx4 v[192:193], v[102:105], off offset:272
.Lpu0_4:
	s_or_b64 exec, exec, s[28:29]
	s_waitcnt vmcnt(8)
	v_mfma_f32_32x32x16_bf16 v[2:17], v[106:109], v[82:85], v[2:17]
	v_mfma_f32_32x32x16_bf16 v[18:33], v[106:109], v[86:89], v[18:33]
	v_mfma_f32_32x32x16_bf16 v[34:49], v[106:109], v[90:93], v[34:49]
	v_mfma_f32_32x32x16_bf16 v[50:65], v[106:109], v[94:97], v[50:65]
	global_load_dwordx4 v[82:85], v[144:145], off offset:3584
	global_load_dwordx4 v[86:89], v[146:147], off offset:3584
	global_load_dwordx4 v[90:93], v[148:149], off offset:3584
	global_load_dwordx4 v[94:97], v[150:151], off offset:3584
	s_waitcnt lgkmcnt(7)
	v_lshlrev_b32_e32 v98, 16, v222
	v_and_b32_e32 v99, 0xffff0000, v222
	v_lshlrev_b32_e32 v100, 16, v223
	v_and_b32_e32 v101, 0xffff0000, v223
	v_lshlrev_b32_e32 v102, 16, v224
	v_and_b32_e32 v103, 0xffff0000, v224
	v_lshlrev_b32_e32 v104, 16, v225
	v_and_b32_e32 v105, 0xffff0000, v225
	ds_read_b128 v[222:225], v246 offset:2064
	s_waitcnt lgkmcnt(7)
	v_lshlrev_b32_e32 v216, 16, v226
	v_and_b32_e32 v217, 0xffff0000, v226
	v_lshlrev_b32_e32 v226, 16, v227
	v_and_b32_e32 v227, 0xffff0000, v227
	v_pk_add_f32 v[106:107], v[98:99], v[216:217]
	v_pk_add_f32 v[108:109], v[100:101], v[226:227]
	v_lshlrev_b32_e32 v216, 16, v228
	v_and_b32_e32 v217, 0xffff0000, v228
	v_lshlrev_b32_e32 v228, 16, v229
	v_and_b32_e32 v229, 0xffff0000, v229
	v_pk_add_f32 v[218:219], v[102:103], v[216:217]
	v_pk_add_f32 v[220:221], v[104:105], v[228:229]
	ds_read_b128 v[226:229], v246 offset:1792
	s_waitcnt lgkmcnt(7)
	v_lshlrev_b32_e32 v216, 16, v230
	v_and_b32_e32 v217, 0xffff0000, v230
	v_lshlrev_b32_e32 v230, 16, v231
	v_and_b32_e32 v231, 0xffff0000, v231
	v_pk_add_f32 v[106:107], v[106:107], v[216:217]
	v_pk_add_f32 v[108:109], v[108:109], v[230:231]
	v_lshlrev_b32_e32 v216, 16, v232
	v_and_b32_e32 v217, 0xffff0000, v232
	v_lshlrev_b32_e32 v232, 16, v233
	v_and_b32_e32 v233, 0xffff0000, v233
	v_pk_add_f32 v[218:219], v[218:219], v[216:217]
	v_pk_add_f32 v[220:221], v[220:221], v[232:233]
	ds_read_b128 v[230:233], v246 offset:1520
	s_waitcnt lgkmcnt(7)
	v_lshlrev_b32_e32 v216, 16, v234
	v_and_b32_e32 v217, 0xffff0000, v234
	v_lshlrev_b32_e32 v234, 16, v235
	v_and_b32_e32 v235, 0xffff0000, v235
	v_pk_add_f32 v[106:107], v[106:107], v[216:217]
	v_pk_add_f32 v[108:109], v[108:109], v[234:235]
	v_lshlrev_b32_e32 v216, 16, v236
	v_and_b32_e32 v217, 0xffff0000, v236
	v_lshlrev_b32_e32 v236, 16, v237
	v_and_b32_e32 v237, 0xffff0000, v237
	v_pk_add_f32 v[218:219], v[218:219], v[216:217]
	v_pk_add_f32 v[220:221], v[220:221], v[236:237]
	ds_read_b128 v[234:237], v246 offset:1248
	s_waitcnt lgkmcnt(7)
	v_lshlrev_b32_e32 v216, 16, v238
	v_and_b32_e32 v217, 0xffff0000, v238
	v_lshlrev_b32_e32 v238, 16, v239
	v_and_b32_e32 v239, 0xffff0000, v239
	v_pk_add_f32 v[106:107], v[106:107], v[216:217]
	v_pk_add_f32 v[108:109], v[108:109], v[238:239]
	v_lshlrev_b32_e32 v216, 16, v240
	v_and_b32_e32 v217, 0xffff0000, v240
	v_lshlrev_b32_e32 v240, 16, v241
	v_and_b32_e32 v241, 0xffff0000, v241
	v_pk_add_f32 v[218:219], v[218:219], v[216:217]
	v_pk_add_f32 v[220:221], v[220:221], v[240:241]
	ds_read_b128 v[238:241], v246 offset:976
	s_waitcnt lgkmcnt(7)
	v_lshlrev_b32_e32 v216, 16, v242
	v_and_b32_e32 v217, 0xffff0000, v242
	v_lshlrev_b32_e32 v242, 16, v243
	v_and_b32_e32 v243, 0xffff0000, v243
	v_pk_add_f32 v[106:107], v[106:107], v[216:217]
	v_pk_add_f32 v[108:109], v[108:109], v[242:243]
	v_lshlrev_b32_e32 v216, 16, v244
	v_and_b32_e32 v217, 0xffff0000, v244
	v_lshlrev_b32_e32 v244, 16, v245
	v_and_b32_e32 v245, 0xffff0000, v245
	v_pk_add_f32 v[218:219], v[218:219], v[216:217]
	v_pk_add_f32 v[220:221], v[220:221], v[244:245]
	ds_read_b128 v[242:245], v246 offset:704
	s_waitcnt lgkmcnt(7)
	v_lshlrev_b32_e32 v216, 16, v248
	v_and_b32_e32 v217, 0xffff0000, v248
	v_lshlrev_b32_e32 v248, 16, v249
	v_and_b32_e32 v249, 0xffff0000, v249
	v_pk_add_f32 v[106:107], v[106:107], v[216:217]
	v_pk_add_f32 v[108:109], v[108:109], v[248:249]
	v_lshlrev_b32_e32 v216, 16, v250
	v_and_b32_e32 v217, 0xffff0000, v250
	v_lshlrev_b32_e32 v250, 16, v251
	v_and_b32_e32 v251, 0xffff0000, v251
	v_pk_add_f32 v[218:219], v[218:219], v[216:217]
	v_pk_add_f32 v[220:221], v[220:221], v[250:251]
	ds_read_b128 v[248:251], v246 offset:432
	s_waitcnt lgkmcnt(7)
	v_lshlrev_b32_e32 v216, 16, v252
	v_and_b32_e32 v217, 0xffff0000, v252
	v_lshlrev_b32_e32 v252, 16, v253
	v_and_b32_e32 v253, 0xffff0000, v253
	v_pk_add_f32 v[106:107], v[106:107], v[216:217]
	v_pk_add_f32 v[108:109], v[108:109], v[252:253]
	v_lshlrev_b32_e32 v216, 16, v254
	v_and_b32_e32 v217, 0xffff0000, v254
	v_lshlrev_b32_e32 v254, 16, v255
	v_and_b32_e32 v255, 0xffff0000, v255
	v_pk_add_f32 v[218:219], v[218:219], v[216:217]
	v_pk_add_f32 v[220:221], v[220:221], v[254:255]
	ds_read_b128 v[252:255], v246 offset:160
	s_waitcnt lgkmcnt(7)
	v_lshlrev_b32_e32 v216, 16, v222
	v_and_b32_e32 v217, 0xffff0000, v222
	v_lshlrev_b32_e32 v222, 16, v223
	v_and_b32_e32 v223, 0xffff0000, v223
	v_pk_add_f32 v[106:107], v[106:107], v[216:217]
	v_pk_add_f32 v[108:109], v[108:109], v[222:223]
	v_lshlrev_b32_e32 v216, 16, v224
	v_and_b32_e32 v217, 0xffff0000, v224
	v_lshlrev_b32_e32 v224, 16, v225
	v_and_b32_e32 v225, 0xffff0000, v225
	v_pk_add_f32 v[218:219], v[218:219], v[216:217]
	v_pk_add_f32 v[220:221], v[220:221], v[224:225]
	ds_read_b128 v[222:225], v246 offset:4272
	s_waitcnt lgkmcnt(7)
	v_lshlrev_b32_e32 v216, 16, v226
	v_and_b32_e32 v217, 0xffff0000, v226
	v_lshlrev_b32_e32 v226, 16, v227
	v_and_b32_e32 v227, 0xffff0000, v227
	v_pk_add_f32 v[106:107], v[106:107], v[216:217]
	v_pk_add_f32 v[108:109], v[108:109], v[226:227]
	v_lshlrev_b32_e32 v216, 16, v228
	v_and_b32_e32 v217, 0xffff0000, v228
	v_lshlrev_b32_e32 v228, 16, v229
	v_and_b32_e32 v229, 0xffff0000, v229
	v_pk_add_f32 v[218:219], v[218:219], v[216:217]
	v_pk_add_f32 v[220:221], v[220:221], v[228:229]
	ds_read_b128 v[226:229], v246 offset:4000
	s_waitcnt lgkmcnt(7)
	v_lshlrev_b32_e32 v216, 16, v230
	v_and_b32_e32 v217, 0xffff0000, v230
	v_lshlrev_b32_e32 v230, 16, v231
	v_and_b32_e32 v231, 0xffff0000, v231
	v_pk_add_f32 v[106:107], v[106:107], v[216:217]
	v_pk_add_f32 v[108:109], v[108:109], v[230:231]
	v_lshlrev_b32_e32 v216, 16, v232
	v_and_b32_e32 v217, 0xffff0000, v232
	v_lshlrev_b32_e32 v232, 16, v233
	v_and_b32_e32 v233, 0xffff0000, v233
	v_pk_add_f32 v[218:219], v[218:219], v[216:217]
	v_pk_add_f32 v[220:221], v[220:221], v[232:233]
	ds_read_b128 v[230:233], v246 offset:3728
	s_waitcnt lgkmcnt(7)
	v_lshlrev_b32_e32 v216, 16, v234
	v_and_b32_e32 v217, 0xffff0000, v234
	v_lshlrev_b32_e32 v234, 16, v235
	v_and_b32_e32 v235, 0xffff0000, v235
	v_pk_add_f32 v[106:107], v[106:107], v[216:217]
	v_pk_add_f32 v[108:109], v[108:109], v[234:235]
	v_lshlrev_b32_e32 v216, 16, v236
	v_and_b32_e32 v217, 0xffff0000, v236
	v_lshlrev_b32_e32 v236, 16, v237
	v_and_b32_e32 v237, 0xffff0000, v237
	v_pk_add_f32 v[218:219], v[218:219], v[216:217]
	v_pk_add_f32 v[220:221], v[220:221], v[236:237]
	ds_read_b128 v[234:237], v246 offset:3456
	s_waitcnt lgkmcnt(7)
	v_lshlrev_b32_e32 v216, 16, v238
	v_and_b32_e32 v217, 0xffff0000, v238
	v_lshlrev_b32_e32 v238, 16, v239
	v_and_b32_e32 v239, 0xffff0000, v239
	v_pk_add_f32 v[106:107], v[106:107], v[216:217]
	v_pk_add_f32 v[108:109], v[108:109], v[238:239]
	v_lshlrev_b32_e32 v216, 16, v240
	v_and_b32_e32 v217, 0xffff0000, v240
	v_lshlrev_b32_e32 v240, 16, v241
	v_and_b32_e32 v241, 0xffff0000, v241
	v_pk_add_f32 v[218:219], v[218:219], v[216:217]
	v_pk_add_f32 v[220:221], v[220:221], v[240:241]
	ds_read_b128 v[238:241], v246 offset:3184
	s_waitcnt lgkmcnt(7)
	v_lshlrev_b32_e32 v216, 16, v242
	v_and_b32_e32 v217, 0xffff0000, v242
	v_lshlrev_b32_e32 v242, 16, v243
	v_and_b32_e32 v243, 0xffff0000, v243
	v_pk_add_f32 v[106:107], v[106:107], v[216:217]
	v_pk_add_f32 v[108:109], v[108:109], v[242:243]
	v_lshlrev_b32_e32 v216, 16, v244
	v_and_b32_e32 v217, 0xffff0000, v244
	v_lshlrev_b32_e32 v244, 16, v245
	v_and_b32_e32 v245, 0xffff0000, v245
	v_pk_add_f32 v[218:219], v[218:219], v[216:217]
	v_pk_add_f32 v[220:221], v[220:221], v[244:245]
	ds_read_b128 v[242:245], v246 offset:2912
	s_waitcnt lgkmcnt(7)
	v_lshlrev_b32_e32 v216, 16, v248
	v_and_b32_e32 v217, 0xffff0000, v248
	v_lshlrev_b32_e32 v248, 16, v249
	v_and_b32_e32 v249, 0xffff0000, v249
	v_pk_add_f32 v[106:107], v[106:107], v[216:217]
	v_pk_add_f32 v[108:109], v[108:109], v[248:249]
	v_lshlrev_b32_e32 v216, 16, v250
	v_and_b32_e32 v217, 0xffff0000, v250
	v_lshlrev_b32_e32 v250, 16, v251
	v_and_b32_e32 v251, 0xffff0000, v251
	v_pk_add_f32 v[218:219], v[218:219], v[216:217]
	v_pk_add_f32 v[220:221], v[220:221], v[250:251]
	ds_read_b128 v[248:251], v246 offset:2640
	s_waitcnt lgkmcnt(7)
	v_lshlrev_b32_e32 v216, 16, v252
	v_and_b32_e32 v217, 0xffff0000, v252
	v_lshlrev_b32_e32 v252, 16, v253
	v_and_b32_e32 v253, 0xffff0000, v253
	v_pk_add_f32 v[106:107], v[106:107], v[216:217]
	v_pk_add_f32 v[108:109], v[108:109], v[252:253]
	v_lshlrev_b32_e32 v216, 16, v254
	v_and_b32_e32 v217, 0xffff0000, v254
	v_lshlrev_b32_e32 v254, 16, v255
	v_and_b32_e32 v255, 0xffff0000, v255
	v_pk_add_f32 v[218:219], v[218:219], v[216:217]
	v_pk_add_f32 v[220:221], v[220:221], v[254:255]
	ds_read_b128 v[252:255], v246 offset:2368
	v_pk_fma_f32 v[106:107], v[158:159], v[106:107], v[98:99] op_sel:[1,0,0] neg_lo:[0,0,1] neg_hi:[0,0,1]
	v_pk_fma_f32 v[108:109], v[158:159], v[108:109], v[100:101] op_sel:[1,0,0] neg_lo:[0,0,1] neg_hi:[0,0,1]
	v_pk_fma_f32 v[218:219], v[158:159], v[218:219], v[102:103] op_sel:[1,0,0] neg_lo:[0,0,1] neg_hi:[0,0,1]
	v_pk_fma_f32 v[220:221], v[158:159], v[220:221], v[104:105] op_sel:[1,0,0] neg_lo:[0,0,1] neg_hi:[0,0,1]
	v_cvt_pk_bf16_f32 v106, v106, v107
	v_cvt_pk_bf16_f32 v107, v108, v109
	v_cvt_pk_bf16_f32 v108, v218, v219
	v_cvt_pk_bf16_f32 v109, v220, v221
	s_and_saveexec_b64 s[28:29], s[6:7]
	s_cbranch_execz .Lpu0_5
	global_store_dwordx4 v[192:193], v[98:101], off offset:320
	global_store_dwordx4 v[192:193], v[102:105], off offset:336
.Lpu0_5:
	s_or_b64 exec, exec, s[28:29]
	s_waitcnt vmcnt(8)
	v_mfma_f32_32x32x16_bf16 v[2:17], v[106:109], v[112:115], v[2:17]
	v_mfma_f32_32x32x16_bf16 v[18:33], v[106:109], v[116:119], v[18:33]
	v_mfma_f32_32x32x16_bf16 v[34:49], v[106:109], v[122:125], v[34:49]
	v_mfma_f32_32x32x16_bf16 v[50:65], v[106:109], v[126:129], v[50:65]
	s_waitcnt lgkmcnt(7)
	v_lshlrev_b32_e32 v98, 16, v222
	v_and_b32_e32 v99, 0xffff0000, v222
	v_lshlrev_b32_e32 v100, 16, v223
	v_and_b32_e32 v101, 0xffff0000, v223
	v_lshlrev_b32_e32 v102, 16, v224
	v_and_b32_e32 v103, 0xffff0000, v224
	v_lshlrev_b32_e32 v104, 16, v225
	v_and_b32_e32 v105, 0xffff0000, v225
	ds_read_b128 v[222:225], v246 offset:2096
	s_waitcnt lgkmcnt(7)
	v_lshlrev_b32_e32 v216, 16, v226
	v_and_b32_e32 v217, 0xffff0000, v226
	v_lshlrev_b32_e32 v226, 16, v227
	v_and_b32_e32 v227, 0xffff0000, v227
	v_pk_add_f32 v[106:107], v[98:99], v[216:217]
	v_pk_add_f32 v[108:109], v[100:101], v[226:227]
	v_lshlrev_b32_e32 v216, 16, v228
	v_and_b32_e32 v217, 0xffff0000, v228
	v_lshlrev_b32_e32 v228, 16, v229
	v_and_b32_e32 v229, 0xffff0000, v229
	v_pk_add_f32 v[218:219], v[102:103], v[216:217]
	v_pk_add_f32 v[220:221], v[104:105], v[228:229]
	ds_read_b128 v[226:229], v246 offset:1824
	s_waitcnt lgkmcnt(7)
	v_lshlrev_b32_e32 v216, 16, v230
	v_and_b32_e32 v217, 0xffff0000, v230
	v_lshlrev_b32_e32 v230, 16, v231
	v_and_b32_e32 v231, 0xffff0000, v231
	v_pk_add_f32 v[106:107], v[106:107], v[216:217]
	v_pk_add_f32 v[108:109], v[108:109], v[230:231]
	v_lshlrev_b32_e32 v216, 16, v232
	v_and_b32_e32 v217, 0xffff0000, v232
	v_lshlrev_b32_e32 v232, 16, v233
	v_and_b32_e32 v233, 0xffff0000, v233
	v_pk_add_f32 v[218:219], v[218:219], v[216:217]
	v_pk_add_f32 v[220:221], v[220:221], v[232:233]
	ds_read_b128 v[230:233], v246 offset:1552
	s_waitcnt lgkmcnt(7)
	v_lshlrev_b32_e32 v216, 16, v234
	v_and_b32_e32 v217, 0xffff0000, v234
	v_lshlrev_b32_e32 v234, 16, v235
	v_and_b32_e32 v235, 0xffff0000, v235
	v_pk_add_f32 v[106:107], v[106:107], v[216:217]
	v_pk_add_f32 v[108:109], v[108:109], v[234:235]
	v_lshlrev_b32_e32 v216, 16, v236
	v_and_b32_e32 v217, 0xffff0000, v236
	v_lshlrev_b32_e32 v236, 16, v237
	v_and_b32_e32 v237, 0xffff0000, v237
	v_pk_add_f32 v[218:219], v[218:219], v[216:217]
	v_pk_add_f32 v[220:221], v[220:221], v[236:237]
	ds_read_b128 v[234:237], v246 offset:1280
	s_waitcnt lgkmcnt(7)
	v_lshlrev_b32_e32 v216, 16, v238
	v_and_b32_e32 v217, 0xffff0000, v238
	v_lshlrev_b32_e32 v238, 16, v239
	v_and_b32_e32 v239, 0xffff0000, v239
	v_pk_add_f32 v[106:107], v[106:107], v[216:217]
	v_pk_add_f32 v[108:109], v[108:109], v[238:239]
	v_lshlrev_b32_e32 v216, 16, v240
	v_and_b32_e32 v217, 0xffff0000, v240
	v_lshlrev_b32_e32 v240, 16, v241
	v_and_b32_e32 v241, 0xffff0000, v241
	v_pk_add_f32 v[218:219], v[218:219], v[216:217]
	v_pk_add_f32 v[220:221], v[220:221], v[240:241]
	ds_read_b128 v[238:241], v246 offset:1008
	s_waitcnt lgkmcnt(7)
	v_lshlrev_b32_e32 v216, 16, v242
	v_and_b32_e32 v217, 0xffff0000, v242
	v_lshlrev_b32_e32 v242, 16, v243
	v_and_b32_e32 v243, 0xffff0000, v243
	v_pk_add_f32 v[106:107], v[106:107], v[216:217]
	v_pk_add_f32 v[108:109], v[108:109], v[242:243]
	v_lshlrev_b32_e32 v216, 16, v244
	v_and_b32_e32 v217, 0xffff0000, v244
	v_lshlrev_b32_e32 v244, 16, v245
	v_and_b32_e32 v245, 0xffff0000, v245
	v_pk_add_f32 v[218:219], v[218:219], v[216:217]
	v_pk_add_f32 v[220:221], v[220:221], v[244:245]
	ds_read_b128 v[242:245], v246 offset:736
	s_waitcnt lgkmcnt(7)
	v_lshlrev_b32_e32 v216, 16, v248
	v_and_b32_e32 v217, 0xffff0000, v248
	v_lshlrev_b32_e32 v248, 16, v249
	v_and_b32_e32 v249, 0xffff0000, v249
	v_pk_add_f32 v[106:107], v[106:107], v[216:217]
	v_pk_add_f32 v[108:109], v[108:109], v[248:249]
	v_lshlrev_b32_e32 v216, 16, v250
	v_and_b32_e32 v217, 0xffff0000, v250
	v_lshlrev_b32_e32 v250, 16, v251
	v_and_b32_e32 v251, 0xffff0000, v251
	v_pk_add_f32 v[218:219], v[218:219], v[216:217]
	v_pk_add_f32 v[220:221], v[220:221], v[250:251]
	ds_read_b128 v[248:251], v246 offset:464
	s_waitcnt lgkmcnt(7)
	v_lshlrev_b32_e32 v216, 16, v252
	v_and_b32_e32 v217, 0xffff0000, v252
	v_lshlrev_b32_e32 v252, 16, v253
	v_and_b32_e32 v253, 0xffff0000, v253
	v_pk_add_f32 v[106:107], v[106:107], v[216:217]
	v_pk_add_f32 v[108:109], v[108:109], v[252:253]
	v_lshlrev_b32_e32 v216, 16, v254
	v_and_b32_e32 v217, 0xffff0000, v254
	v_lshlrev_b32_e32 v254, 16, v255
	v_and_b32_e32 v255, 0xffff0000, v255
	v_pk_add_f32 v[218:219], v[218:219], v[216:217]
	v_pk_add_f32 v[220:221], v[220:221], v[254:255]
	ds_read_b128 v[252:255], v246 offset:192
	s_waitcnt lgkmcnt(7)
	v_lshlrev_b32_e32 v216, 16, v222
	v_and_b32_e32 v217, 0xffff0000, v222
	v_lshlrev_b32_e32 v222, 16, v223
	v_and_b32_e32 v223, 0xffff0000, v223
	v_pk_add_f32 v[106:107], v[106:107], v[216:217]
	v_pk_add_f32 v[108:109], v[108:109], v[222:223]
	v_lshlrev_b32_e32 v216, 16, v224
	v_and_b32_e32 v217, 0xffff0000, v224
	v_lshlrev_b32_e32 v224, 16, v225
	v_and_b32_e32 v225, 0xffff0000, v225
	v_pk_add_f32 v[218:219], v[218:219], v[216:217]
	v_pk_add_f32 v[220:221], v[220:221], v[224:225]
	ds_read_b128 v[222:225], v246 offset:4304
	s_waitcnt lgkmcnt(7)
	v_lshlrev_b32_e32 v216, 16, v226
	v_and_b32_e32 v217, 0xffff0000, v226
	v_lshlrev_b32_e32 v226, 16, v227
	v_and_b32_e32 v227, 0xffff0000, v227
	v_pk_add_f32 v[106:107], v[106:107], v[216:217]
	v_pk_add_f32 v[108:109], v[108:109], v[226:227]
	v_lshlrev_b32_e32 v216, 16, v228
	v_and_b32_e32 v217, 0xffff0000, v228
	v_lshlrev_b32_e32 v228, 16, v229
	v_and_b32_e32 v229, 0xffff0000, v229
	v_pk_add_f32 v[218:219], v[218:219], v[216:217]
	v_pk_add_f32 v[220:221], v[220:221], v[228:229]
	ds_read_b128 v[226:229], v246 offset:4032
	s_waitcnt lgkmcnt(7)
	v_lshlrev_b32_e32 v216, 16, v230
	v_and_b32_e32 v217, 0xffff0000, v230
	v_lshlrev_b32_e32 v230, 16, v231
	v_and_b32_e32 v231, 0xffff0000, v231
	v_pk_add_f32 v[106:107], v[106:107], v[216:217]
	v_pk_add_f32 v[108:109], v[108:109], v[230:231]
	v_lshlrev_b32_e32 v216, 16, v232
	v_and_b32_e32 v217, 0xffff0000, v232
	v_lshlrev_b32_e32 v232, 16, v233
	v_and_b32_e32 v233, 0xffff0000, v233
	v_pk_add_f32 v[218:219], v[218:219], v[216:217]
	v_pk_add_f32 v[220:221], v[220:221], v[232:233]
	ds_read_b128 v[230:233], v246 offset:3760
	s_waitcnt lgkmcnt(7)
	v_lshlrev_b32_e32 v216, 16, v234
	v_and_b32_e32 v217, 0xffff0000, v234
	v_lshlrev_b32_e32 v234, 16, v235
	v_and_b32_e32 v235, 0xffff0000, v235
	v_pk_add_f32 v[106:107], v[106:107], v[216:217]
	v_pk_add_f32 v[108:109], v[108:109], v[234:235]
	v_lshlrev_b32_e32 v216, 16, v236
	v_and_b32_e32 v217, 0xffff0000, v236
	v_lshlrev_b32_e32 v236, 16, v237
	v_and_b32_e32 v237, 0xffff0000, v237
	v_pk_add_f32 v[218:219], v[218:219], v[216:217]
	v_pk_add_f32 v[220:221], v[220:221], v[236:237]
	ds_read_b128 v[234:237], v246 offset:3488
	s_waitcnt lgkmcnt(7)
	v_lshlrev_b32_e32 v216, 16, v238
	v_and_b32_e32 v217, 0xffff0000, v238
	v_lshlrev_b32_e32 v238, 16, v239
	v_and_b32_e32 v239, 0xffff0000, v239
	v_pk_add_f32 v[106:107], v[106:107], v[216:217]
	v_pk_add_f32 v[108:109], v[108:109], v[238:239]
	v_lshlrev_b32_e32 v216, 16, v240
	v_and_b32_e32 v217, 0xffff0000, v240
	v_lshlrev_b32_e32 v240, 16, v241
	v_and_b32_e32 v241, 0xffff0000, v241
	v_pk_add_f32 v[218:219], v[218:219], v[216:217]
	v_pk_add_f32 v[220:221], v[220:221], v[240:241]
	ds_read_b128 v[238:241], v246 offset:3216
	s_waitcnt lgkmcnt(7)
	v_lshlrev_b32_e32 v216, 16, v242
	v_and_b32_e32 v217, 0xffff0000, v242
	v_lshlrev_b32_e32 v242, 16, v243
	v_and_b32_e32 v243, 0xffff0000, v243
	v_pk_add_f32 v[106:107], v[106:107], v[216:217]
	v_pk_add_f32 v[108:109], v[108:109], v[242:243]
	v_lshlrev_b32_e32 v216, 16, v244
	v_and_b32_e32 v217, 0xffff0000, v244
	v_lshlrev_b32_e32 v244, 16, v245
	v_and_b32_e32 v245, 0xffff0000, v245
	v_pk_add_f32 v[218:219], v[218:219], v[216:217]
	v_pk_add_f32 v[220:221], v[220:221], v[244:245]
	ds_read_b128 v[242:245], v246 offset:2944
	s_waitcnt lgkmcnt(7)
	v_lshlrev_b32_e32 v216, 16, v248
	v_and_b32_e32 v217, 0xffff0000, v248
	v_lshlrev_b32_e32 v248, 16, v249
	v_and_b32_e32 v249, 0xffff0000, v249
	v_pk_add_f32 v[106:107], v[106:107], v[216:217]
	v_pk_add_f32 v[108:109], v[108:109], v[248:249]
	v_lshlrev_b32_e32 v216, 16, v250
	v_and_b32_e32 v217, 0xffff0000, v250
	v_lshlrev_b32_e32 v250, 16, v251
	v_and_b32_e32 v251, 0xffff0000, v251
	v_pk_add_f32 v[218:219], v[218:219], v[216:217]
	v_pk_add_f32 v[220:221], v[220:221], v[250:251]
	ds_read_b128 v[248:251], v246 offset:2672
	s_waitcnt lgkmcnt(7)
	v_lshlrev_b32_e32 v216, 16, v252
	v_and_b32_e32 v217, 0xffff0000, v252
	v_lshlrev_b32_e32 v252, 16, v253
	v_and_b32_e32 v253, 0xffff0000, v253
	v_pk_add_f32 v[106:107], v[106:107], v[216:217]
	v_pk_add_f32 v[108:109], v[108:109], v[252:253]
	v_lshlrev_b32_e32 v216, 16, v254
	v_and_b32_e32 v217, 0xffff0000, v254
	v_lshlrev_b32_e32 v254, 16, v255
	v_and_b32_e32 v255, 0xffff0000, v255
	v_pk_add_f32 v[218:219], v[218:219], v[216:217]
	v_pk_add_f32 v[220:221], v[220:221], v[254:255]
	ds_read_b128 v[252:255], v246 offset:2400
	v_pk_fma_f32 v[106:107], v[158:159], v[106:107], v[98:99] op_sel:[1,0,0] neg_lo:[0,0,1] neg_hi:[0,0,1]
	v_pk_fma_f32 v[108:109], v[158:159], v[108:109], v[100:101] op_sel:[1,0,0] neg_lo:[0,0,1] neg_hi:[0,0,1]
	v_pk_fma_f32 v[218:219], v[158:159], v[218:219], v[102:103] op_sel:[1,0,0] neg_lo:[0,0,1] neg_hi:[0,0,1]
	v_pk_fma_f32 v[220:221], v[158:159], v[220:221], v[104:105] op_sel:[1,0,0] neg_lo:[0,0,1] neg_hi:[0,0,1]
	v_cvt_pk_bf16_f32 v106, v106, v107
	v_cvt_pk_bf16_f32 v107, v108, v109
	v_cvt_pk_bf16_f32 v108, v218, v219
	v_cvt_pk_bf16_f32 v109, v220, v221
	s_and_saveexec_b64 s[28:29], s[6:7]
	s_cbranch_execz .Lpu0_6
	global_store_dwordx4 v[192:193], v[98:101], off offset:384
	global_store_dwordx4 v[192:193], v[102:105], off offset:400
.Lpu0_6:
	s_or_b64 exec, exec, s[28:29]
	s_waitcnt vmcnt(4)
	v_mfma_f32_32x32x16_bf16 v[2:17], v[106:109], v[70:73], v[2:17]
	v_mfma_f32_32x32x16_bf16 v[18:33], v[106:109], v[74:77], v[18:33]
	v_mfma_f32_32x32x16_bf16 v[34:49], v[106:109], v[78:81], v[34:49]
	v_mfma_f32_32x32x16_bf16 v[50:65], v[106:109], v[66:69], v[50:65]
	s_waitcnt lgkmcnt(7)
	v_lshlrev_b32_e32 v98, 16, v222
	v_and_b32_e32 v99, 0xffff0000, v222
	v_lshlrev_b32_e32 v100, 16, v223
	v_and_b32_e32 v101, 0xffff0000, v223
	v_lshlrev_b32_e32 v102, 16, v224
	v_and_b32_e32 v103, 0xffff0000, v224
	v_lshlrev_b32_e32 v104, 16, v225
	v_and_b32_e32 v105, 0xffff0000, v225
	ds_read_b128 v[222:225], v246 offset:2128
	s_waitcnt lgkmcnt(7)
	v_lshlrev_b32_e32 v216, 16, v226
	v_and_b32_e32 v217, 0xffff0000, v226
	v_lshlrev_b32_e32 v226, 16, v227
	v_and_b32_e32 v227, 0xffff0000, v227
	v_pk_add_f32 v[106:107], v[98:99], v[216:217]
	v_pk_add_f32 v[108:109], v[100:101], v[226:227]
	v_lshlrev_b32_e32 v216, 16, v228
	v_and_b32_e32 v217, 0xffff0000, v228
	v_lshlrev_b32_e32 v228, 16, v229
	v_and_b32_e32 v229, 0xffff0000, v229
	v_pk_add_f32 v[218:219], v[102:103], v[216:217]
	v_pk_add_f32 v[220:221], v[104:105], v[228:229]
	ds_read_b128 v[226:229], v246 offset:1856
	s_waitcnt lgkmcnt(7)
	v_lshlrev_b32_e32 v216, 16, v230
	v_and_b32_e32 v217, 0xffff0000, v230
	v_lshlrev_b32_e32 v230, 16, v231
	v_and_b32_e32 v231, 0xffff0000, v231
	v_pk_add_f32 v[106:107], v[106:107], v[216:217]
	v_pk_add_f32 v[108:109], v[108:109], v[230:231]
	v_lshlrev_b32_e32 v216, 16, v232
	v_and_b32_e32 v217, 0xffff0000, v232
	v_lshlrev_b32_e32 v232, 16, v233
	v_and_b32_e32 v233, 0xffff0000, v233
	v_pk_add_f32 v[218:219], v[218:219], v[216:217]
	v_pk_add_f32 v[220:221], v[220:221], v[232:233]
	ds_read_b128 v[230:233], v246 offset:1584
	s_waitcnt lgkmcnt(7)
	v_lshlrev_b32_e32 v216, 16, v234
	v_and_b32_e32 v217, 0xffff0000, v234
	v_lshlrev_b32_e32 v234, 16, v235
	v_and_b32_e32 v235, 0xffff0000, v235
	v_pk_add_f32 v[106:107], v[106:107], v[216:217]
	v_pk_add_f32 v[108:109], v[108:109], v[234:235]
	v_lshlrev_b32_e32 v216, 16, v236
	v_and_b32_e32 v217, 0xffff0000, v236
	v_lshlrev_b32_e32 v236, 16, v237
	v_and_b32_e32 v237, 0xffff0000, v237
	v_pk_add_f32 v[218:219], v[218:219], v[216:217]
	v_pk_add_f32 v[220:221], v[220:221], v[236:237]
	ds_read_b128 v[234:237], v246 offset:1312
	s_waitcnt lgkmcnt(7)
	v_lshlrev_b32_e32 v216, 16, v238
	v_and_b32_e32 v217, 0xffff0000, v238
	v_lshlrev_b32_e32 v238, 16, v239
	v_and_b32_e32 v239, 0xffff0000, v239
	v_pk_add_f32 v[106:107], v[106:107], v[216:217]
	v_pk_add_f32 v[108:109], v[108:109], v[238:239]
	v_lshlrev_b32_e32 v216, 16, v240
	v_and_b32_e32 v217, 0xffff0000, v240
	v_lshlrev_b32_e32 v240, 16, v241
	v_and_b32_e32 v241, 0xffff0000, v241
	v_pk_add_f32 v[218:219], v[218:219], v[216:217]
	v_pk_add_f32 v[220:221], v[220:221], v[240:241]
	ds_read_b128 v[238:241], v246 offset:1040
	s_waitcnt lgkmcnt(7)
	v_lshlrev_b32_e32 v216, 16, v242
	v_and_b32_e32 v217, 0xffff0000, v242
	v_lshlrev_b32_e32 v242, 16, v243
	v_and_b32_e32 v243, 0xffff0000, v243
	v_pk_add_f32 v[106:107], v[106:107], v[216:217]
	v_pk_add_f32 v[108:109], v[108:109], v[242:243]
	v_lshlrev_b32_e32 v216, 16, v244
	v_and_b32_e32 v217, 0xffff0000, v244
	v_lshlrev_b32_e32 v244, 16, v245
	v_and_b32_e32 v245, 0xffff0000, v245
	v_pk_add_f32 v[218:219], v[218:219], v[216:217]
	v_pk_add_f32 v[220:221], v[220:221], v[244:245]
	ds_read_b128 v[242:245], v246 offset:768
	s_waitcnt lgkmcnt(7)
	v_lshlrev_b32_e32 v216, 16, v248
	v_and_b32_e32 v217, 0xffff0000, v248
	v_lshlrev_b32_e32 v248, 16, v249
	v_and_b32_e32 v249, 0xffff0000, v249
	v_pk_add_f32 v[106:107], v[106:107], v[216:217]
	v_pk_add_f32 v[108:109], v[108:109], v[248:249]
	v_lshlrev_b32_e32 v216, 16, v250
	v_and_b32_e32 v217, 0xffff0000, v250
	v_lshlrev_b32_e32 v250, 16, v251
	v_and_b32_e32 v251, 0xffff0000, v251
	v_pk_add_f32 v[218:219], v[218:219], v[216:217]
	v_pk_add_f32 v[220:221], v[220:221], v[250:251]
	ds_read_b128 v[248:251], v246 offset:496
	s_waitcnt lgkmcnt(7)
	v_lshlrev_b32_e32 v216, 16, v252
	v_and_b32_e32 v217, 0xffff0000, v252
	v_lshlrev_b32_e32 v252, 16, v253
	v_and_b32_e32 v253, 0xffff0000, v253
	v_pk_add_f32 v[106:107], v[106:107], v[216:217]
	v_pk_add_f32 v[108:109], v[108:109], v[252:253]
	v_lshlrev_b32_e32 v216, 16, v254
	v_and_b32_e32 v217, 0xffff0000, v254
	v_lshlrev_b32_e32 v254, 16, v255
	v_and_b32_e32 v255, 0xffff0000, v255
	v_pk_add_f32 v[218:219], v[218:219], v[216:217]
	v_pk_add_f32 v[220:221], v[220:221], v[254:255]
	ds_read_b128 v[252:255], v246 offset:224
	s_waitcnt lgkmcnt(7)
	v_lshlrev_b32_e32 v216, 16, v222
	v_and_b32_e32 v217, 0xffff0000, v222
	v_lshlrev_b32_e32 v222, 16, v223
	v_and_b32_e32 v223, 0xffff0000, v223
	v_pk_add_f32 v[106:107], v[106:107], v[216:217]
	v_pk_add_f32 v[108:109], v[108:109], v[222:223]
	v_lshlrev_b32_e32 v216, 16, v224
	v_and_b32_e32 v217, 0xffff0000, v224
	v_lshlrev_b32_e32 v224, 16, v225
	v_and_b32_e32 v225, 0xffff0000, v225
	v_pk_add_f32 v[218:219], v[218:219], v[216:217]
	v_pk_add_f32 v[220:221], v[220:221], v[224:225]
	s_waitcnt lgkmcnt(6)
	v_lshlrev_b32_e32 v216, 16, v226
	v_and_b32_e32 v217, 0xffff0000, v226
	v_lshlrev_b32_e32 v226, 16, v227
	v_and_b32_e32 v227, 0xffff0000, v227
	v_pk_add_f32 v[106:107], v[106:107], v[216:217]
	v_pk_add_f32 v[108:109], v[108:109], v[226:227]
	v_lshlrev_b32_e32 v216, 16, v228
	v_and_b32_e32 v217, 0xffff0000, v228
	v_lshlrev_b32_e32 v228, 16, v229
	v_and_b32_e32 v229, 0xffff0000, v229
	v_pk_add_f32 v[218:219], v[218:219], v[216:217]
	v_pk_add_f32 v[220:221], v[220:221], v[228:229]
	s_waitcnt lgkmcnt(5)
	v_lshlrev_b32_e32 v216, 16, v230
	v_and_b32_e32 v217, 0xffff0000, v230
	v_lshlrev_b32_e32 v230, 16, v231
	v_and_b32_e32 v231, 0xffff0000, v231
	v_pk_add_f32 v[106:107], v[106:107], v[216:217]
	v_pk_add_f32 v[108:109], v[108:109], v[230:231]
	v_lshlrev_b32_e32 v216, 16, v232
	v_and_b32_e32 v217, 0xffff0000, v232
	v_lshlrev_b32_e32 v232, 16, v233
	v_and_b32_e32 v233, 0xffff0000, v233
	v_pk_add_f32 v[218:219], v[218:219], v[216:217]
	v_pk_add_f32 v[220:221], v[220:221], v[232:233]
	s_waitcnt lgkmcnt(4)
	v_lshlrev_b32_e32 v216, 16, v234
	v_and_b32_e32 v217, 0xffff0000, v234
	v_lshlrev_b32_e32 v234, 16, v235
	v_and_b32_e32 v235, 0xffff0000, v235
	v_pk_add_f32 v[106:107], v[106:107], v[216:217]
	v_pk_add_f32 v[108:109], v[108:109], v[234:235]
	v_lshlrev_b32_e32 v216, 16, v236
	v_and_b32_e32 v217, 0xffff0000, v236
	v_lshlrev_b32_e32 v236, 16, v237
	v_and_b32_e32 v237, 0xffff0000, v237
	v_pk_add_f32 v[218:219], v[218:219], v[216:217]
	v_pk_add_f32 v[220:221], v[220:221], v[236:237]
	s_waitcnt lgkmcnt(3)
	v_lshlrev_b32_e32 v216, 16, v238
	v_and_b32_e32 v217, 0xffff0000, v238
	v_lshlrev_b32_e32 v238, 16, v239
	v_and_b32_e32 v239, 0xffff0000, v239
	v_pk_add_f32 v[106:107], v[106:107], v[216:217]
	v_pk_add_f32 v[108:109], v[108:109], v[238:239]
	v_lshlrev_b32_e32 v216, 16, v240
	v_and_b32_e32 v217, 0xffff0000, v240
	v_lshlrev_b32_e32 v240, 16, v241
	v_and_b32_e32 v241, 0xffff0000, v241
	v_pk_add_f32 v[218:219], v[218:219], v[216:217]
	v_pk_add_f32 v[220:221], v[220:221], v[240:241]
	s_waitcnt lgkmcnt(2)
	v_lshlrev_b32_e32 v216, 16, v242
	v_and_b32_e32 v217, 0xffff0000, v242
	v_lshlrev_b32_e32 v242, 16, v243
	v_and_b32_e32 v243, 0xffff0000, v243
	v_pk_add_f32 v[106:107], v[106:107], v[216:217]
	v_pk_add_f32 v[108:109], v[108:109], v[242:243]
	v_lshlrev_b32_e32 v216, 16, v244
	v_and_b32_e32 v217, 0xffff0000, v244
	v_lshlrev_b32_e32 v244, 16, v245
	v_and_b32_e32 v245, 0xffff0000, v245
	v_pk_add_f32 v[218:219], v[218:219], v[216:217]
	v_pk_add_f32 v[220:221], v[220:221], v[244:245]
	s_waitcnt lgkmcnt(1)
	v_lshlrev_b32_e32 v216, 16, v248
	v_and_b32_e32 v217, 0xffff0000, v248
	v_lshlrev_b32_e32 v248, 16, v249
	v_and_b32_e32 v249, 0xffff0000, v249
	v_pk_add_f32 v[106:107], v[106:107], v[216:217]
	v_pk_add_f32 v[108:109], v[108:109], v[248:249]
	v_lshlrev_b32_e32 v216, 16, v250
	v_and_b32_e32 v217, 0xffff0000, v250
	v_lshlrev_b32_e32 v250, 16, v251
	v_and_b32_e32 v251, 0xffff0000, v251
	v_pk_add_f32 v[218:219], v[218:219], v[216:217]
	v_pk_add_f32 v[220:221], v[220:221], v[250:251]
	s_waitcnt lgkmcnt(0)
	v_lshlrev_b32_e32 v216, 16, v252
	v_and_b32_e32 v217, 0xffff0000, v252
	v_lshlrev_b32_e32 v252, 16, v253
	v_and_b32_e32 v253, 0xffff0000, v253
	v_pk_add_f32 v[106:107], v[106:107], v[216:217]
	v_pk_add_f32 v[108:109], v[108:109], v[252:253]
	v_lshlrev_b32_e32 v216, 16, v254
	v_and_b32_e32 v217, 0xffff0000, v254
	v_lshlrev_b32_e32 v254, 16, v255
	v_and_b32_e32 v255, 0xffff0000, v255
	v_pk_add_f32 v[218:219], v[218:219], v[216:217]
	v_pk_add_f32 v[220:221], v[220:221], v[254:255]
	v_pk_fma_f32 v[106:107], v[158:159], v[106:107], v[98:99] op_sel:[1,0,0] neg_lo:[0,0,1] neg_hi:[0,0,1]
	v_pk_fma_f32 v[108:109], v[158:159], v[108:109], v[100:101] op_sel:[1,0,0] neg_lo:[0,0,1] neg_hi:[0,0,1]
	v_pk_fma_f32 v[218:219], v[158:159], v[218:219], v[102:103] op_sel:[1,0,0] neg_lo:[0,0,1] neg_hi:[0,0,1]
	v_pk_fma_f32 v[220:221], v[158:159], v[220:221], v[104:105] op_sel:[1,0,0] neg_lo:[0,0,1] neg_hi:[0,0,1]
	v_cvt_pk_bf16_f32 v106, v106, v107
	v_cvt_pk_bf16_f32 v107, v108, v109
	v_cvt_pk_bf16_f32 v108, v218, v219
	v_cvt_pk_bf16_f32 v109, v220, v221
	s_and_saveexec_b64 s[28:29], s[6:7]
	s_cbranch_execz .Lpu0_7
	global_store_dwordx4 v[192:193], v[98:101], off offset:448
	global_store_dwordx4 v[192:193], v[102:105], off offset:464

.LBB0_355:
	s_or_b64 exec, exec, s[6:7]
	s_waitcnt lgkmcnt(0)
	global_load_dwordx4 v[82:85], v[112:113], off offset:512
	global_load_dwordx4 v[86:89], v[114:115], off offset:512
	global_load_dwordx4 v[90:93], v[116:117], off offset:512
	global_load_dwordx4 v[94:97], v[118:119], off offset:512
	global_load_dwordx4 v[222:225], v[112:113], off offset:1024
	global_load_dwordx4 v[226:229], v[114:115], off offset:1024
	global_load_dwordx4 v[230:233], v[116:117], off offset:1024
	global_load_dwordx4 v[234:237], v[118:119], off offset:1024
	v_lshl_add_u32 v246, v197, 1, v214
	ds_read_b128 v[238:241], v246 offset:4080
	ds_read_b128 v[242:245], v246 offset:3808
	ds_read_b128 v[248:251], v246 offset:3536
	ds_read_b128 v[252:255], v246 offset:3264
	v_or_b32_e32 v2, s28, v1
	v_min_u32_e32 v3, 7, v2
	v_add_u32_e32 v3, 1, v3
	v_cvt_f32_ubyte0_e32 v3, v3
	v_div_scale_f32 v4, s[6:7], v3, v3, 1.0
	v_rcp_f32_e32 v5, v4
	s_ashr_i32 s8, s30, 6
	s_mul_i32 s10, s8, 15
	v_cmp_lt_u32_e64 s[6:7], s41, v2
	v_fma_f32 v6, -v4, v5, 1.0
	v_fmac_f32_e32 v5, v6, v5
	v_div_scale_f32 v6, vcc, 1.0, v3, 1.0
	v_mul_f32_e32 v7, v6, v5
	v_fma_f32 v8, -v4, v7, v6
	v_fmac_f32_e32 v7, v8, v5
	v_fma_f32 v4, -v4, v7, v6
	v_div_fmas_f32 v4, v4, v5, v7
	v_div_fixup_f32 v159, v4, v3, 1.0
	s_ashr_i32 s11, s10, 31
	v_add_u32_e32 v2, 0xfffff80f, v2
	v_mov_b32_e32 v3, v155
	v_lshl_add_u64 v[2:3], v[2:3], 0, s[10:11]
	v_lshlrev_b64 v[2:3], 11, v[2:3]
	v_lshl_add_u64 v[2:3], s[70:71], 0, v[2:3]
	v_mov_b32_e32 v163, v155
	v_lshl_add_u64 v[2:3], v[2:3], 0, v[162:163]
	v_lshl_add_u64 v[192:193], v[2:3], 0, s[20:21]
	v_mov_b64_e32 v[2:3], 0
	v_mov_b64_e32 v[4:5], 0
	v_mov_b64_e32 v[6:7], 0
	v_mov_b64_e32 v[8:9], 0
	v_mov_b64_e32 v[10:11], 0
	v_mov_b64_e32 v[12:13], 0
	v_mov_b64_e32 v[14:15], 0
	v_mov_b64_e32 v[16:17], 0
	v_mov_b64_e32 v[18:19], 0
	v_mov_b64_e32 v[20:21], 0
	v_mov_b64_e32 v[22:23], 0
	v_mov_b64_e32 v[24:25], 0
	v_mov_b64_e32 v[26:27], 0
	v_mov_b64_e32 v[28:29], 0
	v_mov_b64_e32 v[30:31], 0
	v_mov_b64_e32 v[32:33], 0
	v_mov_b64_e32 v[34:35], 0
	v_mov_b64_e32 v[36:37], 0
	v_mov_b64_e32 v[38:39], 0
	v_mov_b64_e32 v[40:41], 0
	v_mov_b64_e32 v[42:43], 0
	v_mov_b64_e32 v[44:45], 0
	v_mov_b64_e32 v[46:47], 0
	v_mov_b64_e32 v[48:49], 0
	v_mov_b64_e32 v[50:51], 0
	v_mov_b64_e32 v[52:53], 0
	v_mov_b64_e32 v[54:55], 0
	v_mov_b64_e32 v[56:57], 0
	v_mov_b64_e32 v[58:59], 0
	v_mov_b64_e32 v[60:61], 0
	v_mov_b64_e32 v[62:63], 0
	v_mov_b64_e32 v[64:65], 0
	s_mov_b32 s49, 0
	s_mov_b64 s[10:11], 0
	s_waitcnt lgkmcnt(3)
	v_lshlrev_b32_e32 v98, 16, v238
	v_and_b32_e32 v99, 0xffff0000, v238
	v_lshlrev_b32_e32 v100, 16, v239
	v_and_b32_e32 v101, 0xffff0000, v239
	v_lshlrev_b32_e32 v102, 16, v240
	v_and_b32_e32 v103, 0xffff0000, v240
	v_lshlrev_b32_e32 v104, 16, v241
	v_and_b32_e32 v105, 0xffff0000, v241
	ds_read_b128 v[238:241], v246 offset:2992
	s_waitcnt lgkmcnt(3)
	v_lshlrev_b32_e32 v216, 16, v242
	v_and_b32_e32 v217, 0xffff0000, v242
	v_lshlrev_b32_e32 v242, 16, v243
	v_and_b32_e32 v243, 0xffff0000, v243
	v_pk_add_f32 v[106:107], v[98:99], v[216:217]
	v_pk_add_f32 v[108:109], v[100:101], v[242:243]
	v_lshlrev_b32_e32 v216, 16, v244
	v_and_b32_e32 v217, 0xffff0000, v244
	v_lshlrev_b32_e32 v244, 16, v245
	v_and_b32_e32 v245, 0xffff0000, v245
	v_pk_add_f32 v[218:219], v[102:103], v[216:217]
	v_pk_add_f32 v[220:221], v[104:105], v[244:245]
	ds_read_b128 v[242:245], v246 offset:2720
	s_waitcnt lgkmcnt(3)
	v_lshlrev_b32_e32 v216, 16, v248
	v_and_b32_e32 v217, 0xffff0000, v248
	v_lshlrev_b32_e32 v248, 16, v249
	v_and_b32_e32 v249, 0xffff0000, v249
	v_pk_add_f32 v[106:107], v[106:107], v[216:217]
	v_pk_add_f32 v[108:109], v[108:109], v[248:249]
	v_lshlrev_b32_e32 v216, 16, v250
	v_and_b32_e32 v217, 0xffff0000, v250
	v_lshlrev_b32_e32 v250, 16, v251
	v_and_b32_e32 v251, 0xffff0000, v251
	v_pk_add_f32 v[218:219], v[218:219], v[216:217]
	v_pk_add_f32 v[220:221], v[220:221], v[250:251]
	ds_read_b128 v[248:251], v246 offset:2448
	s_waitcnt lgkmcnt(3)
	v_lshlrev_b32_e32 v216, 16, v252
	v_and_b32_e32 v217, 0xffff0000, v252
	v_lshlrev_b32_e32 v252, 16, v253
	v_and_b32_e32 v253, 0xffff0000, v253
	v_pk_add_f32 v[106:107], v[106:107], v[216:217]
	v_pk_add_f32 v[108:109], v[108:109], v[252:253]
	v_lshlrev_b32_e32 v216, 16, v254
	v_and_b32_e32 v217, 0xffff0000, v254
	v_lshlrev_b32_e32 v254, 16, v255
	v_and_b32_e32 v255, 0xffff0000, v255
	v_pk_add_f32 v[218:219], v[218:219], v[216:217]
	v_pk_add_f32 v[220:221], v[220:221], v[254:255]
	ds_read_b128 v[252:255], v246 offset:2176
	s_waitcnt lgkmcnt(3)
	v_lshlrev_b32_e32 v216, 16, v238
	v_and_b32_e32 v217, 0xffff0000, v238
	v_lshlrev_b32_e32 v238, 16, v239
	v_and_b32_e32 v239, 0xffff0000, v239
	v_pk_add_f32 v[106:107], v[106:107], v[216:217]
	v_pk_add_f32 v[108:109], v[108:109], v[238:239]
	v_lshlrev_b32_e32 v216, 16, v240
	v_and_b32_e32 v217, 0xffff0000, v240
	v_lshlrev_b32_e32 v240, 16, v241
	v_and_b32_e32 v241, 0xffff0000, v241
	v_pk_add_f32 v[218:219], v[218:219], v[216:217]
	v_pk_add_f32 v[220:221], v[220:221], v[240:241]
	ds_read_b128 v[238:241], v246 offset:4112
	s_waitcnt lgkmcnt(3)
	v_lshlrev_b32_e32 v216, 16, v242
	v_and_b32_e32 v217, 0xffff0000, v242
	v_lshlrev_b32_e32 v242, 16, v243
	v_and_b32_e32 v243, 0xffff0000, v243
	v_pk_add_f32 v[106:107], v[106:107], v[216:217]
	v_pk_add_f32 v[108:109], v[108:109], v[242:243]
	v_lshlrev_b32_e32 v216, 16, v244
	v_and_b32_e32 v217, 0xffff0000, v244
	v_lshlrev_b32_e32 v244, 16, v245
	v_and_b32_e32 v245, 0xffff0000, v245
	v_pk_add_f32 v[218:219], v[218:219], v[216:217]
	v_pk_add_f32 v[220:221], v[220:221], v[244:245]
	ds_read_b128 v[242:245], v246 offset:3840
	s_waitcnt lgkmcnt(3)
	v_lshlrev_b32_e32 v216, 16, v248
	v_and_b32_e32 v217, 0xffff0000, v248
	v_lshlrev_b32_e32 v248, 16, v249
	v_and_b32_e32 v249, 0xffff0000, v249
	v_pk_add_f32 v[106:107], v[106:107], v[216:217]
	v_pk_add_f32 v[108:109], v[108:109], v[248:249]
	v_lshlrev_b32_e32 v216, 16, v250
	v_and_b32_e32 v217, 0xffff0000, v250
	v_lshlrev_b32_e32 v250, 16, v251
	v_and_b32_e32 v251, 0xffff0000, v251
	v_pk_add_f32 v[218:219], v[218:219], v[216:217]
	v_pk_add_f32 v[220:221], v[220:221], v[250:251]
	ds_read_b128 v[248:251], v246 offset:3568
	s_waitcnt lgkmcnt(3)
	v_lshlrev_b32_e32 v216, 16, v252
	v_and_b32_e32 v217, 0xffff0000, v252
	v_lshlrev_b32_e32 v252, 16, v253
	v_and_b32_e32 v253, 0xffff0000, v253
	v_pk_add_f32 v[106:107], v[106:107], v[216:217]
	v_pk_add_f32 v[108:109], v[108:109], v[252:253]
	v_lshlrev_b32_e32 v216, 16, v254
	v_and_b32_e32 v217, 0xffff0000, v254
	v_lshlrev_b32_e32 v254, 16, v255
	v_and_b32_e32 v255, 0xffff0000, v255
	v_pk_add_f32 v[218:219], v[218:219], v[216:217]
	v_pk_add_f32 v[220:221], v[220:221], v[254:255]
	ds_read_b128 v[252:255], v246 offset:3296
	v_pk_fma_f32 v[106:107], v[158:159], v[106:107], v[98:99] op_sel:[1,0,0] neg_lo:[0,0,1] neg_hi:[0,0,1]
	v_pk_fma_f32 v[108:109], v[158:159], v[108:109], v[100:101] op_sel:[1,0,0] neg_lo:[0,0,1] neg_hi:[0,0,1]
	v_pk_fma_f32 v[218:219], v[158:159], v[218:219], v[102:103] op_sel:[1,0,0] neg_lo:[0,0,1] neg_hi:[0,0,1]
	v_pk_fma_f32 v[220:221], v[158:159], v[220:221], v[104:105] op_sel:[1,0,0] neg_lo:[0,0,1] neg_hi:[0,0,1]
	v_cvt_pk_bf16_f32 v106, v106, v107
	v_cvt_pk_bf16_f32 v107, v108, v109
	v_cvt_pk_bf16_f32 v108, v218, v219
	v_cvt_pk_bf16_f32 v109, v220, v221
	s_and_saveexec_b64 s[28:29], s[6:7]
	s_cbranch_execz .Lpu1_0
	global_store_dwordx4 v[192:193], v[98:101], off offset:0
	global_store_dwordx4 v[192:193], v[102:105], off offset:16
.Lpu1_0:
	s_or_b64 exec, exec, s[28:29]
	s_waitcnt vmcnt(8)
	v_mfma_f32_32x32x16_bf16 v[2:17], v[106:109], v[70:73], v[2:17]
	v_mfma_f32_32x32x16_bf16 v[18:33], v[106:109], v[74:77], v[18:33]
	v_mfma_f32_32x32x16_bf16 v[34:49], v[106:109], v[78:81], v[34:49]
	v_mfma_f32_32x32x16_bf16 v[50:65], v[106:109], v[66:69], v[50:65]
	global_load_dwordx4 v[70:73], v[112:113], off offset:1536
	global_load_dwordx4 v[74:77], v[114:115], off offset:1536
	global_load_dwordx4 v[78:81], v[116:117], off offset:1536
	global_load_dwordx4 v[66:69], v[118:119], off offset:1536
	s_waitcnt lgkmcnt(3)
	v_lshlrev_b32_e32 v98, 16, v238
	v_and_b32_e32 v99, 0xffff0000, v238
	v_lshlrev_b32_e32 v100, 16, v239
	v_and_b32_e32 v101, 0xffff0000, v239
	v_lshlrev_b32_e32 v102, 16, v240
	v_and_b32_e32 v103, 0xffff0000, v240
	v_lshlrev_b32_e32 v104, 16, v241
	v_and_b32_e32 v105, 0xffff0000, v241
	ds_read_b128 v[238:241], v246 offset:3024
	s_waitcnt lgkmcnt(3)
	v_lshlrev_b32_e32 v216, 16, v242
	v_and_b32_e32 v217, 0xffff0000, v242
	v_lshlrev_b32_e32 v242, 16, v243
	v_and_b32_e32 v243, 0xffff0000, v243
	v_pk_add_f32 v[106:107], v[98:99], v[216:217]
	v_pk_add_f32 v[108:109], v[100:101], v[242:243]
	v_lshlrev_b32_e32 v216, 16, v244
	v_and_b32_e32 v217, 0xffff0000, v244
	v_lshlrev_b32_e32 v244, 16, v245
	v_and_b32_e32 v245, 0xffff0000, v245
	v_pk_add_f32 v[218:219], v[102:103], v[216:217]
	v_pk_add_f32 v[220:221], v[104:105], v[244:245]
	ds_read_b128 v[242:245], v246 offset:2752
	s_waitcnt lgkmcnt(3)
	v_lshlrev_b32_e32 v216, 16, v248
	v_and_b32_e32 v217, 0xffff0000, v248
	v_lshlrev_b32_e32 v248, 16, v249
	v_and_b32_e32 v249, 0xffff0000, v249
	v_pk_add_f32 v[106:107], v[106:107], v[216:217]
	v_pk_add_f32 v[108:109], v[108:109], v[248:249]
	v_lshlrev_b32_e32 v216, 16, v250
	v_and_b32_e32 v217, 0xffff0000, v250
	v_lshlrev_b32_e32 v250, 16, v251
	v_and_b32_e32 v251, 0xffff0000, v251
	v_pk_add_f32 v[218:219], v[218:219], v[216:217]
	v_pk_add_f32 v[220:221], v[220:221], v[250:251]
	ds_read_b128 v[248:251], v246 offset:2480
	s_waitcnt lgkmcnt(3)
	v_lshlrev_b32_e32 v216, 16, v252
	v_and_b32_e32 v217, 0xffff0000, v252
	v_lshlrev_b32_e32 v252, 16, v253
	v_and_b32_e32 v253, 0xffff0000, v253
	v_pk_add_f32 v[106:107], v[106:107], v[216:217]
	v_pk_add_f32 v[108:109], v[108:109], v[252:253]
	v_lshlrev_b32_e32 v216, 16, v254
	v_and_b32_e32 v217, 0xffff0000, v254
	v_lshlrev_b32_e32 v254, 16, v255
	v_and_b32_e32 v255, 0xffff0000, v255
	v_pk_add_f32 v[218:219], v[218:219], v[216:217]
	v_pk_add_f32 v[220:221], v[220:221], v[254:255]
	ds_read_b128 v[252:255], v246 offset:2208
	s_waitcnt lgkmcnt(3)
	v_lshlrev_b32_e32 v216, 16, v238
	v_and_b32_e32 v217, 0xffff0000, v238
	v_lshlrev_b32_e32 v238, 16, v239
	v_and_b32_e32 v239, 0xffff0000, v239
	v_pk_add_f32 v[106:107], v[106:107], v[216:217]
	v_pk_add_f32 v[108:109], v[108:109], v[238:239]
	v_lshlrev_b32_e32 v216, 16, v240
	v_and_b32_e32 v217, 0xffff0000, v240
	v_lshlrev_b32_e32 v240, 16, v241
	v_and_b32_e32 v241, 0xffff0000, v241
	v_pk_add_f32 v[218:219], v[218:219], v[216:217]
	v_pk_add_f32 v[220:221], v[220:221], v[240:241]
	ds_read_b128 v[238:241], v246 offset:4144
	s_waitcnt lgkmcnt(3)
	v_lshlrev_b32_e32 v216, 16, v242
	v_and_b32_e32 v217, 0xffff0000, v242
	v_lshlrev_b32_e32 v242, 16, v243
	v_and_b32_e32 v243, 0xffff0000, v243
	v_pk_add_f32 v[106:107], v[106:107], v[216:217]
	v_pk_add_f32 v[108:109], v[108:109], v[242:243]
	v_lshlrev_b32_e32 v216, 16, v244
	v_and_b32_e32 v217, 0xffff0000, v244
	v_lshlrev_b32_e32 v244, 16, v245
	v_and_b32_e32 v245, 0xffff0000, v245
	v_pk_add_f32 v[218:219], v[218:219], v[216:217]
	v_pk_add_f32 v[220:221], v[220:221], v[244:245]
	ds_read_b128 v[242:245], v246 offset:3872
	s_waitcnt lgkmcnt(3)
	v_lshlrev_b32_e32 v216, 16, v248
	v_and_b32_e32 v217, 0xffff0000, v248
	v_lshlrev_b32_e32 v248, 16, v249
	v_and_b32_e32 v249, 0xffff0000, v249
	v_pk_add_f32 v[106:107], v[106:107], v[216:217]
	v_pk_add_f32 v[108:109], v[108:109], v[248:249]
	v_lshlrev_b32_e32 v216, 16, v250
	v_and_b32_e32 v217, 0xffff0000, v250
	v_lshlrev_b32_e32 v250, 16, v251
	v_and_b32_e32 v251, 0xffff0000, v251
	v_pk_add_f32 v[218:219], v[218:219], v[216:217]
	v_pk_add_f32 v[220:221], v[220:221], v[250:251]
	ds_read_b128 v[248:251], v246 offset:3600
	s_waitcnt lgkmcnt(3)
	v_lshlrev_b32_e32 v216, 16, v252
	v_and_b32_e32 v217, 0xffff0000, v252
	v_lshlrev_b32_e32 v252, 16, v253
	v_and_b32_e32 v253, 0xffff0000, v253
	v_pk_add_f32 v[106:107], v[106:107], v[216:217]
	v_pk_add_f32 v[108:109], v[108:109], v[252:253]
	v_lshlrev_b32_e32 v216, 16, v254
	v_and_b32_e32 v217, 0xffff0000, v254
	v_lshlrev_b32_e32 v254, 16, v255
	v_and_b32_e32 v255, 0xffff0000, v255
	v_pk_add_f32 v[218:219], v[218:219], v[216:217]
	v_pk_add_f32 v[220:221], v[220:221], v[254:255]
	ds_read_b128 v[252:255], v246 offset:3328
	v_pk_fma_f32 v[106:107], v[158:159], v[106:107], v[98:99] op_sel:[1,0,0] neg_lo:[0,0,1] neg_hi:[0,0,1]
	v_pk_fma_f32 v[108:109], v[158:159], v[108:109], v[100:101] op_sel:[1,0,0] neg_lo:[0,0,1] neg_hi:[0,0,1]
	v_pk_fma_f32 v[218:219], v[158:159], v[218:219], v[102:103] op_sel:[1,0,0] neg_lo:[0,0,1] neg_hi:[0,0,1]
	v_pk_fma_f32 v[220:221], v[158:159], v[220:221], v[104:105] op_sel:[1,0,0] neg_lo:[0,0,1] neg_hi:[0,0,1]
	v_cvt_pk_bf16_f32 v106, v106, v107
	v_cvt_pk_bf16_f32 v107, v108, v109
	v_cvt_pk_bf16_f32 v108, v218, v219
	v_cvt_pk_bf16_f32 v109, v220, v221
	s_and_saveexec_b64 s[28:29], s[6:7]
	s_cbranch_execz .Lpu1_1
	global_store_dwordx4 v[192:193], v[98:101], off offset:64
	global_store_dwordx4 v[192:193], v[102:105], off offset:80
.Lpu1_1:
	s_or_b64 exec, exec, s[28:29]
	s_waitcnt vmcnt(8)
	v_mfma_f32_32x32x16_bf16 v[2:17], v[106:109], v[82:85], v[2:17]
	v_mfma_f32_32x32x16_bf16 v[18:33], v[106:109], v[86:89], v[18:33]
	v_mfma_f32_32x32x16_bf16 v[34:49], v[106:109], v[90:93], v[34:49]
	v_mfma_f32_32x32x16_bf16 v[50:65], v[106:109], v[94:97], v[50:65]
	global_load_dwordx4 v[82:85], v[112:113], off offset:2048
	global_load_dwordx4 v[86:89], v[114:115], off offset:2048
	global_load_dwordx4 v[90:93], v[116:117], off offset:2048
	global_load_dwordx4 v[94:97], v[118:119], off offset:2048
	s_waitcnt lgkmcnt(3)
	v_lshlrev_b32_e32 v98, 16, v238
	v_and_b32_e32 v99, 0xffff0000, v238
	v_lshlrev_b32_e32 v100, 16, v239
	v_and_b32_e32 v101, 0xffff0000, v239
	v_lshlrev_b32_e32 v102, 16, v240
	v_and_b32_e32 v103, 0xffff0000, v240
	v_lshlrev_b32_e32 v104, 16, v241
	v_and_b32_e32 v105, 0xffff0000, v241
	ds_read_b128 v[238:241], v246 offset:3056
	s_waitcnt lgkmcnt(3)
	v_lshlrev_b32_e32 v216, 16, v242
	v_and_b32_e32 v217, 0xffff0000, v242
	v_lshlrev_b32_e32 v242, 16, v243
	v_and_b32_e32 v243, 0xffff0000, v243
	v_pk_add_f32 v[106:107], v[98:99], v[216:217]
	v_pk_add_f32 v[108:109], v[100:101], v[242:243]
	v_lshlrev_b32_e32 v216, 16, v244
	v_and_b32_e32 v217, 0xffff0000, v244
	v_lshlrev_b32_e32 v244, 16, v245
	v_and_b32_e32 v245, 0xffff0000, v245
	v_pk_add_f32 v[218:219], v[102:103], v[216:217]
	v_pk_add_f32 v[220:221], v[104:105], v[244:245]
	ds_read_b128 v[242:245], v246 offset:2784
	s_waitcnt lgkmcnt(3)
	v_lshlrev_b32_e32 v216, 16, v248
	v_and_b32_e32 v217, 0xffff0000, v248
	v_lshlrev_b32_e32 v248, 16, v249
	v_and_b32_e32 v249, 0xffff0000, v249
	v_pk_add_f32 v[106:107], v[106:107], v[216:217]
	v_pk_add_f32 v[108:109], v[108:109], v[248:249]
	v_lshlrev_b32_e32 v216, 16, v250
	v_and_b32_e32 v217, 0xffff0000, v250
	v_lshlrev_b32_e32 v250, 16, v251
	v_and_b32_e32 v251, 0xffff0000, v251
	v_pk_add_f32 v[218:219], v[218:219], v[216:217]
	v_pk_add_f32 v[220:221], v[220:221], v[250:251]
	ds_read_b128 v[248:251], v246 offset:2512
	s_waitcnt lgkmcnt(3)
	v_lshlrev_b32_e32 v216, 16, v252
	v_and_b32_e32 v217, 0xffff0000, v252
	v_lshlrev_b32_e32 v252, 16, v253
	v_and_b32_e32 v253, 0xffff0000, v253
	v_pk_add_f32 v[106:107], v[106:107], v[216:217]
	v_pk_add_f32 v[108:109], v[108:109], v[252:253]
	v_lshlrev_b32_e32 v216, 16, v254
	v_and_b32_e32 v217, 0xffff0000, v254
	v_lshlrev_b32_e32 v254, 16, v255
	v_and_b32_e32 v255, 0xffff0000, v255
	v_pk_add_f32 v[218:219], v[218:219], v[216:217]
	v_pk_add_f32 v[220:221], v[220:221], v[254:255]
	ds_read_b128 v[252:255], v246 offset:2240
	s_waitcnt lgkmcnt(3)
	v_lshlrev_b32_e32 v216, 16, v238
	v_and_b32_e32 v217, 0xffff0000, v238
	v_lshlrev_b32_e32 v238, 16, v239
	v_and_b32_e32 v239, 0xffff0000, v239
	v_pk_add_f32 v[106:107], v[106:107], v[216:217]
	v_pk_add_f32 v[108:109], v[108:109], v[238:239]
	v_lshlrev_b32_e32 v216, 16, v240
	v_and_b32_e32 v217, 0xffff0000, v240
	v_lshlrev_b32_e32 v240, 16, v241
	v_and_b32_e32 v241, 0xffff0000, v241
	v_pk_add_f32 v[218:219], v[218:219], v[216:217]
	v_pk_add_f32 v[220:221], v[220:221], v[240:241]
	ds_read_b128 v[238:241], v246 offset:4176
	s_waitcnt lgkmcnt(3)
	v_lshlrev_b32_e32 v216, 16, v242
	v_and_b32_e32 v217, 0xffff0000, v242
	v_lshlrev_b32_e32 v242, 16, v243
	v_and_b32_e32 v243, 0xffff0000, v243
	v_pk_add_f32 v[106:107], v[106:107], v[216:217]
	v_pk_add_f32 v[108:109], v[108:109], v[242:243]
	v_lshlrev_b32_e32 v216, 16, v244
	v_and_b32_e32 v217, 0xffff0000, v244
	v_lshlrev_b32_e32 v244, 16, v245
	v_and_b32_e32 v245, 0xffff0000, v245
	v_pk_add_f32 v[218:219], v[218:219], v[216:217]
	v_pk_add_f32 v[220:221], v[220:221], v[244:245]
	ds_read_b128 v[242:245], v246 offset:3904
	s_waitcnt lgkmcnt(3)
	v_lshlrev_b32_e32 v216, 16, v248
	v_and_b32_e32 v217, 0xffff0000, v248
	v_lshlrev_b32_e32 v248, 16, v249
	v_and_b32_e32 v249, 0xffff0000, v249
	v_pk_add_f32 v[106:107], v[106:107], v[216:217]
	v_pk_add_f32 v[108:109], v[108:109], v[248:249]
	v_lshlrev_b32_e32 v216, 16, v250
	v_and_b32_e32 v217, 0xffff0000, v250
	v_lshlrev_b32_e32 v250, 16, v251
	v_and_b32_e32 v251, 0xffff0000, v251
	v_pk_add_f32 v[218:219], v[218:219], v[216:217]
	v_pk_add_f32 v[220:221], v[220:221], v[250:251]
	ds_read_b128 v[248:251], v246 offset:3632
	s_waitcnt lgkmcnt(3)
	v_lshlrev_b32_e32 v216, 16, v252
	v_and_b32_e32 v217, 0xffff0000, v252
	v_lshlrev_b32_e32 v252, 16, v253
	v_and_b32_e32 v253, 0xffff0000, v253
	v_pk_add_f32 v[106:107], v[106:107], v[216:217]
	v_pk_add_f32 v[108:109], v[108:109], v[252:253]
	v_lshlrev_b32_e32 v216, 16, v254
	v_and_b32_e32 v217, 0xffff0000, v254
	v_lshlrev_b32_e32 v254, 16, v255
	v_and_b32_e32 v255, 0xffff0000, v255
	v_pk_add_f32 v[218:219], v[218:219], v[216:217]
	v_pk_add_f32 v[220:221], v[220:221], v[254:255]
	ds_read_b128 v[252:255], v246 offset:3360
	v_pk_fma_f32 v[106:107], v[158:159], v[106:107], v[98:99] op_sel:[1,0,0] neg_lo:[0,0,1] neg_hi:[0,0,1]
	v_pk_fma_f32 v[108:109], v[158:159], v[108:109], v[100:101] op_sel:[1,0,0] neg_lo:[0,0,1] neg_hi:[0,0,1]
	v_pk_fma_f32 v[218:219], v[158:159], v[218:219], v[102:103] op_sel:[1,0,0] neg_lo:[0,0,1] neg_hi:[0,0,1]
	v_pk_fma_f32 v[220:221], v[158:159], v[220:221], v[104:105] op_sel:[1,0,0] neg_lo:[0,0,1] neg_hi:[0,0,1]
	v_cvt_pk_bf16_f32 v106, v106, v107
	v_cvt_pk_bf16_f32 v107, v108, v109
	v_cvt_pk_bf16_f32 v108, v218, v219
	v_cvt_pk_bf16_f32 v109, v220, v221
	s_and_saveexec_b64 s[28:29], s[6:7]
	s_cbranch_execz .Lpu1_2
	global_store_dwordx4 v[192:193], v[98:101], off offset:128
	global_store_dwordx4 v[192:193], v[102:105], off offset:144
.Lpu1_2:
	s_or_b64 exec, exec, s[28:29]
	s_waitcnt vmcnt(8)
	v_mfma_f32_32x32x16_bf16 v[2:17], v[106:109], v[222:225], v[2:17]
	v_mfma_f32_32x32x16_bf16 v[18:33], v[106:109], v[226:229], v[18:33]
	v_mfma_f32_32x32x16_bf16 v[34:49], v[106:109], v[230:233], v[34:49]
	v_mfma_f32_32x32x16_bf16 v[50:65], v[106:109], v[234:237], v[50:65]
	global_load_dwordx4 v[222:225], v[112:113], off offset:2560
	global_load_dwordx4 v[226:229], v[114:115], off offset:2560
	global_load_dwordx4 v[230:233], v[116:117], off offset:2560
	global_load_dwordx4 v[234:237], v[118:119], off offset:2560
	s_waitcnt lgkmcnt(3)
	v_lshlrev_b32_e32 v98, 16, v238
	v_and_b32_e32 v99, 0xffff0000, v238
	v_lshlrev_b32_e32 v100, 16, v239
	v_and_b32_e32 v101, 0xffff0000, v239
	v_lshlrev_b32_e32 v102, 16, v240
	v_and_b32_e32 v103, 0xffff0000, v240
	v_lshlrev_b32_e32 v104, 16, v241
	v_and_b32_e32 v105, 0xffff0000, v241
	ds_read_b128 v[238:241], v246 offset:3088
	s_waitcnt lgkmcnt(3)
	v_lshlrev_b32_e32 v216, 16, v242
	v_and_b32_e32 v217, 0xffff0000, v242
	v_lshlrev_b32_e32 v242, 16, v243
	v_and_b32_e32 v243, 0xffff0000, v243
	v_pk_add_f32 v[106:107], v[98:99], v[216:217]
	v_pk_add_f32 v[108:109], v[100:101], v[242:243]
	v_lshlrev_b32_e32 v216, 16, v244
	v_and_b32_e32 v217, 0xffff0000, v244
	v_lshlrev_b32_e32 v244, 16, v245
	v_and_b32_e32 v245, 0xffff0000, v245
	v_pk_add_f32 v[218:219], v[102:103], v[216:217]
	v_pk_add_f32 v[220:221], v[104:105], v[244:245]
	ds_read_b128 v[242:245], v246 offset:2816
	s_waitcnt lgkmcnt(3)
	v_lshlrev_b32_e32 v216, 16, v248
	v_and_b32_e32 v217, 0xffff0000, v248
	v_lshlrev_b32_e32 v248, 16, v249
	v_and_b32_e32 v249, 0xffff0000, v249
	v_pk_add_f32 v[106:107], v[106:107], v[216:217]
	v_pk_add_f32 v[108:109], v[108:109], v[248:249]
	v_lshlrev_b32_e32 v216, 16, v250
	v_and_b32_e32 v217, 0xffff0000, v250
	v_lshlrev_b32_e32 v250, 16, v251
	v_and_b32_e32 v251, 0xffff0000, v251
	v_pk_add_f32 v[218:219], v[218:219], v[216:217]
	v_pk_add_f32 v[220:221], v[220:221], v[250:251]
	ds_read_b128 v[248:251], v246 offset:2544
	s_waitcnt lgkmcnt(3)
	v_lshlrev_b32_e32 v216, 16, v252
	v_and_b32_e32 v217, 0xffff0000, v252
	v_lshlrev_b32_e32 v252, 16, v253
	v_and_b32_e32 v253, 0xffff0000, v253
	v_pk_add_f32 v[106:107], v[106:107], v[216:217]
	v_pk_add_f32 v[108:109], v[108:109], v[252:253]
	v_lshlrev_b32_e32 v216, 16, v254
	v_and_b32_e32 v217, 0xffff0000, v254
	v_lshlrev_b32_e32 v254, 16, v255
	v_and_b32_e32 v255, 0xffff0000, v255
	v_pk_add_f32 v[218:219], v[218:219], v[216:217]
	v_pk_add_f32 v[220:221], v[220:221], v[254:255]
	ds_read_b128 v[252:255], v246 offset:2272
	s_waitcnt lgkmcnt(3)
	v_lshlrev_b32_e32 v216, 16, v238
	v_and_b32_e32 v217, 0xffff0000, v238
	v_lshlrev_b32_e32 v238, 16, v239
	v_and_b32_e32 v239, 0xffff0000, v239
	v_pk_add_f32 v[106:107], v[106:107], v[216:217]
	v_pk_add_f32 v[108:109], v[108:109], v[238:239]
	v_lshlrev_b32_e32 v216, 16, v240
	v_and_b32_e32 v217, 0xffff0000, v240
	v_lshlrev_b32_e32 v240, 16, v241
	v_and_b32_e32 v241, 0xffff0000, v241
	v_pk_add_f32 v[218:219], v[218:219], v[216:217]
	v_pk_add_f32 v[220:221], v[220:221], v[240:241]
	ds_read_b128 v[238:241], v246 offset:4208
	s_waitcnt lgkmcnt(3)
	v_lshlrev_b32_e32 v216, 16, v242
	v_and_b32_e32 v217, 0xffff0000, v242
	v_lshlrev_b32_e32 v242, 16, v243
	v_and_b32_e32 v243, 0xffff0000, v243
	v_pk_add_f32 v[106:107], v[106:107], v[216:217]
	v_pk_add_f32 v[108:109], v[108:109], v[242:243]
	v_lshlrev_b32_e32 v216, 16, v244
	v_and_b32_e32 v217, 0xffff0000, v244
	v_lshlrev_b32_e32 v244, 16, v245
	v_and_b32_e32 v245, 0xffff0000, v245
	v_pk_add_f32 v[218:219], v[218:219], v[216:217]
	v_pk_add_f32 v[220:221], v[220:221], v[244:245]
	ds_read_b128 v[242:245], v246 offset:3936
	s_waitcnt lgkmcnt(3)
	v_lshlrev_b32_e32 v216, 16, v248
	v_and_b32_e32 v217, 0xffff0000, v248
	v_lshlrev_b32_e32 v248, 16, v249
	v_and_b32_e32 v249, 0xffff0000, v249
	v_pk_add_f32 v[106:107], v[106:107], v[216:217]
	v_pk_add_f32 v[108:109], v[108:109], v[248:249]
	v_lshlrev_b32_e32 v216, 16, v250
	v_and_b32_e32 v217, 0xffff0000, v250
	v_lshlrev_b32_e32 v250, 16, v251
	v_and_b32_e32 v251, 0xffff0000, v251
	v_pk_add_f32 v[218:219], v[218:219], v[216:217]
	v_pk_add_f32 v[220:221], v[220:221], v[250:251]
	ds_read_b128 v[248:251], v246 offset:3664
	s_waitcnt lgkmcnt(3)
	v_lshlrev_b32_e32 v216, 16, v252
	v_and_b32_e32 v217, 0xffff0000, v252
	v_lshlrev_b32_e32 v252, 16, v253
	v_and_b32_e32 v253, 0xffff0000, v253
	v_pk_add_f32 v[106:107], v[106:107], v[216:217]
	v_pk_add_f32 v[108:109], v[108:109], v[252:253]
	v_lshlrev_b32_e32 v216, 16, v254
	v_and_b32_e32 v217, 0xffff0000, v254
	v_lshlrev_b32_e32 v254, 16, v255
	v_and_b32_e32 v255, 0xffff0000, v255
	v_pk_add_f32 v[218:219], v[218:219], v[216:217]
	v_pk_add_f32 v[220:221], v[220:221], v[254:255]
	ds_read_b128 v[252:255], v246 offset:3392
	v_pk_fma_f32 v[106:107], v[158:159], v[106:107], v[98:99] op_sel:[1,0,0] neg_lo:[0,0,1] neg_hi:[0,0,1]
	v_pk_fma_f32 v[108:109], v[158:159], v[108:109], v[100:101] op_sel:[1,0,0] neg_lo:[0,0,1] neg_hi:[0,0,1]
	v_pk_fma_f32 v[218:219], v[158:159], v[218:219], v[102:103] op_sel:[1,0,0] neg_lo:[0,0,1] neg_hi:[0,0,1]
	v_pk_fma_f32 v[220:221], v[158:159], v[220:221], v[104:105] op_sel:[1,0,0] neg_lo:[0,0,1] neg_hi:[0,0,1]
	v_cvt_pk_bf16_f32 v106, v106, v107
	v_cvt_pk_bf16_f32 v107, v108, v109
	v_cvt_pk_bf16_f32 v108, v218, v219
	v_cvt_pk_bf16_f32 v109, v220, v221
	s_and_saveexec_b64 s[28:29], s[6:7]
	s_cbranch_execz .Lpu1_3
	global_store_dwordx4 v[192:193], v[98:101], off offset:192
	global_store_dwordx4 v[192:193], v[102:105], off offset:208
.Lpu1_3:
	s_or_b64 exec, exec, s[28:29]
	s_waitcnt vmcnt(8)
	v_mfma_f32_32x32x16_bf16 v[2:17], v[106:109], v[70:73], v[2:17]
	v_mfma_f32_32x32x16_bf16 v[18:33], v[106:109], v[74:77], v[18:33]
	v_mfma_f32_32x32x16_bf16 v[34:49], v[106:109], v[78:81], v[34:49]
	v_mfma_f32_32x32x16_bf16 v[50:65], v[106:109], v[66:69], v[50:65]
	global_load_dwordx4 v[70:73], v[112:113], off offset:3072
	global_load_dwordx4 v[74:77], v[114:115], off offset:3072
	global_load_dwordx4 v[78:81], v[116:117], off offset:3072
	global_load_dwordx4 v[66:69], v[118:119], off offset:3072
	s_waitcnt lgkmcnt(3)
	v_lshlrev_b32_e32 v98, 16, v238
	v_and_b32_e32 v99, 0xffff0000, v238
	v_lshlrev_b32_e32 v100, 16, v239
	v_and_b32_e32 v101, 0xffff0000, v239
	v_lshlrev_b32_e32 v102, 16, v240
	v_and_b32_e32 v103, 0xffff0000, v240
	v_lshlrev_b32_e32 v104, 16, v241
	v_and_b32_e32 v105, 0xffff0000, v241
	ds_read_b128 v[238:241], v246 offset:3120
	s_waitcnt lgkmcnt(3)
	v_lshlrev_b32_e32 v216, 16, v242
	v_and_b32_e32 v217, 0xffff0000, v242
	v_lshlrev_b32_e32 v242, 16, v243
	v_and_b32_e32 v243, 0xffff0000, v243
	v_pk_add_f32 v[106:107], v[98:99], v[216:217]
	v_pk_add_f32 v[108:109], v[100:101], v[242:243]
	v_lshlrev_b32_e32 v216, 16, v244
	v_and_b32_e32 v217, 0xffff0000, v244
	v_lshlrev_b32_e32 v244, 16, v245
	v_and_b32_e32 v245, 0xffff0000, v245
	v_pk_add_f32 v[218:219], v[102:103], v[216:217]
	v_pk_add_f32 v[220:221], v[104:105], v[244:245]
	ds_read_b128 v[242:245], v246 offset:2848
	s_waitcnt lgkmcnt(3)
	v_lshlrev_b32_e32 v216, 16, v248
	v_and_b32_e32 v217, 0xffff0000, v248
	v_lshlrev_b32_e32 v248, 16, v249
	v_and_b32_e32 v249, 0xffff0000, v249
	v_pk_add_f32 v[106:107], v[106:107], v[216:217]
	v_pk_add_f32 v[108:109], v[108:109], v[248:249]
	v_lshlrev_b32_e32 v216, 16, v250
	v_and_b32_e32 v217, 0xffff0000, v250
	v_lshlrev_b32_e32 v250, 16, v251
	v_and_b32_e32 v251, 0xffff0000, v251
	v_pk_add_f32 v[218:219], v[218:219], v[216:217]
	v_pk_add_f32 v[220:221], v[220:221], v[250:251]
	ds_read_b128 v[248:251], v246 offset:2576
	s_waitcnt lgkmcnt(3)
	v_lshlrev_b32_e32 v216, 16, v252
	v_and_b32_e32 v217, 0xffff0000, v252
	v_lshlrev_b32_e32 v252, 16, v253
	v_and_b32_e32 v253, 0xffff0000, v253
	v_pk_add_f32 v[106:107], v[106:107], v[216:217]
	v_pk_add_f32 v[108:109], v[108:109], v[252:253]
	v_lshlrev_b32_e32 v216, 16, v254
	v_and_b32_e32 v217, 0xffff0000, v254
	v_lshlrev_b32_e32 v254, 16, v255
	v_and_b32_e32 v255, 0xffff0000, v255
	v_pk_add_f32 v[218:219], v[218:219], v[216:217]
	v_pk_add_f32 v[220:221], v[220:221], v[254:255]
	ds_read_b128 v[252:255], v246 offset:2304
	s_waitcnt lgkmcnt(3)
	v_lshlrev_b32_e32 v216, 16, v238
	v_and_b32_e32 v217, 0xffff0000, v238
	v_lshlrev_b32_e32 v238, 16, v239
	v_and_b32_e32 v239, 0xffff0000, v239
	v_pk_add_f32 v[106:107], v[106:107], v[216:217]
	v_pk_add_f32 v[108:109], v[108:109], v[238:239]
	v_lshlrev_b32_e32 v216, 16, v240
	v_and_b32_e32 v217, 0xffff0000, v240
	v_lshlrev_b32_e32 v240, 16, v241
	v_and_b32_e32 v241, 0xffff0000, v241
	v_pk_add_f32 v[218:219], v[218:219], v[216:217]
	v_pk_add_f32 v[220:221], v[220:221], v[240:241]
	ds_read_b128 v[238:241], v246 offset:4240
	s_waitcnt lgkmcnt(3)
	v_lshlrev_b32_e32 v216, 16, v242
	v_and_b32_e32 v217, 0xffff0000, v242
	v_lshlrev_b32_e32 v242, 16, v243
	v_and_b32_e32 v243, 0xffff0000, v243
	v_pk_add_f32 v[106:107], v[106:107], v[216:217]
	v_pk_add_f32 v[108:109], v[108:109], v[242:243]
	v_lshlrev_b32_e32 v216, 16, v244
	v_and_b32_e32 v217, 0xffff0000, v244
	v_lshlrev_b32_e32 v244, 16, v245
	v_and_b32_e32 v245, 0xffff0000, v245
	v_pk_add_f32 v[218:219], v[218:219], v[216:217]
	v_pk_add_f32 v[220:221], v[220:221], v[244:245]
	ds_read_b128 v[242:245], v246 offset:3968
	s_waitcnt lgkmcnt(3)
	v_lshlrev_b32_e32 v216, 16, v248
	v_and_b32_e32 v217, 0xffff0000, v248
	v_lshlrev_b32_e32 v248, 16, v249
	v_and_b32_e32 v249, 0xffff0000, v249
	v_pk_add_f32 v[106:107], v[106:107], v[216:217]
	v_pk_add_f32 v[108:109], v[108:109], v[248:249]
	v_lshlrev_b32_e32 v216, 16, v250
	v_and_b32_e32 v217, 0xffff0000, v250
	v_lshlrev_b32_e32 v250, 16, v251
	v_and_b32_e32 v251, 0xffff0000, v251
	v_pk_add_f32 v[218:219], v[218:219], v[216:217]
	v_pk_add_f32 v[220:221], v[220:221], v[250:251]
	ds_read_b128 v[248:251], v246 offset:3696
	s_waitcnt lgkmcnt(3)
	v_lshlrev_b32_e32 v216, 16, v252
	v_and_b32_e32 v217, 0xffff0000, v252
	v_lshlrev_b32_e32 v252, 16, v253
	v_and_b32_e32 v253, 0xffff0000, v253
	v_pk_add_f32 v[106:107], v[106:107], v[216:217]
	v_pk_add_f32 v[108:109], v[108:109], v[252:253]
	v_lshlrev_b32_e32 v216, 16, v254
	v_and_b32_e32 v217, 0xffff0000, v254
	v_lshlrev_b32_e32 v254, 16, v255
	v_and_b32_e32 v255, 0xffff0000, v255
	v_pk_add_f32 v[218:219], v[218:219], v[216:217]
	v_pk_add_f32 v[220:221], v[220:221], v[254:255]
	ds_read_b128 v[252:255], v246 offset:3424
	v_pk_fma_f32 v[106:107], v[158:159], v[106:107], v[98:99] op_sel:[1,0,0] neg_lo:[0,0,1] neg_hi:[0,0,1]
	v_pk_fma_f32 v[108:109], v[158:159], v[108:109], v[100:101] op_sel:[1,0,0] neg_lo:[0,0,1] neg_hi:[0,0,1]
	v_pk_fma_f32 v[218:219], v[158:159], v[218:219], v[102:103] op_sel:[1,0,0] neg_lo:[0,0,1] neg_hi:[0,0,1]
	v_pk_fma_f32 v[220:221], v[158:159], v[220:221], v[104:105] op_sel:[1,0,0] neg_lo:[0,0,1] neg_hi:[0,0,1]
	v_cvt_pk_bf16_f32 v106, v106, v107
	v_cvt_pk_bf16_f32 v107, v108, v109
	v_cvt_pk_bf16_f32 v108, v218, v219
	v_cvt_pk_bf16_f32 v109, v220, v221
	s_and_saveexec_b64 s[28:29], s[6:7]
	s_cbranch_execz .Lpu1_4
	global_store_dwordx4 v[192:193], v[98:101], off offset:256
	global_store_dwordx4 v[192:193], v[102:105], off offset:272
.Lpu1_4:
	s_or_b64 exec, exec, s[28:29]
	s_waitcnt vmcnt(8)
	v_mfma_f32_32x32x16_bf16 v[2:17], v[106:109], v[82:85], v[2:17]
	v_mfma_f32_32x32x16_bf16 v[18:33], v[106:109], v[86:89], v[18:33]
	v_mfma_f32_32x32x16_bf16 v[34:49], v[106:109], v[90:93], v[34:49]
	v_mfma_f32_32x32x16_bf16 v[50:65], v[106:109], v[94:97], v[50:65]
	global_load_dwordx4 v[82:85], v[112:113], off offset:3584
	global_load_dwordx4 v[86:89], v[114:115], off offset:3584
	global_load_dwordx4 v[90:93], v[116:117], off offset:3584
	global_load_dwordx4 v[94:97], v[118:119], off offset:3584
	s_waitcnt lgkmcnt(3)
	v_lshlrev_b32_e32 v98, 16, v238
	v_and_b32_e32 v99, 0xffff0000, v238
	v_lshlrev_b32_e32 v100, 16, v239
	v_and_b32_e32 v101, 0xffff0000, v239
	v_lshlrev_b32_e32 v102, 16, v240
	v_and_b32_e32 v103, 0xffff0000, v240
	v_lshlrev_b32_e32 v104, 16, v241
	v_and_b32_e32 v105, 0xffff0000, v241
	ds_read_b128 v[238:241], v246 offset:3152
	s_waitcnt lgkmcnt(3)
	v_lshlrev_b32_e32 v216, 16, v242
	v_and_b32_e32 v217, 0xffff0000, v242
	v_lshlrev_b32_e32 v242, 16, v243
	v_and_b32_e32 v243, 0xffff0000, v243
	v_pk_add_f32 v[106:107], v[98:99], v[216:217]
	v_pk_add_f32 v[108:109], v[100:101], v[242:243]
	v_lshlrev_b32_e32 v216, 16, v244
	v_and_b32_e32 v217, 0xffff0000, v244
	v_lshlrev_b32_e32 v244, 16, v245
	v_and_b32_e32 v245, 0xffff0000, v245
	v_pk_add_f32 v[218:219], v[102:103], v[216:217]
	v_pk_add_f32 v[220:221], v[104:105], v[244:245]
	ds_read_b128 v[242:245], v246 offset:2880
	s_waitcnt lgkmcnt(3)
	v_lshlrev_b32_e32 v216, 16, v248
	v_and_b32_e32 v217, 0xffff0000, v248
	v_lshlrev_b32_e32 v248, 16, v249
	v_and_b32_e32 v249, 0xffff0000, v249
	v_pk_add_f32 v[106:107], v[106:107], v[216:217]
	v_pk_add_f32 v[108:109], v[108:109], v[248:249]
	v_lshlrev_b32_e32 v216, 16, v250
	v_and_b32_e32 v217, 0xffff0000, v250
	v_lshlrev_b32_e32 v250, 16, v251
	v_and_b32_e32 v251, 0xffff0000, v251
	v_pk_add_f32 v[218:219], v[218:219], v[216:217]
	v_pk_add_f32 v[220:221], v[220:221], v[250:251]
	ds_read_b128 v[248:251], v246 offset:2608
	s_waitcnt lgkmcnt(3)
	v_lshlrev_b32_e32 v216, 16, v252
	v_and_b32_e32 v217, 0xffff0000, v252
	v_lshlrev_b32_e32 v252, 16, v253
	v_and_b32_e32 v253, 0xffff0000, v253
	v_pk_add_f32 v[106:107], v[106:107], v[216:217]
	v_pk_add_f32 v[108:109], v[108:109], v[252:253]
	v_lshlrev_b32_e32 v216, 16, v254
	v_and_b32_e32 v217, 0xffff0000, v254
	v_lshlrev_b32_e32 v254, 16, v255
	v_and_b32_e32 v255, 0xffff0000, v255
	v_pk_add_f32 v[218:219], v[218:219], v[216:217]
	v_pk_add_f32 v[220:221], v[220:221], v[254:255]
	ds_read_b128 v[252:255], v246 offset:2336
	s_waitcnt lgkmcnt(3)
	v_lshlrev_b32_e32 v216, 16, v238
	v_and_b32_e32 v217, 0xffff0000, v238
	v_lshlrev_b32_e32 v238, 16, v239
	v_and_b32_e32 v239, 0xffff0000, v239
	v_pk_add_f32 v[106:107], v[106:107], v[216:217]
	v_pk_add_f32 v[108:109], v[108:109], v[238:239]
	v_lshlrev_b32_e32 v216, 16, v240
	v_and_b32_e32 v217, 0xffff0000, v240
	v_lshlrev_b32_e32 v240, 16, v241
	v_and_b32_e32 v241, 0xffff0000, v241
	v_pk_add_f32 v[218:219], v[218:219], v[216:217]
	v_pk_add_f32 v[220:221], v[220:221], v[240:241]
	ds_read_b128 v[238:241], v246 offset:4272
	s_waitcnt lgkmcnt(3)
	v_lshlrev_b32_e32 v216, 16, v242
	v_and_b32_e32 v217, 0xffff0000, v242
	v_lshlrev_b32_e32 v242, 16, v243
	v_and_b32_e32 v243, 0xffff0000, v243
	v_pk_add_f32 v[106:107], v[106:107], v[216:217]
	v_pk_add_f32 v[108:109], v[108:109], v[242:243]
	v_lshlrev_b32_e32 v216, 16, v244
	v_and_b32_e32 v217, 0xffff0000, v244
	v_lshlrev_b32_e32 v244, 16, v245
	v_and_b32_e32 v245, 0xffff0000, v245
	v_pk_add_f32 v[218:219], v[218:219], v[216:217]
	v_pk_add_f32 v[220:221], v[220:221], v[244:245]
	ds_read_b128 v[242:245], v246 offset:4000
	s_waitcnt lgkmcnt(3)
	v_lshlrev_b32_e32 v216, 16, v248
	v_and_b32_e32 v217, 0xffff0000, v248
	v_lshlrev_b32_e32 v248, 16, v249
	v_and_b32_e32 v249, 0xffff0000, v249
	v_pk_add_f32 v[106:107], v[106:107], v[216:217]
	v_pk_add_f32 v[108:109], v[108:109], v[248:249]
	v_lshlrev_b32_e32 v216, 16, v250
	v_and_b32_e32 v217, 0xffff0000, v250
	v_lshlrev_b32_e32 v250, 16, v251
	v_and_b32_e32 v251, 0xffff0000, v251
	v_pk_add_f32 v[218:219], v[218:219], v[216:217]
	v_pk_add_f32 v[220:221], v[220:221], v[250:251]
	ds_read_b128 v[248:251], v246 offset:3728
	s_waitcnt lgkmcnt(3)
	v_lshlrev_b32_e32 v216, 16, v252
	v_and_b32_e32 v217, 0xffff0000, v252
	v_lshlrev_b32_e32 v252, 16, v253
	v_and_b32_e32 v253, 0xffff0000, v253
	v_pk_add_f32 v[106:107], v[106:107], v[216:217]
	v_pk_add_f32 v[108:109], v[108:109], v[252:253]
	v_lshlrev_b32_e32 v216, 16, v254
	v_and_b32_e32 v217, 0xffff0000, v254
	v_lshlrev_b32_e32 v254, 16, v255
	v_and_b32_e32 v255, 0xffff0000, v255
	v_pk_add_f32 v[218:219], v[218:219], v[216:217]
	v_pk_add_f32 v[220:221], v[220:221], v[254:255]
	ds_read_b128 v[252:255], v246 offset:3456
	v_pk_fma_f32 v[106:107], v[158:159], v[106:107], v[98:99] op_sel:[1,0,0] neg_lo:[0,0,1] neg_hi:[0,0,1]
	v_pk_fma_f32 v[108:109], v[158:159], v[108:109], v[100:101] op_sel:[1,0,0] neg_lo:[0,0,1] neg_hi:[0,0,1]
	v_pk_fma_f32 v[218:219], v[158:159], v[218:219], v[102:103] op_sel:[1,0,0] neg_lo:[0,0,1] neg_hi:[0,0,1]
	v_pk_fma_f32 v[220:221], v[158:159], v[220:221], v[104:105] op_sel:[1,0,0] neg_lo:[0,0,1] neg_hi:[0,0,1]
	v_cvt_pk_bf16_f32 v106, v106, v107
	v_cvt_pk_bf16_f32 v107, v108, v109
	v_cvt_pk_bf16_f32 v108, v218, v219
	v_cvt_pk_bf16_f32 v109, v220, v221
	s_and_saveexec_b64 s[28:29], s[6:7]
	s_cbranch_execz .Lpu1_5
	global_store_dwordx4 v[192:193], v[98:101], off offset:320
	global_store_dwordx4 v[192:193], v[102:105], off offset:336
.Lpu1_5:
	s_or_b64 exec, exec, s[28:29]
	s_waitcnt vmcnt(8)
	v_mfma_f32_32x32x16_bf16 v[2:17], v[106:109], v[222:225], v[2:17]
	v_mfma_f32_32x32x16_bf16 v[18:33], v[106:109], v[226:229], v[18:33]
	v_mfma_f32_32x32x16_bf16 v[34:49], v[106:109], v[230:233], v[34:49]
	v_mfma_f32_32x32x16_bf16 v[50:65], v[106:109], v[234:237], v[50:65]
	s_waitcnt lgkmcnt(3)
	v_lshlrev_b32_e32 v98, 16, v238
	v_and_b32_e32 v99, 0xffff0000, v238
	v_lshlrev_b32_e32 v100, 16, v239
	v_and_b32_e32 v101, 0xffff0000, v239
	v_lshlrev_b32_e32 v102, 16, v240
	v_and_b32_e32 v103, 0xffff0000, v240
	v_lshlrev_b32_e32 v104, 16, v241
	v_and_b32_e32 v105, 0xffff0000, v241
	ds_read_b128 v[238:241], v246 offset:3184
	s_waitcnt lgkmcnt(3)
	v_lshlrev_b32_e32 v216, 16, v242
	v_and_b32_e32 v217, 0xffff0000, v242
	v_lshlrev_b32_e32 v242, 16, v243
	v_and_b32_e32 v243, 0xffff0000, v243
	v_pk_add_f32 v[106:107], v[98:99], v[216:217]
	v_pk_add_f32 v[108:109], v[100:101], v[242:243]
	v_lshlrev_b32_e32 v216, 16, v244
	v_and_b32_e32 v217, 0xffff0000, v244
	v_lshlrev_b32_e32 v244, 16, v245
	v_and_b32_e32 v245, 0xffff0000, v245
	v_pk_add_f32 v[218:219], v[102:103], v[216:217]
	v_pk_add_f32 v[220:221], v[104:105], v[244:245]
	ds_read_b128 v[242:245], v246 offset:2912
	s_waitcnt lgkmcnt(3)
	v_lshlrev_b32_e32 v216, 16, v248
	v_and_b32_e32 v217, 0xffff0000, v248
	v_lshlrev_b32_e32 v248, 16, v249
	v_and_b32_e32 v249, 0xffff0000, v249
	v_pk_add_f32 v[106:107], v[106:107], v[216:217]
	v_pk_add_f32 v[108:109], v[108:109], v[248:249]
	v_lshlrev_b32_e32 v216, 16, v250
	v_and_b32_e32 v217, 0xffff0000, v250
	v_lshlrev_b32_e32 v250, 16, v251
	v_and_b32_e32 v251, 0xffff0000, v251
	v_pk_add_f32 v[218:219], v[218:219], v[216:217]
	v_pk_add_f32 v[220:221], v[220:221], v[250:251]
	ds_read_b128 v[248:251], v246 offset:2640
	s_waitcnt lgkmcnt(3)
	v_lshlrev_b32_e32 v216, 16, v252
	v_and_b32_e32 v217, 0xffff0000, v252
	v_lshlrev_b32_e32 v252, 16, v253
	v_and_b32_e32 v253, 0xffff0000, v253
	v_pk_add_f32 v[106:107], v[106:107], v[216:217]
	v_pk_add_f32 v[108:109], v[108:109], v[252:253]
	v_lshlrev_b32_e32 v216, 16, v254
	v_and_b32_e32 v217, 0xffff0000, v254
	v_lshlrev_b32_e32 v254, 16, v255
	v_and_b32_e32 v255, 0xffff0000, v255
	v_pk_add_f32 v[218:219], v[218:219], v[216:217]
	v_pk_add_f32 v[220:221], v[220:221], v[254:255]
	ds_read_b128 v[252:255], v246 offset:2368
	s_waitcnt lgkmcnt(3)
	v_lshlrev_b32_e32 v216, 16, v238
	v_and_b32_e32 v217, 0xffff0000, v238
	v_lshlrev_b32_e32 v238, 16, v239
	v_and_b32_e32 v239, 0xffff0000, v239
	v_pk_add_f32 v[106:107], v[106:107], v[216:217]
	v_pk_add_f32 v[108:109], v[108:109], v[238:239]
	v_lshlrev_b32_e32 v216, 16, v240
	v_and_b32_e32 v217, 0xffff0000, v240
	v_lshlrev_b32_e32 v240, 16, v241
	v_and_b32_e32 v241, 0xffff0000, v241
	v_pk_add_f32 v[218:219], v[218:219], v[216:217]
	v_pk_add_f32 v[220:221], v[220:221], v[240:241]
	ds_read_b128 v[238:241], v246 offset:4304
	s_waitcnt lgkmcnt(3)
	v_lshlrev_b32_e32 v216, 16, v242
	v_and_b32_e32 v217, 0xffff0000, v242
	v_lshlrev_b32_e32 v242, 16, v243
	v_and_b32_e32 v243, 0xffff0000, v243
	v_pk_add_f32 v[106:107], v[106:107], v[216:217]
	v_pk_add_f32 v[108:109], v[108:109], v[242:243]
	v_lshlrev_b32_e32 v216, 16, v244
	v_and_b32_e32 v217, 0xffff0000, v244
	v_lshlrev_b32_e32 v244, 16, v245
	v_and_b32_e32 v245, 0xffff0000, v245
	v_pk_add_f32 v[218:219], v[218:219], v[216:217]
	v_pk_add_f32 v[220:221], v[220:221], v[244:245]
	ds_read_b128 v[242:245], v246 offset:4032
	s_waitcnt lgkmcnt(3)
	v_lshlrev_b32_e32 v216, 16, v248
	v_and_b32_e32 v217, 0xffff0000, v248
	v_lshlrev_b32_e32 v248, 16, v249
	v_and_b32_e32 v249, 0xffff0000, v249
	v_pk_add_f32 v[106:107], v[106:107], v[216:217]
	v_pk_add_f32 v[108:109], v[108:109], v[248:249]
	v_lshlrev_b32_e32 v216, 16, v250
	v_and_b32_e32 v217, 0xffff0000, v250
	v_lshlrev_b32_e32 v250, 16, v251
	v_and_b32_e32 v251, 0xffff0000, v251
	v_pk_add_f32 v[218:219], v[218:219], v[216:217]
	v_pk_add_f32 v[220:221], v[220:221], v[250:251]
	ds_read_b128 v[248:251], v246 offset:3760
	s_waitcnt lgkmcnt(3)
	v_lshlrev_b32_e32 v216, 16, v252
	v_and_b32_e32 v217, 0xffff0000, v252
	v_lshlrev_b32_e32 v252, 16, v253
	v_and_b32_e32 v253, 0xffff0000, v253
	v_pk_add_f32 v[106:107], v[106:107], v[216:217]
	v_pk_add_f32 v[108:109], v[108:109], v[252:253]
	v_lshlrev_b32_e32 v216, 16, v254
	v_and_b32_e32 v217, 0xffff0000, v254
	v_lshlrev_b32_e32 v254, 16, v255
	v_and_b32_e32 v255, 0xffff0000, v255
	v_pk_add_f32 v[218:219], v[218:219], v[216:217]
	v_pk_add_f32 v[220:221], v[220:221], v[254:255]
	ds_read_b128 v[252:255], v246 offset:3488
	v_pk_fma_f32 v[106:107], v[158:159], v[106:107], v[98:99] op_sel:[1,0,0] neg_lo:[0,0,1] neg_hi:[0,0,1]
	v_pk_fma_f32 v[108:109], v[158:159], v[108:109], v[100:101] op_sel:[1,0,0] neg_lo:[0,0,1] neg_hi:[0,0,1]
	v_pk_fma_f32 v[218:219], v[158:159], v[218:219], v[102:103] op_sel:[1,0,0] neg_lo:[0,0,1] neg_hi:[0,0,1]
	v_pk_fma_f32 v[220:221], v[158:159], v[220:221], v[104:105] op_sel:[1,0,0] neg_lo:[0,0,1] neg_hi:[0,0,1]
	v_cvt_pk_bf16_f32 v106, v106, v107
	v_cvt_pk_bf16_f32 v107, v108, v109
	v_cvt_pk_bf16_f32 v108, v218, v219
	v_cvt_pk_bf16_f32 v109, v220, v221
	s_and_saveexec_b64 s[28:29], s[6:7]
	s_cbranch_execz .Lpu1_6
	global_store_dwordx4 v[192:193], v[98:101], off offset:384
	global_store_dwordx4 v[192:193], v[102:105], off offset:400
.Lpu1_6:
	s_or_b64 exec, exec, s[28:29]
	s_waitcnt vmcnt(4)
	v_mfma_f32_32x32x16_bf16 v[2:17], v[106:109], v[70:73], v[2:17]
	v_mfma_f32_32x32x16_bf16 v[18:33], v[106:109], v[74:77], v[18:33]
	v_mfma_f32_32x32x16_bf16 v[34:49], v[106:109], v[78:81], v[34:49]
	v_mfma_f32_32x32x16_bf16 v[50:65], v[106:109], v[66:69], v[50:65]
	s_waitcnt lgkmcnt(3)
	v_lshlrev_b32_e32 v98, 16, v238
	v_and_b32_e32 v99, 0xffff0000, v238
	v_lshlrev_b32_e32 v100, 16, v239
	v_and_b32_e32 v101, 0xffff0000, v239
	v_lshlrev_b32_e32 v102, 16, v240
	v_and_b32_e32 v103, 0xffff0000, v240
	v_lshlrev_b32_e32 v104, 16, v241
	v_and_b32_e32 v105, 0xffff0000, v241
	ds_read_b128 v[238:241], v246 offset:3216
	s_waitcnt lgkmcnt(3)
	v_lshlrev_b32_e32 v216, 16, v242
	v_and_b32_e32 v217, 0xffff0000, v242
	v_lshlrev_b32_e32 v242, 16, v243
	v_and_b32_e32 v243, 0xffff0000, v243
	v_pk_add_f32 v[106:107], v[98:99], v[216:217]
	v_pk_add_f32 v[108:109], v[100:101], v[242:243]
	v_lshlrev_b32_e32 v216, 16, v244
	v_and_b32_e32 v217, 0xffff0000, v244
	v_lshlrev_b32_e32 v244, 16, v245
	v_and_b32_e32 v245, 0xffff0000, v245
	v_pk_add_f32 v[218:219], v[102:103], v[216:217]
	v_pk_add_f32 v[220:221], v[104:105], v[244:245]
	ds_read_b128 v[242:245], v246 offset:2944
	s_waitcnt lgkmcnt(3)
	v_lshlrev_b32_e32 v216, 16, v248
	v_and_b32_e32 v217, 0xffff0000, v248
	v_lshlrev_b32_e32 v248, 16, v249
	v_and_b32_e32 v249, 0xffff0000, v249
	v_pk_add_f32 v[106:107], v[106:107], v[216:217]
	v_pk_add_f32 v[108:109], v[108:109], v[248:249]
	v_lshlrev_b32_e32 v216, 16, v250
	v_and_b32_e32 v217, 0xffff0000, v250
	v_lshlrev_b32_e32 v250, 16, v251
	v_and_b32_e32 v251, 0xffff0000, v251
	v_pk_add_f32 v[218:219], v[218:219], v[216:217]
	v_pk_add_f32 v[220:221], v[220:221], v[250:251]
	ds_read_b128 v[248:251], v246 offset:2672
	s_waitcnt lgkmcnt(3)
	v_lshlrev_b32_e32 v216, 16, v252
	v_and_b32_e32 v217, 0xffff0000, v252
	v_lshlrev_b32_e32 v252, 16, v253
	v_and_b32_e32 v253, 0xffff0000, v253
	v_pk_add_f32 v[106:107], v[106:107], v[216:217]
	v_pk_add_f32 v[108:109], v[108:109], v[252:253]
	v_lshlrev_b32_e32 v216, 16, v254
	v_and_b32_e32 v217, 0xffff0000, v254
	v_lshlrev_b32_e32 v254, 16, v255
	v_and_b32_e32 v255, 0xffff0000, v255
	v_pk_add_f32 v[218:219], v[218:219], v[216:217]
	v_pk_add_f32 v[220:221], v[220:221], v[254:255]
	ds_read_b128 v[252:255], v246 offset:2400
	s_waitcnt lgkmcnt(3)
	v_lshlrev_b32_e32 v216, 16, v238
	v_and_b32_e32 v217, 0xffff0000, v238
	v_lshlrev_b32_e32 v238, 16, v239
	v_and_b32_e32 v239, 0xffff0000, v239
	v_pk_add_f32 v[106:107], v[106:107], v[216:217]
	v_pk_add_f32 v[108:109], v[108:109], v[238:239]
	v_lshlrev_b32_e32 v216, 16, v240
	v_and_b32_e32 v217, 0xffff0000, v240
	v_lshlrev_b32_e32 v240, 16, v241
	v_and_b32_e32 v241, 0xffff0000, v241
	v_pk_add_f32 v[218:219], v[218:219], v[216:217]
	v_pk_add_f32 v[220:221], v[220:221], v[240:241]
	s_waitcnt lgkmcnt(2)
	v_lshlrev_b32_e32 v216, 16, v242
	v_and_b32_e32 v217, 0xffff0000, v242
	v_lshlrev_b32_e32 v242, 16, v243
	v_and_b32_e32 v243, 0xffff0000, v243
	v_pk_add_f32 v[106:107], v[106:107], v[216:217]
	v_pk_add_f32 v[108:109], v[108:109], v[242:243]
	v_lshlrev_b32_e32 v216, 16, v244
	v_and_b32_e32 v217, 0xffff0000, v244
	v_lshlrev_b32_e32 v244, 16, v245
	v_and_b32_e32 v245, 0xffff0000, v245
	v_pk_add_f32 v[218:219], v[218:219], v[216:217]
	v_pk_add_f32 v[220:221], v[220:221], v[244:245]
	s_waitcnt lgkmcnt(1)
	v_lshlrev_b32_e32 v216, 16, v248
	v_and_b32_e32 v217, 0xffff0000, v248
	v_lshlrev_b32_e32 v248, 16, v249
	v_and_b32_e32 v249, 0xffff0000, v249
	v_pk_add_f32 v[106:107], v[106:107], v[216:217]
	v_pk_add_f32 v[108:109], v[108:109], v[248:249]
	v_lshlrev_b32_e32 v216, 16, v250
	v_and_b32_e32 v217, 0xffff0000, v250
	v_lshlrev_b32_e32 v250, 16, v251
	v_and_b32_e32 v251, 0xffff0000, v251
	v_pk_add_f32 v[218:219], v[218:219], v[216:217]
	v_pk_add_f32 v[220:221], v[220:221], v[250:251]
	s_waitcnt lgkmcnt(0)
	v_lshlrev_b32_e32 v216, 16, v252
	v_and_b32_e32 v217, 0xffff0000, v252
	v_lshlrev_b32_e32 v252, 16, v253
	v_and_b32_e32 v253, 0xffff0000, v253
	v_pk_add_f32 v[106:107], v[106:107], v[216:217]
	v_pk_add_f32 v[108:109], v[108:109], v[252:253]
	v_lshlrev_b32_e32 v216, 16, v254
	v_and_b32_e32 v217, 0xffff0000, v254
	v_lshlrev_b32_e32 v254, 16, v255
	v_and_b32_e32 v255, 0xffff0000, v255
	v_pk_add_f32 v[218:219], v[218:219], v[216:217]
	v_pk_add_f32 v[220:221], v[220:221], v[254:255]
	v_pk_fma_f32 v[106:107], v[158:159], v[106:107], v[98:99] op_sel:[1,0,0] neg_lo:[0,0,1] neg_hi:[0,0,1]
	v_pk_fma_f32 v[108:109], v[158:159], v[108:109], v[100:101] op_sel:[1,0,0] neg_lo:[0,0,1] neg_hi:[0,0,1]
	v_pk_fma_f32 v[218:219], v[158:159], v[218:219], v[102:103] op_sel:[1,0,0] neg_lo:[0,0,1] neg_hi:[0,0,1]
	v_pk_fma_f32 v[220:221], v[158:159], v[220:221], v[104:105] op_sel:[1,0,0] neg_lo:[0,0,1] neg_hi:[0,0,1]
	v_cvt_pk_bf16_f32 v106, v106, v107
	v_cvt_pk_bf16_f32 v107, v108, v109
	v_cvt_pk_bf16_f32 v108, v218, v219
	v_cvt_pk_bf16_f32 v109, v220, v221
	s_and_saveexec_b64 s[28:29], s[6:7]
	s_cbranch_execz .Lpu1_7
	global_store_dwordx4 v[192:193], v[98:101], off offset:448
	global_store_dwordx4 v[192:193], v[102:105], off offset:464

.LBB0_379:
	s_or_b64 exec, exec, s[6:7]
	s_waitcnt lgkmcnt(0)
	global_load_dwordx4 v[82:85], v[122:123], off offset:512
	global_load_dwordx4 v[86:89], v[124:125], off offset:512
	global_load_dwordx4 v[90:93], v[126:127], off offset:512
	global_load_dwordx4 v[94:97], v[128:129], off offset:512
	global_load_dwordx4 v[222:225], v[122:123], off offset:1024
	global_load_dwordx4 v[226:229], v[124:125], off offset:1024
	global_load_dwordx4 v[230:233], v[126:127], off offset:1024
	global_load_dwordx4 v[234:237], v[128:129], off offset:1024
	v_lshl_add_u32 v246, v197, 1, v214
	ds_read_b128 v[238:241], v246 offset:4080
	ds_read_b128 v[242:245], v246 offset:3808
	ds_read_b128 v[248:251], v246 offset:3536
	ds_read_b128 v[252:255], v246 offset:3264
	v_or_b32_e32 v2, s28, v1
	v_min_u32_e32 v3, 3, v2
	v_add_u32_e32 v3, 1, v3
	v_cvt_f32_ubyte0_e32 v3, v3
	v_div_scale_f32 v4, s[6:7], v3, v3, 1.0
	v_rcp_f32_e32 v5, v4
	s_ashr_i32 s8, s30, 6
	s_mul_i32 s10, s8, 15
	v_cmp_lt_u32_e64 s[6:7], s41, v2
	v_fma_f32 v6, -v4, v5, 1.0
	v_fmac_f32_e32 v5, v6, v5
	v_div_scale_f32 v6, vcc, 1.0, v3, 1.0
	v_mul_f32_e32 v7, v6, v5
	v_fma_f32 v8, -v4, v7, v6
	v_fmac_f32_e32 v7, v8, v5
	v_fma_f32 v4, -v4, v7, v6
	v_div_fmas_f32 v4, v4, v5, v7
	v_div_fixup_f32 v159, v4, v3, 1.0
	s_ashr_i32 s11, s10, 31
	v_add_u32_e32 v2, 0xfffff80f, v2
	v_mov_b32_e32 v3, v155
	v_lshl_add_u64 v[2:3], v[2:3], 0, s[10:11]
	v_lshlrev_b64 v[2:3], 11, v[2:3]
	v_lshl_add_u64 v[2:3], s[70:71], 0, v[2:3]
	v_mov_b32_e32 v163, v155
	v_lshl_add_u64 v[2:3], v[2:3], 0, v[162:163]
	v_lshl_add_u64 v[190:191], v[2:3], 0, s[24:25]
	v_mov_b64_e32 v[2:3], 0
	v_mov_b64_e32 v[4:5], 0
	v_mov_b64_e32 v[6:7], 0
	v_mov_b64_e32 v[8:9], 0
	v_mov_b64_e32 v[10:11], 0
	v_mov_b64_e32 v[12:13], 0
	v_mov_b64_e32 v[14:15], 0
	v_mov_b64_e32 v[16:17], 0
	v_mov_b64_e32 v[18:19], 0
	v_mov_b64_e32 v[20:21], 0
	v_mov_b64_e32 v[22:23], 0
	v_mov_b64_e32 v[24:25], 0
	v_mov_b64_e32 v[26:27], 0
	v_mov_b64_e32 v[28:29], 0
	v_mov_b64_e32 v[30:31], 0
	v_mov_b64_e32 v[32:33], 0
	v_mov_b64_e32 v[34:35], 0
	v_mov_b64_e32 v[36:37], 0
	v_mov_b64_e32 v[38:39], 0
	v_mov_b64_e32 v[40:41], 0
	v_mov_b64_e32 v[42:43], 0
	v_mov_b64_e32 v[44:45], 0
	v_mov_b64_e32 v[46:47], 0
	v_mov_b64_e32 v[48:49], 0
	v_mov_b64_e32 v[50:51], 0
	v_mov_b64_e32 v[52:53], 0
	v_mov_b64_e32 v[54:55], 0
	v_mov_b64_e32 v[56:57], 0
	v_mov_b64_e32 v[58:59], 0
	v_mov_b64_e32 v[60:61], 0
	v_mov_b64_e32 v[62:63], 0
	v_mov_b64_e32 v[64:65], 0
	s_mov_b32 s49, 0
	s_mov_b64 s[10:11], 0
	s_waitcnt lgkmcnt(3)
	v_lshlrev_b32_e32 v98, 16, v238
	v_and_b32_e32 v99, 0xffff0000, v238
	v_lshlrev_b32_e32 v100, 16, v239
	v_and_b32_e32 v101, 0xffff0000, v239
	v_lshlrev_b32_e32 v102, 16, v240
	v_and_b32_e32 v103, 0xffff0000, v240
	v_lshlrev_b32_e32 v104, 16, v241
	v_and_b32_e32 v105, 0xffff0000, v241
	ds_read_b128 v[238:241], v246 offset:4112
	s_waitcnt lgkmcnt(3)
	v_lshlrev_b32_e32 v216, 16, v242
	v_and_b32_e32 v217, 0xffff0000, v242
	v_lshlrev_b32_e32 v242, 16, v243
	v_and_b32_e32 v243, 0xffff0000, v243
	v_pk_add_f32 v[106:107], v[98:99], v[216:217]
	v_pk_add_f32 v[108:109], v[100:101], v[242:243]
	v_lshlrev_b32_e32 v216, 16, v244
	v_and_b32_e32 v217, 0xffff0000, v244
	v_lshlrev_b32_e32 v244, 16, v245
	v_and_b32_e32 v245, 0xffff0000, v245
	v_pk_add_f32 v[218:219], v[102:103], v[216:217]
	v_pk_add_f32 v[220:221], v[104:105], v[244:245]
	ds_read_b128 v[242:245], v246 offset:3840
	s_waitcnt lgkmcnt(3)
	v_lshlrev_b32_e32 v216, 16, v248
	v_and_b32_e32 v217, 0xffff0000, v248
	v_lshlrev_b32_e32 v248, 16, v249
	v_and_b32_e32 v249, 0xffff0000, v249
	v_pk_add_f32 v[106:107], v[106:107], v[216:217]
	v_pk_add_f32 v[108:109], v[108:109], v[248:249]
	v_lshlrev_b32_e32 v216, 16, v250
	v_and_b32_e32 v217, 0xffff0000, v250
	v_lshlrev_b32_e32 v250, 16, v251
	v_and_b32_e32 v251, 0xffff0000, v251
	v_pk_add_f32 v[218:219], v[218:219], v[216:217]
	v_pk_add_f32 v[220:221], v[220:221], v[250:251]
	ds_read_b128 v[248:251], v246 offset:3568
	s_waitcnt lgkmcnt(3)
	v_lshlrev_b32_e32 v216, 16, v252
	v_and_b32_e32 v217, 0xffff0000, v252
	v_lshlrev_b32_e32 v252, 16, v253
	v_and_b32_e32 v253, 0xffff0000, v253
	v_pk_add_f32 v[106:107], v[106:107], v[216:217]
	v_pk_add_f32 v[108:109], v[108:109], v[252:253]
	v_lshlrev_b32_e32 v216, 16, v254
	v_and_b32_e32 v217, 0xffff0000, v254
	v_lshlrev_b32_e32 v254, 16, v255
	v_and_b32_e32 v255, 0xffff0000, v255
	v_pk_add_f32 v[218:219], v[218:219], v[216:217]
	v_pk_add_f32 v[220:221], v[220:221], v[254:255]
	ds_read_b128 v[252:255], v246 offset:3296
	v_pk_fma_f32 v[106:107], v[158:159], v[106:107], v[98:99] op_sel:[1,0,0] neg_lo:[0,0,1] neg_hi:[0,0,1]
	v_pk_fma_f32 v[108:109], v[158:159], v[108:109], v[100:101] op_sel:[1,0,0] neg_lo:[0,0,1] neg_hi:[0,0,1]
	v_pk_fma_f32 v[218:219], v[158:159], v[218:219], v[102:103] op_sel:[1,0,0] neg_lo:[0,0,1] neg_hi:[0,0,1]
	v_pk_fma_f32 v[220:221], v[158:159], v[220:221], v[104:105] op_sel:[1,0,0] neg_lo:[0,0,1] neg_hi:[0,0,1]
	v_cvt_pk_bf16_f32 v106, v106, v107
	v_cvt_pk_bf16_f32 v107, v108, v109
	v_cvt_pk_bf16_f32 v108, v218, v219
	v_cvt_pk_bf16_f32 v109, v220, v221
	s_and_saveexec_b64 s[28:29], s[6:7]
	s_cbranch_execz .Lpu2_0
	global_store_dwordx4 v[190:191], v[98:101], off offset:0
	global_store_dwordx4 v[190:191], v[102:105], off offset:16
.Lpu2_0:
	s_or_b64 exec, exec, s[28:29]
	s_waitcnt vmcnt(8)
	v_mfma_f32_32x32x16_bf16 v[2:17], v[106:109], v[70:73], v[2:17]
	v_mfma_f32_32x32x16_bf16 v[18:33], v[106:109], v[74:77], v[18:33]
	v_mfma_f32_32x32x16_bf16 v[34:49], v[106:109], v[78:81], v[34:49]
	v_mfma_f32_32x32x16_bf16 v[50:65], v[106:109], v[66:69], v[50:65]
	global_load_dwordx4 v[70:73], v[122:123], off offset:1536
	global_load_dwordx4 v[74:77], v[124:125], off offset:1536
	global_load_dwordx4 v[78:81], v[126:127], off offset:1536
	global_load_dwordx4 v[66:69], v[128:129], off offset:1536
	s_waitcnt lgkmcnt(3)
	v_lshlrev_b32_e32 v98, 16, v238
	v_and_b32_e32 v99, 0xffff0000, v238
	v_lshlrev_b32_e32 v100, 16, v239
	v_and_b32_e32 v101, 0xffff0000, v239
	v_lshlrev_b32_e32 v102, 16, v240
	v_and_b32_e32 v103, 0xffff0000, v240
	v_lshlrev_b32_e32 v104, 16, v241
	v_and_b32_e32 v105, 0xffff0000, v241
	ds_read_b128 v[238:241], v246 offset:4144
	s_waitcnt lgkmcnt(3)
	v_lshlrev_b32_e32 v216, 16, v242
	v_and_b32_e32 v217, 0xffff0000, v242
	v_lshlrev_b32_e32 v242, 16, v243
	v_and_b32_e32 v243, 0xffff0000, v243
	v_pk_add_f32 v[106:107], v[98:99], v[216:217]
	v_pk_add_f32 v[108:109], v[100:101], v[242:243]
	v_lshlrev_b32_e32 v216, 16, v244
	v_and_b32_e32 v217, 0xffff0000, v244
	v_lshlrev_b32_e32 v244, 16, v245
	v_and_b32_e32 v245, 0xffff0000, v245
	v_pk_add_f32 v[218:219], v[102:103], v[216:217]
	v_pk_add_f32 v[220:221], v[104:105], v[244:245]
	ds_read_b128 v[242:245], v246 offset:3872
	s_waitcnt lgkmcnt(3)
	v_lshlrev_b32_e32 v216, 16, v248
	v_and_b32_e32 v217, 0xffff0000, v248
	v_lshlrev_b32_e32 v248, 16, v249
	v_and_b32_e32 v249, 0xffff0000, v249
	v_pk_add_f32 v[106:107], v[106:107], v[216:217]
	v_pk_add_f32 v[108:109], v[108:109], v[248:249]
	v_lshlrev_b32_e32 v216, 16, v250
	v_and_b32_e32 v217, 0xffff0000, v250
	v_lshlrev_b32_e32 v250, 16, v251
	v_and_b32_e32 v251, 0xffff0000, v251
	v_pk_add_f32 v[218:219], v[218:219], v[216:217]
	v_pk_add_f32 v[220:221], v[220:221], v[250:251]
	ds_read_b128 v[248:251], v246 offset:3600
	s_waitcnt lgkmcnt(3)
	v_lshlrev_b32_e32 v216, 16, v252
	v_and_b32_e32 v217, 0xffff0000, v252
	v_lshlrev_b32_e32 v252, 16, v253
	v_and_b32_e32 v253, 0xffff0000, v253
	v_pk_add_f32 v[106:107], v[106:107], v[216:217]
	v_pk_add_f32 v[108:109], v[108:109], v[252:253]
	v_lshlrev_b32_e32 v216, 16, v254
	v_and_b32_e32 v217, 0xffff0000, v254
	v_lshlrev_b32_e32 v254, 16, v255
	v_and_b32_e32 v255, 0xffff0000, v255
	v_pk_add_f32 v[218:219], v[218:219], v[216:217]
	v_pk_add_f32 v[220:221], v[220:221], v[254:255]
	ds_read_b128 v[252:255], v246 offset:3328
	v_pk_fma_f32 v[106:107], v[158:159], v[106:107], v[98:99] op_sel:[1,0,0] neg_lo:[0,0,1] neg_hi:[0,0,1]
	v_pk_fma_f32 v[108:109], v[158:159], v[108:109], v[100:101] op_sel:[1,0,0] neg_lo:[0,0,1] neg_hi:[0,0,1]
	v_pk_fma_f32 v[218:219], v[158:159], v[218:219], v[102:103] op_sel:[1,0,0] neg_lo:[0,0,1] neg_hi:[0,0,1]
	v_pk_fma_f32 v[220:221], v[158:159], v[220:221], v[104:105] op_sel:[1,0,0] neg_lo:[0,0,1] neg_hi:[0,0,1]
	v_cvt_pk_bf16_f32 v106, v106, v107
	v_cvt_pk_bf16_f32 v107, v108, v109
	v_cvt_pk_bf16_f32 v108, v218, v219
	v_cvt_pk_bf16_f32 v109, v220, v221
	s_and_saveexec_b64 s[28:29], s[6:7]
	s_cbranch_execz .Lpu2_1
	global_store_dwordx4 v[190:191], v[98:101], off offset:64
	global_store_dwordx4 v[190:191], v[102:105], off offset:80
.Lpu2_1:
	s_or_b64 exec, exec, s[28:29]
	s_waitcnt vmcnt(8)
	v_mfma_f32_32x32x16_bf16 v[2:17], v[106:109], v[82:85], v[2:17]
	v_mfma_f32_32x32x16_bf16 v[18:33], v[106:109], v[86:89], v[18:33]
	v_mfma_f32_32x32x16_bf16 v[34:49], v[106:109], v[90:93], v[34:49]
	v_mfma_f32_32x32x16_bf16 v[50:65], v[106:109], v[94:97], v[50:65]
	global_load_dwordx4 v[82:85], v[122:123], off offset:2048
	global_load_dwordx4 v[86:89], v[124:125], off offset:2048
	global_load_dwordx4 v[90:93], v[126:127], off offset:2048
	global_load_dwordx4 v[94:97], v[128:129], off offset:2048
	s_waitcnt lgkmcnt(3)
	v_lshlrev_b32_e32 v98, 16, v238
	v_and_b32_e32 v99, 0xffff0000, v238
	v_lshlrev_b32_e32 v100, 16, v239
	v_and_b32_e32 v101, 0xffff0000, v239
	v_lshlrev_b32_e32 v102, 16, v240
	v_and_b32_e32 v103, 0xffff0000, v240
	v_lshlrev_b32_e32 v104, 16, v241
	v_and_b32_e32 v105, 0xffff0000, v241
	ds_read_b128 v[238:241], v246 offset:4176
	s_waitcnt lgkmcnt(3)
	v_lshlrev_b32_e32 v216, 16, v242
	v_and_b32_e32 v217, 0xffff0000, v242
	v_lshlrev_b32_e32 v242, 16, v243
	v_and_b32_e32 v243, 0xffff0000, v243
	v_pk_add_f32 v[106:107], v[98:99], v[216:217]
	v_pk_add_f32 v[108:109], v[100:101], v[242:243]
	v_lshlrev_b32_e32 v216, 16, v244
	v_and_b32_e32 v217, 0xffff0000, v244
	v_lshlrev_b32_e32 v244, 16, v245
	v_and_b32_e32 v245, 0xffff0000, v245
	v_pk_add_f32 v[218:219], v[102:103], v[216:217]
	v_pk_add_f32 v[220:221], v[104:105], v[244:245]
	ds_read_b128 v[242:245], v246 offset:3904
	s_waitcnt lgkmcnt(3)
	v_lshlrev_b32_e32 v216, 16, v248
	v_and_b32_e32 v217, 0xffff0000, v248
	v_lshlrev_b32_e32 v248, 16, v249
	v_and_b32_e32 v249, 0xffff0000, v249
	v_pk_add_f32 v[106:107], v[106:107], v[216:217]
	v_pk_add_f32 v[108:109], v[108:109], v[248:249]
	v_lshlrev_b32_e32 v216, 16, v250
	v_and_b32_e32 v217, 0xffff0000, v250
	v_lshlrev_b32_e32 v250, 16, v251
	v_and_b32_e32 v251, 0xffff0000, v251
	v_pk_add_f32 v[218:219], v[218:219], v[216:217]
	v_pk_add_f32 v[220:221], v[220:221], v[250:251]
	ds_read_b128 v[248:251], v246 offset:3632
	s_waitcnt lgkmcnt(3)
	v_lshlrev_b32_e32 v216, 16, v252
	v_and_b32_e32 v217, 0xffff0000, v252
	v_lshlrev_b32_e32 v252, 16, v253
	v_and_b32_e32 v253, 0xffff0000, v253
	v_pk_add_f32 v[106:107], v[106:107], v[216:217]
	v_pk_add_f32 v[108:109], v[108:109], v[252:253]
	v_lshlrev_b32_e32 v216, 16, v254
	v_and_b32_e32 v217, 0xffff0000, v254
	v_lshlrev_b32_e32 v254, 16, v255
	v_and_b32_e32 v255, 0xffff0000, v255
	v_pk_add_f32 v[218:219], v[218:219], v[216:217]
	v_pk_add_f32 v[220:221], v[220:221], v[254:255]
	ds_read_b128 v[252:255], v246 offset:3360
	v_pk_fma_f32 v[106:107], v[158:159], v[106:107], v[98:99] op_sel:[1,0,0] neg_lo:[0,0,1] neg_hi:[0,0,1]
	v_pk_fma_f32 v[108:109], v[158:159], v[108:109], v[100:101] op_sel:[1,0,0] neg_lo:[0,0,1] neg_hi:[0,0,1]
	v_pk_fma_f32 v[218:219], v[158:159], v[218:219], v[102:103] op_sel:[1,0,0] neg_lo:[0,0,1] neg_hi:[0,0,1]
	v_pk_fma_f32 v[220:221], v[158:159], v[220:221], v[104:105] op_sel:[1,0,0] neg_lo:[0,0,1] neg_hi:[0,0,1]
	v_cvt_pk_bf16_f32 v106, v106, v107
	v_cvt_pk_bf16_f32 v107, v108, v109
	v_cvt_pk_bf16_f32 v108, v218, v219
	v_cvt_pk_bf16_f32 v109, v220, v221
	s_and_saveexec_b64 s[28:29], s[6:7]
	s_cbranch_execz .Lpu2_2
	global_store_dwordx4 v[190:191], v[98:101], off offset:128
	global_store_dwordx4 v[190:191], v[102:105], off offset:144
.Lpu2_2:
	s_or_b64 exec, exec, s[28:29]
	s_waitcnt vmcnt(8)
	v_mfma_f32_32x32x16_bf16 v[2:17], v[106:109], v[222:225], v[2:17]
	v_mfma_f32_32x32x16_bf16 v[18:33], v[106:109], v[226:229], v[18:33]
	v_mfma_f32_32x32x16_bf16 v[34:49], v[106:109], v[230:233], v[34:49]
	v_mfma_f32_32x32x16_bf16 v[50:65], v[106:109], v[234:237], v[50:65]
	global_load_dwordx4 v[222:225], v[122:123], off offset:2560
	global_load_dwordx4 v[226:229], v[124:125], off offset:2560
	global_load_dwordx4 v[230:233], v[126:127], off offset:2560
	global_load_dwordx4 v[234:237], v[128:129], off offset:2560
	s_waitcnt lgkmcnt(3)
	v_lshlrev_b32_e32 v98, 16, v238
	v_and_b32_e32 v99, 0xffff0000, v238
	v_lshlrev_b32_e32 v100, 16, v239
	v_and_b32_e32 v101, 0xffff0000, v239
	v_lshlrev_b32_e32 v102, 16, v240
	v_and_b32_e32 v103, 0xffff0000, v240
	v_lshlrev_b32_e32 v104, 16, v241
	v_and_b32_e32 v105, 0xffff0000, v241
	ds_read_b128 v[238:241], v246 offset:4208
	s_waitcnt lgkmcnt(3)
	v_lshlrev_b32_e32 v216, 16, v242
	v_and_b32_e32 v217, 0xffff0000, v242
	v_lshlrev_b32_e32 v242, 16, v243
	v_and_b32_e32 v243, 0xffff0000, v243
	v_pk_add_f32 v[106:107], v[98:99], v[216:217]
	v_pk_add_f32 v[108:109], v[100:101], v[242:243]
	v_lshlrev_b32_e32 v216, 16, v244
	v_and_b32_e32 v217, 0xffff0000, v244
	v_lshlrev_b32_e32 v244, 16, v245
	v_and_b32_e32 v245, 0xffff0000, v245
	v_pk_add_f32 v[218:219], v[102:103], v[216:217]
	v_pk_add_f32 v[220:221], v[104:105], v[244:245]
	ds_read_b128 v[242:245], v246 offset:3936
	s_waitcnt lgkmcnt(3)
	v_lshlrev_b32_e32 v216, 16, v248
	v_and_b32_e32 v217, 0xffff0000, v248
	v_lshlrev_b32_e32 v248, 16, v249
	v_and_b32_e32 v249, 0xffff0000, v249
	v_pk_add_f32 v[106:107], v[106:107], v[216:217]
	v_pk_add_f32 v[108:109], v[108:109], v[248:249]
	v_lshlrev_b32_e32 v216, 16, v250
	v_and_b32_e32 v217, 0xffff0000, v250
	v_lshlrev_b32_e32 v250, 16, v251
	v_and_b32_e32 v251, 0xffff0000, v251
	v_pk_add_f32 v[218:219], v[218:219], v[216:217]
	v_pk_add_f32 v[220:221], v[220:221], v[250:251]
	ds_read_b128 v[248:251], v246 offset:3664
	s_waitcnt lgkmcnt(3)
	v_lshlrev_b32_e32 v216, 16, v252
	v_and_b32_e32 v217, 0xffff0000, v252
	v_lshlrev_b32_e32 v252, 16, v253
	v_and_b32_e32 v253, 0xffff0000, v253
	v_pk_add_f32 v[106:107], v[106:107], v[216:217]
	v_pk_add_f32 v[108:109], v[108:109], v[252:253]
	v_lshlrev_b32_e32 v216, 16, v254
	v_and_b32_e32 v217, 0xffff0000, v254
	v_lshlrev_b32_e32 v254, 16, v255
	v_and_b32_e32 v255, 0xffff0000, v255
	v_pk_add_f32 v[218:219], v[218:219], v[216:217]
	v_pk_add_f32 v[220:221], v[220:221], v[254:255]
	ds_read_b128 v[252:255], v246 offset:3392
	v_pk_fma_f32 v[106:107], v[158:159], v[106:107], v[98:99] op_sel:[1,0,0] neg_lo:[0,0,1] neg_hi:[0,0,1]
	v_pk_fma_f32 v[108:109], v[158:159], v[108:109], v[100:101] op_sel:[1,0,0] neg_lo:[0,0,1] neg_hi:[0,0,1]
	v_pk_fma_f32 v[218:219], v[158:159], v[218:219], v[102:103] op_sel:[1,0,0] neg_lo:[0,0,1] neg_hi:[0,0,1]
	v_pk_fma_f32 v[220:221], v[158:159], v[220:221], v[104:105] op_sel:[1,0,0] neg_lo:[0,0,1] neg_hi:[0,0,1]
	v_cvt_pk_bf16_f32 v106, v106, v107
	v_cvt_pk_bf16_f32 v107, v108, v109
	v_cvt_pk_bf16_f32 v108, v218, v219
	v_cvt_pk_bf16_f32 v109, v220, v221
	s_and_saveexec_b64 s[28:29], s[6:7]
	s_cbranch_execz .Lpu2_3
	global_store_dwordx4 v[190:191], v[98:101], off offset:192
	global_store_dwordx4 v[190:191], v[102:105], off offset:208
.Lpu2_3:
	s_or_b64 exec, exec, s[28:29]
	s_waitcnt vmcnt(8)
	v_mfma_f32_32x32x16_bf16 v[2:17], v[106:109], v[70:73], v[2:17]
	v_mfma_f32_32x32x16_bf16 v[18:33], v[106:109], v[74:77], v[18:33]
	v_mfma_f32_32x32x16_bf16 v[34:49], v[106:109], v[78:81], v[34:49]
	v_mfma_f32_32x32x16_bf16 v[50:65], v[106:109], v[66:69], v[50:65]
	global_load_dwordx4 v[70:73], v[122:123], off offset:3072
	global_load_dwordx4 v[74:77], v[124:125], off offset:3072
	global_load_dwordx4 v[78:81], v[126:127], off offset:3072
	global_load_dwordx4 v[66:69], v[128:129], off offset:3072
	s_waitcnt lgkmcnt(3)
	v_lshlrev_b32_e32 v98, 16, v238
	v_and_b32_e32 v99, 0xffff0000, v238
	v_lshlrev_b32_e32 v100, 16, v239
	v_and_b32_e32 v101, 0xffff0000, v239
	v_lshlrev_b32_e32 v102, 16, v240
	v_and_b32_e32 v103, 0xffff0000, v240
	v_lshlrev_b32_e32 v104, 16, v241
	v_and_b32_e32 v105, 0xffff0000, v241
	ds_read_b128 v[238:241], v246 offset:4240
	s_waitcnt lgkmcnt(3)
	v_lshlrev_b32_e32 v216, 16, v242
	v_and_b32_e32 v217, 0xffff0000, v242
	v_lshlrev_b32_e32 v242, 16, v243
	v_and_b32_e32 v243, 0xffff0000, v243
	v_pk_add_f32 v[106:107], v[98:99], v[216:217]
	v_pk_add_f32 v[108:109], v[100:101], v[242:243]
	v_lshlrev_b32_e32 v216, 16, v244
	v_and_b32_e32 v217, 0xffff0000, v244
	v_lshlrev_b32_e32 v244, 16, v245
	v_and_b32_e32 v245, 0xffff0000, v245
	v_pk_add_f32 v[218:219], v[102:103], v[216:217]
	v_pk_add_f32 v[220:221], v[104:105], v[244:245]
	ds_read_b128 v[242:245], v246 offset:3968
	s_waitcnt lgkmcnt(3)
	v_lshlrev_b32_e32 v216, 16, v248
	v_and_b32_e32 v217, 0xffff0000, v248
	v_lshlrev_b32_e32 v248, 16, v249
	v_and_b32_e32 v249, 0xffff0000, v249
	v_pk_add_f32 v[106:107], v[106:107], v[216:217]
	v_pk_add_f32 v[108:109], v[108:109], v[248:249]
	v_lshlrev_b32_e32 v216, 16, v250
	v_and_b32_e32 v217, 0xffff0000, v250
	v_lshlrev_b32_e32 v250, 16, v251
	v_and_b32_e32 v251, 0xffff0000, v251
	v_pk_add_f32 v[218:219], v[218:219], v[216:217]
	v_pk_add_f32 v[220:221], v[220:221], v[250:251]
	ds_read_b128 v[248:251], v246 offset:3696
	s_waitcnt lgkmcnt(3)
	v_lshlrev_b32_e32 v216, 16, v252
	v_and_b32_e32 v217, 0xffff0000, v252
	v_lshlrev_b32_e32 v252, 16, v253
	v_and_b32_e32 v253, 0xffff0000, v253
	v_pk_add_f32 v[106:107], v[106:107], v[216:217]
	v_pk_add_f32 v[108:109], v[108:109], v[252:253]
	v_lshlrev_b32_e32 v216, 16, v254
	v_and_b32_e32 v217, 0xffff0000, v254
	v_lshlrev_b32_e32 v254, 16, v255
	v_and_b32_e32 v255, 0xffff0000, v255
	v_pk_add_f32 v[218:219], v[218:219], v[216:217]
	v_pk_add_f32 v[220:221], v[220:221], v[254:255]
	ds_read_b128 v[252:255], v246 offset:3424
	v_pk_fma_f32 v[106:107], v[158:159], v[106:107], v[98:99] op_sel:[1,0,0] neg_lo:[0,0,1] neg_hi:[0,0,1]
	v_pk_fma_f32 v[108:109], v[158:159], v[108:109], v[100:101] op_sel:[1,0,0] neg_lo:[0,0,1] neg_hi:[0,0,1]
	v_pk_fma_f32 v[218:219], v[158:159], v[218:219], v[102:103] op_sel:[1,0,0] neg_lo:[0,0,1] neg_hi:[0,0,1]
	v_pk_fma_f32 v[220:221], v[158:159], v[220:221], v[104:105] op_sel:[1,0,0] neg_lo:[0,0,1] neg_hi:[0,0,1]
	v_cvt_pk_bf16_f32 v106, v106, v107
	v_cvt_pk_bf16_f32 v107, v108, v109
	v_cvt_pk_bf16_f32 v108, v218, v219
	v_cvt_pk_bf16_f32 v109, v220, v221
	s_and_saveexec_b64 s[28:29], s[6:7]
	s_cbranch_execz .Lpu2_4
	global_store_dwordx4 v[190:191], v[98:101], off offset:256
	global_store_dwordx4 v[190:191], v[102:105], off offset:272
.Lpu2_4:
	s_or_b64 exec, exec, s[28:29]
	s_waitcnt vmcnt(8)
	v_mfma_f32_32x32x16_bf16 v[2:17], v[106:109], v[82:85], v[2:17]
	v_mfma_f32_32x32x16_bf16 v[18:33], v[106:109], v[86:89], v[18:33]
	v_mfma_f32_32x32x16_bf16 v[34:49], v[106:109], v[90:93], v[34:49]
	v_mfma_f32_32x32x16_bf16 v[50:65], v[106:109], v[94:97], v[50:65]
	global_load_dwordx4 v[82:85], v[122:123], off offset:3584
	global_load_dwordx4 v[86:89], v[124:125], off offset:3584
	global_load_dwordx4 v[90:93], v[126:127], off offset:3584
	global_load_dwordx4 v[94:97], v[128:129], off offset:3584
	s_waitcnt lgkmcnt(3)
	v_lshlrev_b32_e32 v98, 16, v238
	v_and_b32_e32 v99, 0xffff0000, v238
	v_lshlrev_b32_e32 v100, 16, v239
	v_and_b32_e32 v101, 0xffff0000, v239
	v_lshlrev_b32_e32 v102, 16, v240
	v_and_b32_e32 v103, 0xffff0000, v240
	v_lshlrev_b32_e32 v104, 16, v241
	v_and_b32_e32 v105, 0xffff0000, v241
	ds_read_b128 v[238:241], v246 offset:4272
	s_waitcnt lgkmcnt(3)
	v_lshlrev_b32_e32 v216, 16, v242
	v_and_b32_e32 v217, 0xffff0000, v242
	v_lshlrev_b32_e32 v242, 16, v243
	v_and_b32_e32 v243, 0xffff0000, v243
	v_pk_add_f32 v[106:107], v[98:99], v[216:217]
	v_pk_add_f32 v[108:109], v[100:101], v[242:243]
	v_lshlrev_b32_e32 v216, 16, v244
	v_and_b32_e32 v217, 0xffff0000, v244
	v_lshlrev_b32_e32 v244, 16, v245
	v_and_b32_e32 v245, 0xffff0000, v245
	v_pk_add_f32 v[218:219], v[102:103], v[216:217]
	v_pk_add_f32 v[220:221], v[104:105], v[244:245]
	ds_read_b128 v[242:245], v246 offset:4000
	s_waitcnt lgkmcnt(3)
	v_lshlrev_b32_e32 v216, 16, v248
	v_and_b32_e32 v217, 0xffff0000, v248
	v_lshlrev_b32_e32 v248, 16, v249
	v_and_b32_e32 v249, 0xffff0000, v249
	v_pk_add_f32 v[106:107], v[106:107], v[216:217]
	v_pk_add_f32 v[108:109], v[108:109], v[248:249]
	v_lshlrev_b32_e32 v216, 16, v250
	v_and_b32_e32 v217, 0xffff0000, v250
	v_lshlrev_b32_e32 v250, 16, v251
	v_and_b32_e32 v251, 0xffff0000, v251
	v_pk_add_f32 v[218:219], v[218:219], v[216:217]
	v_pk_add_f32 v[220:221], v[220:221], v[250:251]
	ds_read_b128 v[248:251], v246 offset:3728
	s_waitcnt lgkmcnt(3)
	v_lshlrev_b32_e32 v216, 16, v252
	v_and_b32_e32 v217, 0xffff0000, v252
	v_lshlrev_b32_e32 v252, 16, v253
	v_and_b32_e32 v253, 0xffff0000, v253
	v_pk_add_f32 v[106:107], v[106:107], v[216:217]
	v_pk_add_f32 v[108:109], v[108:109], v[252:253]
	v_lshlrev_b32_e32 v216, 16, v254
	v_and_b32_e32 v217, 0xffff0000, v254
	v_lshlrev_b32_e32 v254, 16, v255
	v_and_b32_e32 v255, 0xffff0000, v255
	v_pk_add_f32 v[218:219], v[218:219], v[216:217]
	v_pk_add_f32 v[220:221], v[220:221], v[254:255]
	ds_read_b128 v[252:255], v246 offset:3456
	v_pk_fma_f32 v[106:107], v[158:159], v[106:107], v[98:99] op_sel:[1,0,0] neg_lo:[0,0,1] neg_hi:[0,0,1]
	v_pk_fma_f32 v[108:109], v[158:159], v[108:109], v[100:101] op_sel:[1,0,0] neg_lo:[0,0,1] neg_hi:[0,0,1]
	v_pk_fma_f32 v[218:219], v[158:159], v[218:219], v[102:103] op_sel:[1,0,0] neg_lo:[0,0,1] neg_hi:[0,0,1]
	v_pk_fma_f32 v[220:221], v[158:159], v[220:221], v[104:105] op_sel:[1,0,0] neg_lo:[0,0,1] neg_hi:[0,0,1]
	v_cvt_pk_bf16_f32 v106, v106, v107
	v_cvt_pk_bf16_f32 v107, v108, v109
	v_cvt_pk_bf16_f32 v108, v218, v219
	v_cvt_pk_bf16_f32 v109, v220, v221
	s_and_saveexec_b64 s[28:29], s[6:7]
	s_cbranch_execz .Lpu2_5
	global_store_dwordx4 v[190:191], v[98:101], off offset:320
	global_store_dwordx4 v[190:191], v[102:105], off offset:336
.Lpu2_5:
	s_or_b64 exec, exec, s[28:29]
	s_waitcnt vmcnt(8)
	v_mfma_f32_32x32x16_bf16 v[2:17], v[106:109], v[222:225], v[2:17]
	v_mfma_f32_32x32x16_bf16 v[18:33], v[106:109], v[226:229], v[18:33]
	v_mfma_f32_32x32x16_bf16 v[34:49], v[106:109], v[230:233], v[34:49]
	v_mfma_f32_32x32x16_bf16 v[50:65], v[106:109], v[234:237], v[50:65]
	s_waitcnt lgkmcnt(3)
	v_lshlrev_b32_e32 v98, 16, v238
	v_and_b32_e32 v99, 0xffff0000, v238
	v_lshlrev_b32_e32 v100, 16, v239
	v_and_b32_e32 v101, 0xffff0000, v239
	v_lshlrev_b32_e32 v102, 16, v240
	v_and_b32_e32 v103, 0xffff0000, v240
	v_lshlrev_b32_e32 v104, 16, v241
	v_and_b32_e32 v105, 0xffff0000, v241
	ds_read_b128 v[238:241], v246 offset:4304
	s_waitcnt lgkmcnt(3)
	v_lshlrev_b32_e32 v216, 16, v242
	v_and_b32_e32 v217, 0xffff0000, v242
	v_lshlrev_b32_e32 v242, 16, v243
	v_and_b32_e32 v243, 0xffff0000, v243
	v_pk_add_f32 v[106:107], v[98:99], v[216:217]
	v_pk_add_f32 v[108:109], v[100:101], v[242:243]
	v_lshlrev_b32_e32 v216, 16, v244
	v_and_b32_e32 v217, 0xffff0000, v244
	v_lshlrev_b32_e32 v244, 16, v245
	v_and_b32_e32 v245, 0xffff0000, v245
	v_pk_add_f32 v[218:219], v[102:103], v[216:217]
	v_pk_add_f32 v[220:221], v[104:105], v[244:245]
	ds_read_b128 v[242:245], v246 offset:4032
	s_waitcnt lgkmcnt(3)
	v_lshlrev_b32_e32 v216, 16, v248
	v_and_b32_e32 v217, 0xffff0000, v248
	v_lshlrev_b32_e32 v248, 16, v249
	v_and_b32_e32 v249, 0xffff0000, v249
	v_pk_add_f32 v[106:107], v[106:107], v[216:217]
	v_pk_add_f32 v[108:109], v[108:109], v[248:249]
	v_lshlrev_b32_e32 v216, 16, v250
	v_and_b32_e32 v217, 0xffff0000, v250
	v_lshlrev_b32_e32 v250, 16, v251
	v_and_b32_e32 v251, 0xffff0000, v251
	v_pk_add_f32 v[218:219], v[218:219], v[216:217]
	v_pk_add_f32 v[220:221], v[220:221], v[250:251]
	ds_read_b128 v[248:251], v246 offset:3760
	s_waitcnt lgkmcnt(3)
	v_lshlrev_b32_e32 v216, 16, v252
	v_and_b32_e32 v217, 0xffff0000, v252
	v_lshlrev_b32_e32 v252, 16, v253
	v_and_b32_e32 v253, 0xffff0000, v253
	v_pk_add_f32 v[106:107], v[106:107], v[216:217]
	v_pk_add_f32 v[108:109], v[108:109], v[252:253]
	v_lshlrev_b32_e32 v216, 16, v254
	v_and_b32_e32 v217, 0xffff0000, v254
	v_lshlrev_b32_e32 v254, 16, v255
	v_and_b32_e32 v255, 0xffff0000, v255
	v_pk_add_f32 v[218:219], v[218:219], v[216:217]
	v_pk_add_f32 v[220:221], v[220:221], v[254:255]
	ds_read_b128 v[252:255], v246 offset:3488
	v_pk_fma_f32 v[106:107], v[158:159], v[106:107], v[98:99] op_sel:[1,0,0] neg_lo:[0,0,1] neg_hi:[0,0,1]
	v_pk_fma_f32 v[108:109], v[158:159], v[108:109], v[100:101] op_sel:[1,0,0] neg_lo:[0,0,1] neg_hi:[0,0,1]
	v_pk_fma_f32 v[218:219], v[158:159], v[218:219], v[102:103] op_sel:[1,0,0] neg_lo:[0,0,1] neg_hi:[0,0,1]
	v_pk_fma_f32 v[220:221], v[158:159], v[220:221], v[104:105] op_sel:[1,0,0] neg_lo:[0,0,1] neg_hi:[0,0,1]
	v_cvt_pk_bf16_f32 v106, v106, v107
	v_cvt_pk_bf16_f32 v107, v108, v109
	v_cvt_pk_bf16_f32 v108, v218, v219
	v_cvt_pk_bf16_f32 v109, v220, v221
	s_and_saveexec_b64 s[28:29], s[6:7]
	s_cbranch_execz .Lpu2_6
	global_store_dwordx4 v[190:191], v[98:101], off offset:384
	global_store_dwordx4 v[190:191], v[102:105], off offset:400
.Lpu2_6:
	s_or_b64 exec, exec, s[28:29]
	s_waitcnt vmcnt(4)
	v_mfma_f32_32x32x16_bf16 v[2:17], v[106:109], v[70:73], v[2:17]
	v_mfma_f32_32x32x16_bf16 v[18:33], v[106:109], v[74:77], v[18:33]
	v_mfma_f32_32x32x16_bf16 v[34:49], v[106:109], v[78:81], v[34:49]
	v_mfma_f32_32x32x16_bf16 v[50:65], v[106:109], v[66:69], v[50:65]
	s_waitcnt lgkmcnt(3)
	v_lshlrev_b32_e32 v98, 16, v238
	v_and_b32_e32 v99, 0xffff0000, v238
	v_lshlrev_b32_e32 v100, 16, v239
	v_and_b32_e32 v101, 0xffff0000, v239
	v_lshlrev_b32_e32 v102, 16, v240
	v_and_b32_e32 v103, 0xffff0000, v240
	v_lshlrev_b32_e32 v104, 16, v241
	v_and_b32_e32 v105, 0xffff0000, v241
	s_waitcnt lgkmcnt(2)
	v_lshlrev_b32_e32 v216, 16, v242
	v_and_b32_e32 v217, 0xffff0000, v242
	v_lshlrev_b32_e32 v242, 16, v243
	v_and_b32_e32 v243, 0xffff0000, v243
	v_pk_add_f32 v[106:107], v[98:99], v[216:217]
	v_pk_add_f32 v[108:109], v[100:101], v[242:243]
	v_lshlrev_b32_e32 v216, 16, v244
	v_and_b32_e32 v217, 0xffff0000, v244
	v_lshlrev_b32_e32 v244, 16, v245
	v_and_b32_e32 v245, 0xffff0000, v245
	v_pk_add_f32 v[218:219], v[102:103], v[216:217]
	v_pk_add_f32 v[220:221], v[104:105], v[244:245]
	s_waitcnt lgkmcnt(1)
	v_lshlrev_b32_e32 v216, 16, v248
	v_and_b32_e32 v217, 0xffff0000, v248
	v_lshlrev_b32_e32 v248, 16, v249
	v_and_b32_e32 v249, 0xffff0000, v249
	v_pk_add_f32 v[106:107], v[106:107], v[216:217]
	v_pk_add_f32 v[108:109], v[108:109], v[248:249]
	v_lshlrev_b32_e32 v216, 16, v250
	v_and_b32_e32 v217, 0xffff0000, v250
	v_lshlrev_b32_e32 v250, 16, v251
	v_and_b32_e32 v251, 0xffff0000, v251
	v_pk_add_f32 v[218:219], v[218:219], v[216:217]
	v_pk_add_f32 v[220:221], v[220:221], v[250:251]
	s_waitcnt lgkmcnt(0)
	v_lshlrev_b32_e32 v216, 16, v252
	v_and_b32_e32 v217, 0xffff0000, v252
	v_lshlrev_b32_e32 v252, 16, v253
	v_and_b32_e32 v253, 0xffff0000, v253
	v_pk_add_f32 v[106:107], v[106:107], v[216:217]
	v_pk_add_f32 v[108:109], v[108:109], v[252:253]
	v_lshlrev_b32_e32 v216, 16, v254
	v_and_b32_e32 v217, 0xffff0000, v254
	v_lshlrev_b32_e32 v254, 16, v255
	v_and_b32_e32 v255, 0xffff0000, v255
	v_pk_add_f32 v[218:219], v[218:219], v[216:217]
	v_pk_add_f32 v[220:221], v[220:221], v[254:255]
	v_pk_fma_f32 v[106:107], v[158:159], v[106:107], v[98:99] op_sel:[1,0,0] neg_lo:[0,0,1] neg_hi:[0,0,1]
	v_pk_fma_f32 v[108:109], v[158:159], v[108:109], v[100:101] op_sel:[1,0,0] neg_lo:[0,0,1] neg_hi:[0,0,1]
	v_pk_fma_f32 v[218:219], v[158:159], v[218:219], v[102:103] op_sel:[1,0,0] neg_lo:[0,0,1] neg_hi:[0,0,1]
	v_pk_fma_f32 v[220:221], v[158:159], v[220:221], v[104:105] op_sel:[1,0,0] neg_lo:[0,0,1] neg_hi:[0,0,1]
	v_cvt_pk_bf16_f32 v106, v106, v107
	v_cvt_pk_bf16_f32 v107, v108, v109
	v_cvt_pk_bf16_f32 v108, v218, v219
	v_cvt_pk_bf16_f32 v109, v220, v221
	s_and_saveexec_b64 s[28:29], s[6:7]
	s_cbranch_execz .Lpu2_7
	global_store_dwordx4 v[190:191], v[98:101], off offset:448
	global_store_dwordx4 v[190:191], v[102:105], off offset:464

.LBB0_403:
	s_or_b64 exec, exec, s[2:3]
	s_waitcnt lgkmcnt(0)
	global_load_dwordx4 v[82:85], v[110:111], off offset:512
	global_load_dwordx4 v[86:89], v[134:135], off offset:512
	global_load_dwordx4 v[90:93], v[136:137], off offset:512
	global_load_dwordx4 v[94:97], v[138:139], off offset:512
	global_load_dwordx4 v[222:225], v[110:111], off offset:1024
	global_load_dwordx4 v[226:229], v[134:135], off offset:1024
	global_load_dwordx4 v[230:233], v[136:137], off offset:1024
	global_load_dwordx4 v[234:237], v[138:139], off offset:1024
	v_lshl_add_u32 v246, v197, 1, v214
	ds_read_b128 v[238:241], v246 offset:4080
	ds_read_b128 v[242:245], v246 offset:3808
	ds_read_b128 v[248:251], v246 offset:4112
	ds_read_b128 v[252:255], v246 offset:3840
	s_ashr_i32 s2, s30, 6
	v_or_b32_e32 v2, s28, v1
	s_mul_i32 s2, s2, 15
	v_cmp_eq_u32_e32 vcc, 0, v2
	v_cmp_lt_u32_e64 s[6:7], s41, v2
	s_ashr_i32 s3, s2, 31
	v_add_u32_e32 v2, 0xfffff80f, v2
	v_mov_b32_e32 v3, v155
	v_lshl_add_u64 v[2:3], v[2:3], 0, s[2:3]
	v_lshlrev_b64 v[2:3], 11, v[2:3]
	v_lshl_add_u64 v[184:185], v[140:141], 0, v[2:3]
	v_mov_b64_e32 v[2:3], 0
	v_mov_b64_e32 v[4:5], 0
	v_mov_b64_e32 v[6:7], 0
	v_mov_b64_e32 v[8:9], 0
	v_mov_b64_e32 v[10:11], 0
	v_mov_b64_e32 v[12:13], 0
	v_mov_b64_e32 v[14:15], 0
	v_mov_b64_e32 v[16:17], 0
	v_mov_b64_e32 v[18:19], 0
	v_mov_b64_e32 v[20:21], 0
	v_mov_b64_e32 v[22:23], 0
	v_mov_b64_e32 v[24:25], 0
	v_mov_b64_e32 v[26:27], 0
	v_mov_b64_e32 v[28:29], 0
	v_mov_b64_e32 v[30:31], 0
	v_mov_b64_e32 v[32:33], 0
	v_mov_b64_e32 v[34:35], 0
	v_mov_b64_e32 v[36:37], 0
	v_mov_b64_e32 v[38:39], 0
	v_mov_b64_e32 v[40:41], 0
	v_mov_b64_e32 v[42:43], 0
	v_mov_b64_e32 v[44:45], 0
	v_mov_b64_e32 v[46:47], 0
	v_mov_b64_e32 v[48:49], 0
	v_mov_b64_e32 v[50:51], 0
	v_mov_b64_e32 v[52:53], 0
	v_mov_b64_e32 v[54:55], 0
	v_mov_b64_e32 v[56:57], 0
	v_mov_b64_e32 v[58:59], 0
	v_mov_b64_e32 v[60:61], 0
	v_mov_b64_e32 v[62:63], 0
	v_mov_b64_e32 v[64:65], 0
	s_mov_b32 s28, 0
	v_cndmask_b32_e64 v159, 0.5, 1.0, vcc
	s_mov_b64 s[2:3], 0
	s_waitcnt lgkmcnt(3)
	v_lshlrev_b32_e32 v98, 16, v238
	v_and_b32_e32 v99, 0xffff0000, v238
	v_lshlrev_b32_e32 v100, 16, v239
	v_and_b32_e32 v101, 0xffff0000, v239
	v_lshlrev_b32_e32 v102, 16, v240
	v_and_b32_e32 v103, 0xffff0000, v240
	v_lshlrev_b32_e32 v104, 16, v241
	v_and_b32_e32 v105, 0xffff0000, v241
	ds_read_b128 v[238:241], v246 offset:4144
	s_waitcnt lgkmcnt(3)
	v_lshlrev_b32_e32 v216, 16, v242
	v_and_b32_e32 v217, 0xffff0000, v242
	v_lshlrev_b32_e32 v242, 16, v243
	v_and_b32_e32 v243, 0xffff0000, v243
	v_pk_add_f32 v[106:107], v[98:99], v[216:217]
	v_pk_add_f32 v[108:109], v[100:101], v[242:243]
	v_lshlrev_b32_e32 v216, 16, v244
	v_and_b32_e32 v217, 0xffff0000, v244
	v_lshlrev_b32_e32 v244, 16, v245
	v_and_b32_e32 v245, 0xffff0000, v245
	v_pk_add_f32 v[218:219], v[102:103], v[216:217]
	v_pk_add_f32 v[220:221], v[104:105], v[244:245]
	ds_read_b128 v[242:245], v246 offset:3872
	v_pk_fma_f32 v[106:107], v[158:159], v[106:107], v[98:99] op_sel:[1,0,0] neg_lo:[0,0,1] neg_hi:[0,0,1]
	v_pk_fma_f32 v[108:109], v[158:159], v[108:109], v[100:101] op_sel:[1,0,0] neg_lo:[0,0,1] neg_hi:[0,0,1]
	v_pk_fma_f32 v[218:219], v[158:159], v[218:219], v[102:103] op_sel:[1,0,0] neg_lo:[0,0,1] neg_hi:[0,0,1]
	v_pk_fma_f32 v[220:221], v[158:159], v[220:221], v[104:105] op_sel:[1,0,0] neg_lo:[0,0,1] neg_hi:[0,0,1]
	v_cvt_pk_bf16_f32 v106, v106, v107
	v_cvt_pk_bf16_f32 v107, v108, v109
	v_cvt_pk_bf16_f32 v108, v218, v219
	v_cvt_pk_bf16_f32 v109, v220, v221
	s_and_saveexec_b64 s[10:11], s[6:7]
	s_cbranch_execz .Lpu3_0
	global_store_dwordx4 v[184:185], v[98:101], off offset:0
	global_store_dwordx4 v[184:185], v[102:105], off offset:16
.Lpu3_0:
	s_or_b64 exec, exec, s[10:11]
	s_waitcnt vmcnt(8)
	v_mfma_f32_32x32x16_bf16 v[2:17], v[106:109], v[70:73], v[2:17]
	v_mfma_f32_32x32x16_bf16 v[18:33], v[106:109], v[74:77], v[18:33]
	v_mfma_f32_32x32x16_bf16 v[34:49], v[106:109], v[78:81], v[34:49]
	v_mfma_f32_32x32x16_bf16 v[50:65], v[106:109], v[66:69], v[50:65]
	global_load_dwordx4 v[70:73], v[110:111], off offset:1536
	global_load_dwordx4 v[74:77], v[134:135], off offset:1536
	global_load_dwordx4 v[78:81], v[136:137], off offset:1536
	global_load_dwordx4 v[66:69], v[138:139], off offset:1536
	s_waitcnt lgkmcnt(3)
	v_lshlrev_b32_e32 v98, 16, v248
	v_and_b32_e32 v99, 0xffff0000, v248
	v_lshlrev_b32_e32 v100, 16, v249
	v_and_b32_e32 v101, 0xffff0000, v249
	v_lshlrev_b32_e32 v102, 16, v250
	v_and_b32_e32 v103, 0xffff0000, v250
	v_lshlrev_b32_e32 v104, 16, v251
	v_and_b32_e32 v105, 0xffff0000, v251
	ds_read_b128 v[248:251], v246 offset:4176
	s_waitcnt lgkmcnt(3)
	v_lshlrev_b32_e32 v216, 16, v252
	v_and_b32_e32 v217, 0xffff0000, v252
	v_lshlrev_b32_e32 v252, 16, v253
	v_and_b32_e32 v253, 0xffff0000, v253
	v_pk_add_f32 v[106:107], v[98:99], v[216:217]
	v_pk_add_f32 v[108:109], v[100:101], v[252:253]
	v_lshlrev_b32_e32 v216, 16, v254
	v_and_b32_e32 v217, 0xffff0000, v254
	v_lshlrev_b32_e32 v254, 16, v255
	v_and_b32_e32 v255, 0xffff0000, v255
	v_pk_add_f32 v[218:219], v[102:103], v[216:217]
	v_pk_add_f32 v[220:221], v[104:105], v[254:255]
	ds_read_b128 v[252:255], v246 offset:3904
	v_pk_fma_f32 v[106:107], v[158:159], v[106:107], v[98:99] op_sel:[1,0,0] neg_lo:[0,0,1] neg_hi:[0,0,1]
	v_pk_fma_f32 v[108:109], v[158:159], v[108:109], v[100:101] op_sel:[1,0,0] neg_lo:[0,0,1] neg_hi:[0,0,1]
	v_pk_fma_f32 v[218:219], v[158:159], v[218:219], v[102:103] op_sel:[1,0,0] neg_lo:[0,0,1] neg_hi:[0,0,1]
	v_pk_fma_f32 v[220:221], v[158:159], v[220:221], v[104:105] op_sel:[1,0,0] neg_lo:[0,0,1] neg_hi:[0,0,1]
	v_cvt_pk_bf16_f32 v106, v106, v107
	v_cvt_pk_bf16_f32 v107, v108, v109
	v_cvt_pk_bf16_f32 v108, v218, v219
	v_cvt_pk_bf16_f32 v109, v220, v221
	s_and_saveexec_b64 s[10:11], s[6:7]
	s_cbranch_execz .Lpu3_1
	global_store_dwordx4 v[184:185], v[98:101], off offset:64
	global_store_dwordx4 v[184:185], v[102:105], off offset:80
.Lpu3_1:
	s_or_b64 exec, exec, s[10:11]
	s_waitcnt vmcnt(8)
	v_mfma_f32_32x32x16_bf16 v[2:17], v[106:109], v[82:85], v[2:17]
	v_mfma_f32_32x32x16_bf16 v[18:33], v[106:109], v[86:89], v[18:33]
	v_mfma_f32_32x32x16_bf16 v[34:49], v[106:109], v[90:93], v[34:49]
	v_mfma_f32_32x32x16_bf16 v[50:65], v[106:109], v[94:97], v[50:65]
	global_load_dwordx4 v[82:85], v[110:111], off offset:2048
	global_load_dwordx4 v[86:89], v[134:135], off offset:2048
	global_load_dwordx4 v[90:93], v[136:137], off offset:2048
	global_load_dwordx4 v[94:97], v[138:139], off offset:2048
	s_waitcnt lgkmcnt(3)
	v_lshlrev_b32_e32 v98, 16, v238
	v_and_b32_e32 v99, 0xffff0000, v238
	v_lshlrev_b32_e32 v100, 16, v239
	v_and_b32_e32 v101, 0xffff0000, v239
	v_lshlrev_b32_e32 v102, 16, v240
	v_and_b32_e32 v103, 0xffff0000, v240
	v_lshlrev_b32_e32 v104, 16, v241
	v_and_b32_e32 v105, 0xffff0000, v241
	ds_read_b128 v[238:241], v246 offset:4208
	s_waitcnt lgkmcnt(3)
	v_lshlrev_b32_e32 v216, 16, v242
	v_and_b32_e32 v217, 0xffff0000, v242
	v_lshlrev_b32_e32 v242, 16, v243
	v_and_b32_e32 v243, 0xffff0000, v243
	v_pk_add_f32 v[106:107], v[98:99], v[216:217]
	v_pk_add_f32 v[108:109], v[100:101], v[242:243]
	v_lshlrev_b32_e32 v216, 16, v244
	v_and_b32_e32 v217, 0xffff0000, v244
	v_lshlrev_b32_e32 v244, 16, v245
	v_and_b32_e32 v245, 0xffff0000, v245
	v_pk_add_f32 v[218:219], v[102:103], v[216:217]
	v_pk_add_f32 v[220:221], v[104:105], v[244:245]
	ds_read_b128 v[242:245], v246 offset:3936
	v_pk_fma_f32 v[106:107], v[158:159], v[106:107], v[98:99] op_sel:[1,0,0] neg_lo:[0,0,1] neg_hi:[0,0,1]
	v_pk_fma_f32 v[108:109], v[158:159], v[108:109], v[100:101] op_sel:[1,0,0] neg_lo:[0,0,1] neg_hi:[0,0,1]
	v_pk_fma_f32 v[218:219], v[158:159], v[218:219], v[102:103] op_sel:[1,0,0] neg_lo:[0,0,1] neg_hi:[0,0,1]
	v_pk_fma_f32 v[220:221], v[158:159], v[220:221], v[104:105] op_sel:[1,0,0] neg_lo:[0,0,1] neg_hi:[0,0,1]
	v_cvt_pk_bf16_f32 v106, v106, v107
	v_cvt_pk_bf16_f32 v107, v108, v109
	v_cvt_pk_bf16_f32 v108, v218, v219
	v_cvt_pk_bf16_f32 v109, v220, v221
	s_and_saveexec_b64 s[10:11], s[6:7]
	s_cbranch_execz .Lpu3_2
	global_store_dwordx4 v[184:185], v[98:101], off offset:128
	global_store_dwordx4 v[184:185], v[102:105], off offset:144
.Lpu3_2:
	s_or_b64 exec, exec, s[10:11]
	s_waitcnt vmcnt(8)
	v_mfma_f32_32x32x16_bf16 v[2:17], v[106:109], v[222:225], v[2:17]
	v_mfma_f32_32x32x16_bf16 v[18:33], v[106:109], v[226:229], v[18:33]
	v_mfma_f32_32x32x16_bf16 v[34:49], v[106:109], v[230:233], v[34:49]
	v_mfma_f32_32x32x16_bf16 v[50:65], v[106:109], v[234:237], v[50:65]
	global_load_dwordx4 v[222:225], v[110:111], off offset:2560
	global_load_dwordx4 v[226:229], v[134:135], off offset:2560
	global_load_dwordx4 v[230:233], v[136:137], off offset:2560
	global_load_dwordx4 v[234:237], v[138:139], off offset:2560
	s_waitcnt lgkmcnt(3)
	v_lshlrev_b32_e32 v98, 16, v248
	v_and_b32_e32 v99, 0xffff0000, v248
	v_lshlrev_b32_e32 v100, 16, v249
	v_and_b32_e32 v101, 0xffff0000, v249
	v_lshlrev_b32_e32 v102, 16, v250
	v_and_b32_e32 v103, 0xffff0000, v250
	v_lshlrev_b32_e32 v104, 16, v251
	v_and_b32_e32 v105, 0xffff0000, v251
	ds_read_b128 v[248:251], v246 offset:4240
	s_waitcnt lgkmcnt(3)
	v_lshlrev_b32_e32 v216, 16, v252
	v_and_b32_e32 v217, 0xffff0000, v252
	v_lshlrev_b32_e32 v252, 16, v253
	v_and_b32_e32 v253, 0xffff0000, v253
	v_pk_add_f32 v[106:107], v[98:99], v[216:217]
	v_pk_add_f32 v[108:109], v[100:101], v[252:253]
	v_lshlrev_b32_e32 v216, 16, v254
	v_and_b32_e32 v217, 0xffff0000, v254
	v_lshlrev_b32_e32 v254, 16, v255
	v_and_b32_e32 v255, 0xffff0000, v255
	v_pk_add_f32 v[218:219], v[102:103], v[216:217]
	v_pk_add_f32 v[220:221], v[104:105], v[254:255]
	ds_read_b128 v[252:255], v246 offset:3968
	v_pk_fma_f32 v[106:107], v[158:159], v[106:107], v[98:99] op_sel:[1,0,0] neg_lo:[0,0,1] neg_hi:[0,0,1]
	v_pk_fma_f32 v[108:109], v[158:159], v[108:109], v[100:101] op_sel:[1,0,0] neg_lo:[0,0,1] neg_hi:[0,0,1]
	v_pk_fma_f32 v[218:219], v[158:159], v[218:219], v[102:103] op_sel:[1,0,0] neg_lo:[0,0,1] neg_hi:[0,0,1]
	v_pk_fma_f32 v[220:221], v[158:159], v[220:221], v[104:105] op_sel:[1,0,0] neg_lo:[0,0,1] neg_hi:[0,0,1]
	v_cvt_pk_bf16_f32 v106, v106, v107
	v_cvt_pk_bf16_f32 v107, v108, v109
	v_cvt_pk_bf16_f32 v108, v218, v219
	v_cvt_pk_bf16_f32 v109, v220, v221
	s_and_saveexec_b64 s[10:11], s[6:7]
	s_cbranch_execz .Lpu3_3
	global_store_dwordx4 v[184:185], v[98:101], off offset:192
	global_store_dwordx4 v[184:185], v[102:105], off offset:208
.Lpu3_3:
	s_or_b64 exec, exec, s[10:11]
	s_waitcnt vmcnt(8)
	v_mfma_f32_32x32x16_bf16 v[2:17], v[106:109], v[70:73], v[2:17]
	v_mfma_f32_32x32x16_bf16 v[18:33], v[106:109], v[74:77], v[18:33]
	v_mfma_f32_32x32x16_bf16 v[34:49], v[106:109], v[78:81], v[34:49]
	v_mfma_f32_32x32x16_bf16 v[50:65], v[106:109], v[66:69], v[50:65]
	global_load_dwordx4 v[70:73], v[110:111], off offset:3072
	global_load_dwordx4 v[74:77], v[134:135], off offset:3072
	global_load_dwordx4 v[78:81], v[136:137], off offset:3072
	global_load_dwordx4 v[66:69], v[138:139], off offset:3072
	s_waitcnt lgkmcnt(3)
	v_lshlrev_b32_e32 v98, 16, v238
	v_and_b32_e32 v99, 0xffff0000, v238
	v_lshlrev_b32_e32 v100, 16, v239
	v_and_b32_e32 v101, 0xffff0000, v239
	v_lshlrev_b32_e32 v102, 16, v240
	v_and_b32_e32 v103, 0xffff0000, v240
	v_lshlrev_b32_e32 v104, 16, v241
	v_and_b32_e32 v105, 0xffff0000, v241
	ds_read_b128 v[238:241], v246 offset:4272
	s_waitcnt lgkmcnt(3)
	v_lshlrev_b32_e32 v216, 16, v242
	v_and_b32_e32 v217, 0xffff0000, v242
	v_lshlrev_b32_e32 v242, 16, v243
	v_and_b32_e32 v243, 0xffff0000, v243
	v_pk_add_f32 v[106:107], v[98:99], v[216:217]
	v_pk_add_f32 v[108:109], v[100:101], v[242:243]
	v_lshlrev_b32_e32 v216, 16, v244
	v_and_b32_e32 v217, 0xffff0000, v244
	v_lshlrev_b32_e32 v244, 16, v245
	v_and_b32_e32 v245, 0xffff0000, v245
	v_pk_add_f32 v[218:219], v[102:103], v[216:217]
	v_pk_add_f32 v[220:221], v[104:105], v[244:245]
	ds_read_b128 v[242:245], v246 offset:4000
	v_pk_fma_f32 v[106:107], v[158:159], v[106:107], v[98:99] op_sel:[1,0,0] neg_lo:[0,0,1] neg_hi:[0,0,1]
	v_pk_fma_f32 v[108:109], v[158:159], v[108:109], v[100:101] op_sel:[1,0,0] neg_lo:[0,0,1] neg_hi:[0,0,1]
	v_pk_fma_f32 v[218:219], v[158:159], v[218:219], v[102:103] op_sel:[1,0,0] neg_lo:[0,0,1] neg_hi:[0,0,1]
	v_pk_fma_f32 v[220:221], v[158:159], v[220:221], v[104:105] op_sel:[1,0,0] neg_lo:[0,0,1] neg_hi:[0,0,1]
	v_cvt_pk_bf16_f32 v106, v106, v107
	v_cvt_pk_bf16_f32 v107, v108, v109
	v_cvt_pk_bf16_f32 v108, v218, v219
	v_cvt_pk_bf16_f32 v109, v220, v221
	s_and_saveexec_b64 s[10:11], s[6:7]
	s_cbranch_execz .Lpu3_4
	global_store_dwordx4 v[184:185], v[98:101], off offset:256
	global_store_dwordx4 v[184:185], v[102:105], off offset:272
.Lpu3_4:
	s_or_b64 exec, exec, s[10:11]
	s_waitcnt vmcnt(8)
	v_mfma_f32_32x32x16_bf16 v[2:17], v[106:109], v[82:85], v[2:17]
	v_mfma_f32_32x32x16_bf16 v[18:33], v[106:109], v[86:89], v[18:33]
	v_mfma_f32_32x32x16_bf16 v[34:49], v[106:109], v[90:93], v[34:49]
	v_mfma_f32_32x32x16_bf16 v[50:65], v[106:109], v[94:97], v[50:65]
	global_load_dwordx4 v[82:85], v[110:111], off offset:3584
	global_load_dwordx4 v[86:89], v[134:135], off offset:3584
	global_load_dwordx4 v[90:93], v[136:137], off offset:3584
	global_load_dwordx4 v[94:97], v[138:139], off offset:3584
	s_waitcnt lgkmcnt(3)
	v_lshlrev_b32_e32 v98, 16, v248
	v_and_b32_e32 v99, 0xffff0000, v248
	v_lshlrev_b32_e32 v100, 16, v249
	v_and_b32_e32 v101, 0xffff0000, v249
	v_lshlrev_b32_e32 v102, 16, v250
	v_and_b32_e32 v103, 0xffff0000, v250
	v_lshlrev_b32_e32 v104, 16, v251
	v_and_b32_e32 v105, 0xffff0000, v251
	ds_read_b128 v[248:251], v246 offset:4304
	s_waitcnt lgkmcnt(3)
	v_lshlrev_b32_e32 v216, 16, v252
	v_and_b32_e32 v217, 0xffff0000, v252
	v_lshlrev_b32_e32 v252, 16, v253
	v_and_b32_e32 v253, 0xffff0000, v253
	v_pk_add_f32 v[106:107], v[98:99], v[216:217]
	v_pk_add_f32 v[108:109], v[100:101], v[252:253]
	v_lshlrev_b32_e32 v216, 16, v254
	v_and_b32_e32 v217, 0xffff0000, v254
	v_lshlrev_b32_e32 v254, 16, v255
	v_and_b32_e32 v255, 0xffff0000, v255
	v_pk_add_f32 v[218:219], v[102:103], v[216:217]
	v_pk_add_f32 v[220:221], v[104:105], v[254:255]
	ds_read_b128 v[252:255], v246 offset:4032
	v_pk_fma_f32 v[106:107], v[158:159], v[106:107], v[98:99] op_sel:[1,0,0] neg_lo:[0,0,1] neg_hi:[0,0,1]
	v_pk_fma_f32 v[108:109], v[158:159], v[108:109], v[100:101] op_sel:[1,0,0] neg_lo:[0,0,1] neg_hi:[0,0,1]
	v_pk_fma_f32 v[218:219], v[158:159], v[218:219], v[102:103] op_sel:[1,0,0] neg_lo:[0,0,1] neg_hi:[0,0,1]
	v_pk_fma_f32 v[220:221], v[158:159], v[220:221], v[104:105] op_sel:[1,0,0] neg_lo:[0,0,1] neg_hi:[0,0,1]
	v_cvt_pk_bf16_f32 v106, v106, v107
	v_cvt_pk_bf16_f32 v107, v108, v109
	v_cvt_pk_bf16_f32 v108, v218, v219
	v_cvt_pk_bf16_f32 v109, v220, v221
	s_and_saveexec_b64 s[10:11], s[6:7]
	s_cbranch_execz .Lpu3_5
	global_store_dwordx4 v[184:185], v[98:101], off offset:320
	global_store_dwordx4 v[184:185], v[102:105], off offset:336
.Lpu3_5:
	s_or_b64 exec, exec, s[10:11]
	s_waitcnt vmcnt(8)
	v_mfma_f32_32x32x16_bf16 v[2:17], v[106:109], v[222:225], v[2:17]
	v_mfma_f32_32x32x16_bf16 v[18:33], v[106:109], v[226:229], v[18:33]
	v_mfma_f32_32x32x16_bf16 v[34:49], v[106:109], v[230:233], v[34:49]
	v_mfma_f32_32x32x16_bf16 v[50:65], v[106:109], v[234:237], v[50:65]
	s_waitcnt lgkmcnt(3)
	v_lshlrev_b32_e32 v98, 16, v238
	v_and_b32_e32 v99, 0xffff0000, v238
	v_lshlrev_b32_e32 v100, 16, v239
	v_and_b32_e32 v101, 0xffff0000, v239
	v_lshlrev_b32_e32 v102, 16, v240
	v_and_b32_e32 v103, 0xffff0000, v240
	v_lshlrev_b32_e32 v104, 16, v241
	v_and_b32_e32 v105, 0xffff0000, v241
	s_waitcnt lgkmcnt(2)
	v_lshlrev_b32_e32 v216, 16, v242
	v_and_b32_e32 v217, 0xffff0000, v242
	v_lshlrev_b32_e32 v242, 16, v243
	v_and_b32_e32 v243, 0xffff0000, v243
	v_pk_add_f32 v[106:107], v[98:99], v[216:217]
	v_pk_add_f32 v[108:109], v[100:101], v[242:243]
	v_lshlrev_b32_e32 v216, 16, v244
	v_and_b32_e32 v217, 0xffff0000, v244
	v_lshlrev_b32_e32 v244, 16, v245
	v_and_b32_e32 v245, 0xffff0000, v245
	v_pk_add_f32 v[218:219], v[102:103], v[216:217]
	v_pk_add_f32 v[220:221], v[104:105], v[244:245]
	v_pk_fma_f32 v[106:107], v[158:159], v[106:107], v[98:99] op_sel:[1,0,0] neg_lo:[0,0,1] neg_hi:[0,0,1]
	v_pk_fma_f32 v[108:109], v[158:159], v[108:109], v[100:101] op_sel:[1,0,0] neg_lo:[0,0,1] neg_hi:[0,0,1]
	v_pk_fma_f32 v[218:219], v[158:159], v[218:219], v[102:103] op_sel:[1,0,0] neg_lo:[0,0,1] neg_hi:[0,0,1]
	v_pk_fma_f32 v[220:221], v[158:159], v[220:221], v[104:105] op_sel:[1,0,0] neg_lo:[0,0,1] neg_hi:[0,0,1]
	v_cvt_pk_bf16_f32 v106, v106, v107
	v_cvt_pk_bf16_f32 v107, v108, v109
	v_cvt_pk_bf16_f32 v108, v218, v219
	v_cvt_pk_bf16_f32 v109, v220, v221
	s_and_saveexec_b64 s[10:11], s[6:7]
	s_cbranch_execz .Lpu3_6
	global_store_dwordx4 v[184:185], v[98:101], off offset:384
	global_store_dwordx4 v[184:185], v[102:105], off offset:400
.Lpu3_6:
	s_or_b64 exec, exec, s[10:11]
	s_waitcnt vmcnt(4)
	v_mfma_f32_32x32x16_bf16 v[2:17], v[106:109], v[70:73], v[2:17]
	v_mfma_f32_32x32x16_bf16 v[18:33], v[106:109], v[74:77], v[18:33]
	v_mfma_f32_32x32x16_bf16 v[34:49], v[106:109], v[78:81], v[34:49]
	v_mfma_f32_32x32x16_bf16 v[50:65], v[106:109], v[66:69], v[50:65]
	s_waitcnt lgkmcnt(1)
	v_lshlrev_b32_e32 v98, 16, v248
	v_and_b32_e32 v99, 0xffff0000, v248
	v_lshlrev_b32_e32 v100, 16, v249
	v_and_b32_e32 v101, 0xffff0000, v249
	v_lshlrev_b32_e32 v102, 16, v250
	v_and_b32_e32 v103, 0xffff0000, v250
	v_lshlrev_b32_e32 v104, 16, v251
	v_and_b32_e32 v105, 0xffff0000, v251
	s_waitcnt lgkmcnt(0)
	v_lshlrev_b32_e32 v216, 16, v252
	v_and_b32_e32 v217, 0xffff0000, v252
	v_lshlrev_b32_e32 v252, 16, v253
	v_and_b32_e32 v253, 0xffff0000, v253
	v_pk_add_f32 v[106:107], v[98:99], v[216:217]
	v_pk_add_f32 v[108:109], v[100:101], v[252:253]
	v_lshlrev_b32_e32 v216, 16, v254
	v_and_b32_e32 v217, 0xffff0000, v254
	v_lshlrev_b32_e32 v254, 16, v255
	v_and_b32_e32 v255, 0xffff0000, v255
	v_pk_add_f32 v[218:219], v[102:103], v[216:217]
	v_pk_add_f32 v[220:221], v[104:105], v[254:255]
	v_pk_fma_f32 v[106:107], v[158:159], v[106:107], v[98:99] op_sel:[1,0,0] neg_lo:[0,0,1] neg_hi:[0,0,1]
	v_pk_fma_f32 v[108:109], v[158:159], v[108:109], v[100:101] op_sel:[1,0,0] neg_lo:[0,0,1] neg_hi:[0,0,1]
	v_pk_fma_f32 v[218:219], v[158:159], v[218:219], v[102:103] op_sel:[1,0,0] neg_lo:[0,0,1] neg_hi:[0,0,1]
	v_pk_fma_f32 v[220:221], v[158:159], v[220:221], v[104:105] op_sel:[1,0,0] neg_lo:[0,0,1] neg_hi:[0,0,1]
	v_cvt_pk_bf16_f32 v106, v106, v107
	v_cvt_pk_bf16_f32 v107, v108, v109
	v_cvt_pk_bf16_f32 v108, v218, v219
	v_cvt_pk_bf16_f32 v109, v220, v221
	s_and_saveexec_b64 s[10:11], s[6:7]
	s_cbranch_execz .Lpu3_7
	global_store_dwordx4 v[184:185], v[98:101], off offset:448
	global_store_dwordx4 v[184:185], v[102:105], off offset:464
